# all GEMM K-loops: LDS-DMA issues moved ahead of the ds_reads in every load segment, lgkmcnt wait before the counted vmcnt wait
# speedup vs baseline: 1.0048x; 1.0048x over previous
.Lzgo_1:
	s_add_u32 s22, s22, 0x80
	s_addc_u32 s23, s23, 0
	s_add_u32 vcc_lo, s66, 0x100
	s_addc_u32 vcc_hi, s67, 0
	s_mov_b32 s66, 0
	s_add_i32 s88, s66, 2
	s_add_u32 s62, s22, 0x80
	s_addc_u32 s63, s23, 0
	s_add_i32 s89, 0, 0x10000
	s_cmp_eq_u32 s93, s66
	s_cselect_b32 s67, s3, s63
	s_cselect_b32 s66, s2, s62
	s_cselect_b32 s63, s21, vcc_hi
	s_cselect_b32 s62, s20, vcc_lo
	s_add_i32 s31, 0, 0x14000
	v_lshl_add_u64 v[218:219], s[22:23], 0, v[138:139]
	s_add_i32 m0, s77, 0xc000
	s_nop 0
	global_load_lds_dwordx4 v[218:219], off
	v_lshl_add_u64 v[218:219], s[22:23], 0, v[140:141]
	s_add_i32 m0, s77, 0xe000
	s_nop 0
	global_load_lds_dwordx4 v[218:219], off
	v_add_u32_e32 v149, s89, v146
	ds_read_b128 v[142:145], v149
	ds_read_b128 v[150:153], v149 offset:1024
	ds_read_b128 v[154:157], v149 offset:2048
	ds_read_b128 v[158:161], v149 offset:3072
	v_add_u32_e32 v149, s31, v146
	ds_read_b128 v[162:165], v149
	ds_read_b128 v[166:169], v149 offset:1024
	ds_read_b128 v[170:173], v149 offset:2048
	ds_read_b128 v[174:177], v149 offset:3072
	ds_read_b128 v[178:181], v148
	ds_read_b128 v[182:185], v148 offset:1024
	ds_read_b128 v[186:189], v148 offset:2048
	ds_read_b128 v[190:193], v148 offset:3072
	ds_read_b128 v[194:197], v148 offset:4096
	ds_read_b128 v[198:201], v148 offset:5120
	ds_read_b128 v[202:205], v148 offset:6144
	ds_read_b128 v[214:217], v148 offset:7168
	s_waitcnt lgkmcnt(0)
	s_waitcnt vmcnt(8)
	s_barrier
	s_setprio 1
	s_waitcnt lgkmcnt(0)
	v_mfma_f32_16x16x32_bf16 v[122:125], v[142:145], v[178:181], 0
	v_mfma_f32_16x16x32_bf16 v[118:121], v[154:157], v[178:181], 0
	v_mfma_f32_16x16x32_bf16 v[110:113], v[142:145], v[186:189], 0
	v_mfma_f32_16x16x32_bf16 v[102:105], v[154:157], v[186:189], 0
	v_mfma_f32_16x16x32_bf16 v[94:97], v[142:145], v[194:197], 0
	v_mfma_f32_16x16x32_bf16 v[86:89], v[154:157], v[194:197], 0
	v_mfma_f32_16x16x32_bf16 v[78:81], v[142:145], v[202:205], 0
	v_mfma_f32_16x16x32_bf16 v[70:73], v[154:157], v[202:205], 0
	v_mfma_f32_16x16x32_bf16 v[122:125], v[150:153], v[182:185], v[122:125]
	v_mfma_f32_16x16x32_bf16 v[118:121], v[158:161], v[182:185], v[118:121]
	v_mfma_f32_16x16x32_bf16 v[110:113], v[150:153], v[190:193], v[110:113]
	v_mfma_f32_16x16x32_bf16 v[102:105], v[158:161], v[190:193], v[102:105]
	v_mfma_f32_16x16x32_bf16 v[94:97], v[150:153], v[198:201], v[94:97]
	v_mfma_f32_16x16x32_bf16 v[86:89], v[158:161], v[198:201], v[86:89]
	v_mfma_f32_16x16x32_bf16 v[78:81], v[150:153], v[214:217], v[78:81]
	v_mfma_f32_16x16x32_bf16 v[70:73], v[158:161], v[214:217], v[70:73]
	s_setprio 0
	s_setprio 1
	v_mfma_f32_16x16x32_bf16 v[126:129], v[162:165], v[178:181], 0
	v_mfma_f32_16x16x32_bf16 v[114:117], v[170:173], v[178:181], 0
	v_mfma_f32_16x16x32_bf16 v[106:109], v[162:165], v[186:189], 0
	v_mfma_f32_16x16x32_bf16 v[98:101], v[170:173], v[186:189], 0
	v_mfma_f32_16x16x32_bf16 v[90:93], v[162:165], v[194:197], 0
	v_mfma_f32_16x16x32_bf16 v[82:85], v[170:173], v[194:197], 0
	v_mfma_f32_16x16x32_bf16 v[74:77], v[162:165], v[202:205], 0
	v_mfma_f32_16x16x32_bf16 v[66:69], v[170:173], v[202:205], 0
	v_mfma_f32_16x16x32_bf16 v[126:129], v[166:169], v[182:185], v[126:129]
	v_mfma_f32_16x16x32_bf16 v[114:117], v[174:177], v[182:185], v[114:117]
	v_mfma_f32_16x16x32_bf16 v[106:109], v[166:169], v[190:193], v[106:109]
	v_mfma_f32_16x16x32_bf16 v[98:101], v[174:177], v[190:193], v[98:101]
	v_mfma_f32_16x16x32_bf16 v[90:93], v[166:169], v[198:201], v[90:93]
	v_mfma_f32_16x16x32_bf16 v[82:85], v[174:177], v[198:201], v[82:85]
	v_mfma_f32_16x16x32_bf16 v[74:77], v[166:169], v[214:217], v[74:77]
	v_mfma_f32_16x16x32_bf16 v[66:69], v[174:177], v[214:217], v[66:69]
	s_setprio 0
	s_barrier
	s_add_i32 s89, s89, s74
	v_lshl_add_u64 v[218:219], s[62:63], 0, v[134:135]
	s_mov_b32 m0, s89
	s_nop 0
	global_load_lds_dwordx4 v[218:219], off
	s_add_i32 m0, s89, 0x2000
	v_lshl_add_u64 v[220:221], s[62:63], 0, v[130:131]
	s_add_u32 s62, s62, s8
	s_addc_u32 s63, s63, s9
	s_add_i32 s31, s31, s74
	global_load_lds_dwordx4 v[220:221], off
	v_lshl_add_u64 v[222:223], s[62:63], 0, v[134:135]
	s_mov_b32 m0, s31
	v_lshl_add_u64 v[224:225], s[62:63], 0, v[130:131]
	global_load_lds_dwordx4 v[222:223], off
	s_add_i32 m0, s31, 0x2000
	v_lshl_add_u64 v[226:227], s[66:67], 0, v[136:137]
	global_load_lds_dwordx4 v[224:225], off
	s_mov_b32 m0, s77
	v_lshl_add_u64 v[236:237], s[66:67], 0, v[132:133]
	global_load_lds_dwordx4 v[226:227], off
	s_mov_b32 m0, s78
	s_nop 0
	global_load_lds_dwordx4 v[236:237], off
	ds_read_b128 v[178:181], v148 offset:16384
	ds_read_b128 v[182:185], v148 offset:17408
	ds_read_b128 v[186:189], v148 offset:18432
	ds_read_b128 v[190:193], v148 offset:19456
	ds_read_b128 v[194:197], v148 offset:20480
	ds_read_b128 v[198:201], v148 offset:21504
	ds_read_b128 v[202:205], v148 offset:22528
	ds_read_b128 v[214:217], v148 offset:23552
	s_waitcnt lgkmcnt(0)
	s_waitcnt vmcnt(8)
	s_barrier
	s_setprio 1
	s_waitcnt lgkmcnt(0)
	v_mfma_f32_16x16x32_bf16 v[62:65], v[142:145], v[178:181], 0
	v_mfma_f32_16x16x32_bf16 v[54:57], v[154:157], v[178:181], 0
	v_mfma_f32_16x16x32_bf16 v[46:49], v[142:145], v[186:189], 0
	v_mfma_f32_16x16x32_bf16 v[38:41], v[154:157], v[186:189], 0
	v_mfma_f32_16x16x32_bf16 v[30:33], v[142:145], v[194:197], 0
	v_mfma_f32_16x16x32_bf16 v[22:25], v[154:157], v[194:197], 0
	v_mfma_f32_16x16x32_bf16 v[14:17], v[142:145], v[202:205], 0
	v_mfma_f32_16x16x32_bf16 v[6:9], v[154:157], v[202:205], 0
	v_mfma_f32_16x16x32_bf16 v[62:65], v[150:153], v[182:185], v[62:65]
	v_mfma_f32_16x16x32_bf16 v[54:57], v[158:161], v[182:185], v[54:57]
	v_mfma_f32_16x16x32_bf16 v[46:49], v[150:153], v[190:193], v[46:49]
	v_mfma_f32_16x16x32_bf16 v[38:41], v[158:161], v[190:193], v[38:41]
	v_mfma_f32_16x16x32_bf16 v[30:33], v[150:153], v[198:201], v[30:33]
	v_mfma_f32_16x16x32_bf16 v[22:25], v[158:161], v[198:201], v[22:25]
	v_mfma_f32_16x16x32_bf16 v[14:17], v[150:153], v[214:217], v[14:17]
	v_mfma_f32_16x16x32_bf16 v[6:9], v[158:161], v[214:217], v[6:9]
	s_setprio 0
	s_setprio 1
	v_mfma_f32_16x16x32_bf16 v[58:61], v[162:165], v[178:181], 0
	v_mfma_f32_16x16x32_bf16 v[50:53], v[170:173], v[178:181], 0
	v_mfma_f32_16x16x32_bf16 v[42:45], v[162:165], v[186:189], 0
	v_mfma_f32_16x16x32_bf16 v[34:37], v[170:173], v[186:189], 0
	v_mfma_f32_16x16x32_bf16 v[26:29], v[162:165], v[194:197], 0
	v_mfma_f32_16x16x32_bf16 v[18:21], v[170:173], v[194:197], 0
	v_mfma_f32_16x16x32_bf16 v[10:13], v[162:165], v[202:205], 0
	v_mfma_f32_16x16x32_bf16 v[2:5], v[170:173], v[202:205], 0
	v_mfma_f32_16x16x32_bf16 v[58:61], v[166:169], v[182:185], v[58:61]
	v_mfma_f32_16x16x32_bf16 v[50:53], v[174:177], v[182:185], v[50:53]
	v_mfma_f32_16x16x32_bf16 v[42:45], v[166:169], v[190:193], v[42:45]
	v_mfma_f32_16x16x32_bf16 v[34:37], v[174:177], v[190:193], v[34:37]
	v_mfma_f32_16x16x32_bf16 v[26:29], v[166:169], v[198:201], v[26:29]
	v_mfma_f32_16x16x32_bf16 v[18:21], v[174:177], v[198:201], v[18:21]
	v_mfma_f32_16x16x32_bf16 v[10:13], v[166:169], v[214:217], v[10:13]
	v_mfma_f32_16x16x32_bf16 v[2:5], v[174:177], v[214:217], v[2:5]
	s_setprio 0
	s_barrier
	s_add_i32 s31, 0, 0x18000
	s_add_i32 s89, 0, 0x1c000
	s_add_u32 s62, s66, s8
	s_addc_u32 s63, s67, s9
	s_mov_b32 m0, s79
	v_lshl_add_u64 v[238:239], s[62:63], 0, v[136:137]
	global_load_lds_dwordx4 v[238:239], off
	v_lshl_add_u64 v[238:239], s[62:63], 0, v[132:133]
	s_mov_b32 m0, s90
	s_nop 0
	global_load_lds_dwordx4 v[238:239], off
	v_add_u32_e32 v149, s31, v146
	ds_read_b128 v[142:145], v149
	ds_read_b128 v[150:153], v149 offset:1024
	ds_read_b128 v[154:157], v149 offset:2048
	ds_read_b128 v[158:161], v149 offset:3072
	v_add_u32_e32 v149, s89, v146
	ds_read_b128 v[162:165], v149
	ds_read_b128 v[166:169], v149 offset:1024
	ds_read_b128 v[170:173], v149 offset:2048
	ds_read_b128 v[174:177], v149 offset:3072
	ds_read_b128 v[178:181], v148 offset:32768
	ds_read_b128 v[182:185], v148 offset:33792
	ds_read_b128 v[186:189], v148 offset:34816
	ds_read_b128 v[190:193], v148 offset:35840
	ds_read_b128 v[194:197], v148 offset:36864
	ds_read_b128 v[198:201], v148 offset:37888
	ds_read_b128 v[202:205], v148 offset:38912
	ds_read_b128 v[214:217], v148 offset:39936
	s_waitcnt lgkmcnt(0)
	s_waitcnt vmcnt(8)
	s_barrier
	s_setprio 1
	s_waitcnt lgkmcnt(0)
	v_mfma_f32_16x16x32_bf16 v[122:125], v[142:145], v[178:181], v[122:125]
	v_mfma_f32_16x16x32_bf16 v[118:121], v[154:157], v[178:181], v[118:121]
	v_mfma_f32_16x16x32_bf16 v[110:113], v[142:145], v[186:189], v[110:113]
	v_mfma_f32_16x16x32_bf16 v[102:105], v[154:157], v[186:189], v[102:105]
	v_mfma_f32_16x16x32_bf16 v[94:97], v[142:145], v[194:197], v[94:97]
	v_mfma_f32_16x16x32_bf16 v[86:89], v[154:157], v[194:197], v[86:89]
	v_mfma_f32_16x16x32_bf16 v[78:81], v[142:145], v[202:205], v[78:81]
	v_mfma_f32_16x16x32_bf16 v[70:73], v[154:157], v[202:205], v[70:73]
	v_mfma_f32_16x16x32_bf16 v[122:125], v[150:153], v[182:185], v[122:125]
	v_mfma_f32_16x16x32_bf16 v[118:121], v[158:161], v[182:185], v[118:121]
	v_mfma_f32_16x16x32_bf16 v[110:113], v[150:153], v[190:193], v[110:113]
	v_mfma_f32_16x16x32_bf16 v[102:105], v[158:161], v[190:193], v[102:105]
	v_mfma_f32_16x16x32_bf16 v[94:97], v[150:153], v[198:201], v[94:97]
	v_mfma_f32_16x16x32_bf16 v[86:89], v[158:161], v[198:201], v[86:89]
	v_mfma_f32_16x16x32_bf16 v[78:81], v[150:153], v[214:217], v[78:81]
	v_mfma_f32_16x16x32_bf16 v[70:73], v[158:161], v[214:217], v[70:73]
	s_setprio 0
	s_setprio 1
	v_mfma_f32_16x16x32_bf16 v[126:129], v[162:165], v[178:181], v[126:129]
	v_mfma_f32_16x16x32_bf16 v[114:117], v[170:173], v[178:181], v[114:117]
	v_mfma_f32_16x16x32_bf16 v[106:109], v[162:165], v[186:189], v[106:109]
	v_mfma_f32_16x16x32_bf16 v[98:101], v[170:173], v[186:189], v[98:101]
	v_mfma_f32_16x16x32_bf16 v[90:93], v[162:165], v[194:197], v[90:93]
	v_mfma_f32_16x16x32_bf16 v[82:85], v[170:173], v[194:197], v[82:85]
	v_mfma_f32_16x16x32_bf16 v[74:77], v[162:165], v[202:205], v[74:77]
	v_mfma_f32_16x16x32_bf16 v[66:69], v[170:173], v[202:205], v[66:69]
	v_mfma_f32_16x16x32_bf16 v[126:129], v[166:169], v[182:185], v[126:129]
	v_mfma_f32_16x16x32_bf16 v[114:117], v[174:177], v[182:185], v[114:117]
	v_mfma_f32_16x16x32_bf16 v[106:109], v[166:169], v[190:193], v[106:109]
	v_mfma_f32_16x16x32_bf16 v[98:101], v[174:177], v[190:193], v[98:101]
	v_mfma_f32_16x16x32_bf16 v[90:93], v[166:169], v[198:201], v[90:93]
	v_mfma_f32_16x16x32_bf16 v[82:85], v[174:177], v[198:201], v[82:85]
	v_mfma_f32_16x16x32_bf16 v[74:77], v[166:169], v[214:217], v[74:77]
	v_mfma_f32_16x16x32_bf16 v[66:69], v[174:177], v[214:217], v[66:69]
	s_setprio 0
	s_barrier
	s_add_i32 s31, s31, s74
	v_lshl_add_u64 v[218:219], v[218:219], 0, s[60:61]
	s_mov_b32 m0, s31
	s_nop 0
	global_load_lds_dwordx4 v[218:219], off
	v_lshl_add_u64 v[218:219], v[220:221], 0, s[60:61]
	s_add_i32 m0, s31, 0x2000
	s_add_i32 s31, s89, s74
	global_load_lds_dwordx4 v[218:219], off
	v_lshl_add_u64 v[218:219], v[222:223], 0, s[60:61]
	s_mov_b32 m0, s31
	s_nop 0
	global_load_lds_dwordx4 v[218:219], off
	v_lshl_add_u64 v[218:219], v[224:225], 0, s[60:61]
	s_add_i32 m0, s31, 0x2000
	s_nop 0
	global_load_lds_dwordx4 v[218:219], off
	v_lshl_add_u64 v[218:219], v[226:227], 0, s[60:61]
	s_mov_b32 m0, s91
	s_nop 0
	global_load_lds_dwordx4 v[218:219], off
	v_lshl_add_u64 v[218:219], v[236:237], 0, s[60:61]
	s_mov_b32 m0, s92
	s_nop 0
	global_load_lds_dwordx4 v[218:219], off
	ds_read_b128 v[178:181], v148 offset:49152
	ds_read_b128 v[182:185], v148 offset:50176
	ds_read_b128 v[186:189], v148 offset:51200
	ds_read_b128 v[190:193], v148 offset:52224
	ds_read_b128 v[194:197], v148 offset:53248
	ds_read_b128 v[198:201], v148 offset:54272
	ds_read_b128 v[202:205], v148 offset:55296
	ds_read_b128 v[214:217], v148 offset:56320
	s_waitcnt lgkmcnt(0)
	s_waitcnt vmcnt(8)
	s_barrier
	s_setprio 1
	s_waitcnt lgkmcnt(0)
	v_mfma_f32_16x16x32_bf16 v[62:65], v[142:145], v[178:181], v[62:65]
	v_mfma_f32_16x16x32_bf16 v[54:57], v[154:157], v[178:181], v[54:57]
	v_mfma_f32_16x16x32_bf16 v[46:49], v[142:145], v[186:189], v[46:49]
	v_mfma_f32_16x16x32_bf16 v[38:41], v[154:157], v[186:189], v[38:41]
	v_mfma_f32_16x16x32_bf16 v[30:33], v[142:145], v[194:197], v[30:33]
	v_mfma_f32_16x16x32_bf16 v[22:25], v[154:157], v[194:197], v[22:25]
	v_mfma_f32_16x16x32_bf16 v[14:17], v[142:145], v[202:205], v[14:17]
	v_mfma_f32_16x16x32_bf16 v[6:9], v[154:157], v[202:205], v[6:9]
	v_mfma_f32_16x16x32_bf16 v[62:65], v[150:153], v[182:185], v[62:65]
	v_mfma_f32_16x16x32_bf16 v[54:57], v[158:161], v[182:185], v[54:57]
	v_mfma_f32_16x16x32_bf16 v[46:49], v[150:153], v[190:193], v[46:49]
	v_mfma_f32_16x16x32_bf16 v[38:41], v[158:161], v[190:193], v[38:41]
	v_mfma_f32_16x16x32_bf16 v[30:33], v[150:153], v[198:201], v[30:33]
	v_mfma_f32_16x16x32_bf16 v[22:25], v[158:161], v[198:201], v[22:25]
	v_mfma_f32_16x16x32_bf16 v[14:17], v[150:153], v[214:217], v[14:17]
	v_mfma_f32_16x16x32_bf16 v[6:9], v[158:161], v[214:217], v[6:9]
	s_setprio 0
	s_setprio 1
	v_mfma_f32_16x16x32_bf16 v[58:61], v[162:165], v[178:181], v[58:61]
	v_mfma_f32_16x16x32_bf16 v[50:53], v[170:173], v[178:181], v[50:53]
	v_mfma_f32_16x16x32_bf16 v[42:45], v[162:165], v[186:189], v[42:45]
	v_mfma_f32_16x16x32_bf16 v[34:37], v[170:173], v[186:189], v[34:37]
	v_mfma_f32_16x16x32_bf16 v[26:29], v[162:165], v[194:197], v[26:29]
	v_mfma_f32_16x16x32_bf16 v[18:21], v[170:173], v[194:197], v[18:21]
	v_mfma_f32_16x16x32_bf16 v[10:13], v[162:165], v[202:205], v[10:13]
	v_mfma_f32_16x16x32_bf16 v[2:5], v[170:173], v[202:205], v[2:5]
	v_mfma_f32_16x16x32_bf16 v[58:61], v[166:169], v[182:185], v[58:61]
	v_mfma_f32_16x16x32_bf16 v[50:53], v[174:177], v[182:185], v[50:53]
	v_mfma_f32_16x16x32_bf16 v[42:45], v[166:169], v[190:193], v[42:45]
	v_mfma_f32_16x16x32_bf16 v[34:37], v[174:177], v[190:193], v[34:37]
	v_mfma_f32_16x16x32_bf16 v[26:29], v[166:169], v[198:201], v[26:29]
	v_mfma_f32_16x16x32_bf16 v[18:21], v[174:177], v[198:201], v[18:21]
	v_mfma_f32_16x16x32_bf16 v[10:13], v[166:169], v[214:217], v[10:13]
	v_mfma_f32_16x16x32_bf16 v[2:5], v[174:177], v[214:217], v[2:5]
	s_setprio 0
	s_barrier
	s_add_u32 s22, s22, 0x100
	s_addc_u32 s23, s23, 0
	s_add_u32 vcc_lo, vcc_lo, 0x100
	s_addc_u32 vcc_hi, vcc_hi, 0
	s_cmp_ge_i32 s88, s52
	s_mov_b32 s66, s88
	s_cbranch_scc1 .LBB0_288
.LBB0_287:
	s_add_i32 s88, s66, 2
	s_add_u32 s62, s22, 0x80
	s_addc_u32 s63, s23, 0
	s_add_i32 s89, 0, 0x10000
	s_cmp_eq_u32 s93, s66
	s_cselect_b32 s67, s3, s63
	s_cselect_b32 s66, s2, s62
	s_cselect_b32 s63, s21, vcc_hi
	s_cselect_b32 s62, s20, vcc_lo
	s_add_i32 s31, 0, 0x14000
	v_lshl_add_u64 v[218:219], s[22:23], 0, v[138:139]
	s_add_i32 m0, s77, 0xc000
	s_nop 0
	global_load_lds_dwordx4 v[218:219], off
	v_lshl_add_u64 v[218:219], s[22:23], 0, v[140:141]
	s_add_i32 m0, s77, 0xe000
	s_nop 0
	global_load_lds_dwordx4 v[218:219], off
	v_add_u32_e32 v149, s89, v146
	ds_read_b128 v[142:145], v149
	ds_read_b128 v[150:153], v149 offset:1024
	ds_read_b128 v[154:157], v149 offset:2048
	ds_read_b128 v[158:161], v149 offset:3072
	v_add_u32_e32 v149, s31, v146
	ds_read_b128 v[162:165], v149
	ds_read_b128 v[166:169], v149 offset:1024
	ds_read_b128 v[170:173], v149 offset:2048
	ds_read_b128 v[174:177], v149 offset:3072
	ds_read_b128 v[178:181], v148
	ds_read_b128 v[182:185], v148 offset:1024
	ds_read_b128 v[186:189], v148 offset:2048
	ds_read_b128 v[190:193], v148 offset:3072
	ds_read_b128 v[194:197], v148 offset:4096
	ds_read_b128 v[198:201], v148 offset:5120
	ds_read_b128 v[202:205], v148 offset:6144
	ds_read_b128 v[214:217], v148 offset:7168
	s_waitcnt lgkmcnt(0)
	s_waitcnt vmcnt(8)
	s_barrier
	s_setprio 1
	s_waitcnt lgkmcnt(0)
	v_mfma_f32_16x16x32_bf16 v[122:125], v[142:145], v[178:181], v[122:125]
	v_mfma_f32_16x16x32_bf16 v[118:121], v[154:157], v[178:181], v[118:121]
	v_mfma_f32_16x16x32_bf16 v[110:113], v[142:145], v[186:189], v[110:113]
	v_mfma_f32_16x16x32_bf16 v[102:105], v[154:157], v[186:189], v[102:105]
	v_mfma_f32_16x16x32_bf16 v[94:97], v[142:145], v[194:197], v[94:97]
	v_mfma_f32_16x16x32_bf16 v[86:89], v[154:157], v[194:197], v[86:89]
	v_mfma_f32_16x16x32_bf16 v[78:81], v[142:145], v[202:205], v[78:81]
	v_mfma_f32_16x16x32_bf16 v[70:73], v[154:157], v[202:205], v[70:73]
	v_mfma_f32_16x16x32_bf16 v[122:125], v[150:153], v[182:185], v[122:125]
	v_mfma_f32_16x16x32_bf16 v[118:121], v[158:161], v[182:185], v[118:121]
	v_mfma_f32_16x16x32_bf16 v[110:113], v[150:153], v[190:193], v[110:113]
	v_mfma_f32_16x16x32_bf16 v[102:105], v[158:161], v[190:193], v[102:105]
	v_mfma_f32_16x16x32_bf16 v[94:97], v[150:153], v[198:201], v[94:97]
	v_mfma_f32_16x16x32_bf16 v[86:89], v[158:161], v[198:201], v[86:89]
	v_mfma_f32_16x16x32_bf16 v[78:81], v[150:153], v[214:217], v[78:81]
	v_mfma_f32_16x16x32_bf16 v[70:73], v[158:161], v[214:217], v[70:73]
	s_setprio 0
	s_setprio 1
	v_mfma_f32_16x16x32_bf16 v[126:129], v[162:165], v[178:181], v[126:129]
	v_mfma_f32_16x16x32_bf16 v[114:117], v[170:173], v[178:181], v[114:117]
	v_mfma_f32_16x16x32_bf16 v[106:109], v[162:165], v[186:189], v[106:109]
	v_mfma_f32_16x16x32_bf16 v[98:101], v[170:173], v[186:189], v[98:101]
	v_mfma_f32_16x16x32_bf16 v[90:93], v[162:165], v[194:197], v[90:93]
	v_mfma_f32_16x16x32_bf16 v[82:85], v[170:173], v[194:197], v[82:85]
	v_mfma_f32_16x16x32_bf16 v[74:77], v[162:165], v[202:205], v[74:77]
	v_mfma_f32_16x16x32_bf16 v[66:69], v[170:173], v[202:205], v[66:69]
	v_mfma_f32_16x16x32_bf16 v[126:129], v[166:169], v[182:185], v[126:129]
	v_mfma_f32_16x16x32_bf16 v[114:117], v[174:177], v[182:185], v[114:117]
	v_mfma_f32_16x16x32_bf16 v[106:109], v[166:169], v[190:193], v[106:109]
	v_mfma_f32_16x16x32_bf16 v[98:101], v[174:177], v[190:193], v[98:101]
	v_mfma_f32_16x16x32_bf16 v[90:93], v[166:169], v[198:201], v[90:93]
	v_mfma_f32_16x16x32_bf16 v[82:85], v[174:177], v[198:201], v[82:85]
	v_mfma_f32_16x16x32_bf16 v[74:77], v[166:169], v[214:217], v[74:77]
	v_mfma_f32_16x16x32_bf16 v[66:69], v[174:177], v[214:217], v[66:69]
	s_setprio 0
	s_barrier
	s_add_i32 s89, s89, s74
	v_lshl_add_u64 v[218:219], s[62:63], 0, v[134:135]
	s_mov_b32 m0, s89
	s_nop 0
	global_load_lds_dwordx4 v[218:219], off
	s_add_i32 m0, s89, 0x2000
	v_lshl_add_u64 v[220:221], s[62:63], 0, v[130:131]
	s_add_u32 s62, s62, s8
	s_addc_u32 s63, s63, s9
	s_add_i32 s31, s31, s74
	global_load_lds_dwordx4 v[220:221], off
	v_lshl_add_u64 v[222:223], s[62:63], 0, v[134:135]
	s_mov_b32 m0, s31
	v_lshl_add_u64 v[224:225], s[62:63], 0, v[130:131]
	global_load_lds_dwordx4 v[222:223], off
	s_add_i32 m0, s31, 0x2000
	v_lshl_add_u64 v[226:227], s[66:67], 0, v[136:137]
	global_load_lds_dwordx4 v[224:225], off
	s_mov_b32 m0, s77
	v_lshl_add_u64 v[236:237], s[66:67], 0, v[132:133]
	global_load_lds_dwordx4 v[226:227], off
	s_mov_b32 m0, s78
	s_nop 0
	global_load_lds_dwordx4 v[236:237], off
	ds_read_b128 v[178:181], v148 offset:16384
	ds_read_b128 v[182:185], v148 offset:17408
	ds_read_b128 v[186:189], v148 offset:18432
	ds_read_b128 v[190:193], v148 offset:19456
	ds_read_b128 v[194:197], v148 offset:20480
	ds_read_b128 v[198:201], v148 offset:21504
	ds_read_b128 v[202:205], v148 offset:22528
	ds_read_b128 v[214:217], v148 offset:23552
	s_waitcnt lgkmcnt(0)
	s_waitcnt vmcnt(8)
	s_barrier
	s_setprio 1
	s_waitcnt lgkmcnt(0)
	v_mfma_f32_16x16x32_bf16 v[62:65], v[142:145], v[178:181], v[62:65]
	v_mfma_f32_16x16x32_bf16 v[54:57], v[154:157], v[178:181], v[54:57]
	v_mfma_f32_16x16x32_bf16 v[46:49], v[142:145], v[186:189], v[46:49]
	v_mfma_f32_16x16x32_bf16 v[38:41], v[154:157], v[186:189], v[38:41]
	v_mfma_f32_16x16x32_bf16 v[30:33], v[142:145], v[194:197], v[30:33]
	v_mfma_f32_16x16x32_bf16 v[22:25], v[154:157], v[194:197], v[22:25]
	v_mfma_f32_16x16x32_bf16 v[14:17], v[142:145], v[202:205], v[14:17]
	v_mfma_f32_16x16x32_bf16 v[6:9], v[154:157], v[202:205], v[6:9]
	v_mfma_f32_16x16x32_bf16 v[62:65], v[150:153], v[182:185], v[62:65]
	v_mfma_f32_16x16x32_bf16 v[54:57], v[158:161], v[182:185], v[54:57]
	v_mfma_f32_16x16x32_bf16 v[46:49], v[150:153], v[190:193], v[46:49]
	v_mfma_f32_16x16x32_bf16 v[38:41], v[158:161], v[190:193], v[38:41]
	v_mfma_f32_16x16x32_bf16 v[30:33], v[150:153], v[198:201], v[30:33]
	v_mfma_f32_16x16x32_bf16 v[22:25], v[158:161], v[198:201], v[22:25]
	v_mfma_f32_16x16x32_bf16 v[14:17], v[150:153], v[214:217], v[14:17]
	v_mfma_f32_16x16x32_bf16 v[6:9], v[158:161], v[214:217], v[6:9]
	s_setprio 0
	s_setprio 1
	v_mfma_f32_16x16x32_bf16 v[58:61], v[162:165], v[178:181], v[58:61]
	v_mfma_f32_16x16x32_bf16 v[50:53], v[170:173], v[178:181], v[50:53]
	v_mfma_f32_16x16x32_bf16 v[42:45], v[162:165], v[186:189], v[42:45]
	v_mfma_f32_16x16x32_bf16 v[34:37], v[170:173], v[186:189], v[34:37]
	v_mfma_f32_16x16x32_bf16 v[26:29], v[162:165], v[194:197], v[26:29]
	v_mfma_f32_16x16x32_bf16 v[18:21], v[170:173], v[194:197], v[18:21]
	v_mfma_f32_16x16x32_bf16 v[10:13], v[162:165], v[202:205], v[10:13]
	v_mfma_f32_16x16x32_bf16 v[2:5], v[170:173], v[202:205], v[2:5]
	v_mfma_f32_16x16x32_bf16 v[58:61], v[166:169], v[182:185], v[58:61]
	v_mfma_f32_16x16x32_bf16 v[50:53], v[174:177], v[182:185], v[50:53]
	v_mfma_f32_16x16x32_bf16 v[42:45], v[166:169], v[190:193], v[42:45]
	v_mfma_f32_16x16x32_bf16 v[34:37], v[174:177], v[190:193], v[34:37]
	v_mfma_f32_16x16x32_bf16 v[26:29], v[166:169], v[198:201], v[26:29]
	v_mfma_f32_16x16x32_bf16 v[18:21], v[174:177], v[198:201], v[18:21]
	v_mfma_f32_16x16x32_bf16 v[10:13], v[166:169], v[214:217], v[10:13]
	v_mfma_f32_16x16x32_bf16 v[2:5], v[174:177], v[214:217], v[2:5]
	s_setprio 0
	s_barrier
	s_add_i32 s31, 0, 0x18000
	s_add_i32 s89, 0, 0x1c000
	s_add_u32 s62, s66, s8
	s_addc_u32 s63, s67, s9
	s_mov_b32 m0, s79
	v_lshl_add_u64 v[238:239], s[62:63], 0, v[136:137]
	global_load_lds_dwordx4 v[238:239], off
	v_lshl_add_u64 v[238:239], s[62:63], 0, v[132:133]
	s_mov_b32 m0, s90
	s_nop 0
	global_load_lds_dwordx4 v[238:239], off
	v_add_u32_e32 v149, s31, v146
	ds_read_b128 v[142:145], v149
	ds_read_b128 v[150:153], v149 offset:1024
	ds_read_b128 v[154:157], v149 offset:2048
	ds_read_b128 v[158:161], v149 offset:3072
	v_add_u32_e32 v149, s89, v146
	ds_read_b128 v[162:165], v149
	ds_read_b128 v[166:169], v149 offset:1024
	ds_read_b128 v[170:173], v149 offset:2048
	ds_read_b128 v[174:177], v149 offset:3072
	ds_read_b128 v[178:181], v148 offset:32768
	ds_read_b128 v[182:185], v148 offset:33792
	ds_read_b128 v[186:189], v148 offset:34816
	ds_read_b128 v[190:193], v148 offset:35840
	ds_read_b128 v[194:197], v148 offset:36864
	ds_read_b128 v[198:201], v148 offset:37888
	ds_read_b128 v[202:205], v148 offset:38912
	ds_read_b128 v[214:217], v148 offset:39936
	s_waitcnt lgkmcnt(0)
	s_waitcnt vmcnt(8)
	s_barrier
	s_setprio 1
	s_waitcnt lgkmcnt(0)
	v_mfma_f32_16x16x32_bf16 v[122:125], v[142:145], v[178:181], v[122:125]
	v_mfma_f32_16x16x32_bf16 v[118:121], v[154:157], v[178:181], v[118:121]
	v_mfma_f32_16x16x32_bf16 v[110:113], v[142:145], v[186:189], v[110:113]
	v_mfma_f32_16x16x32_bf16 v[102:105], v[154:157], v[186:189], v[102:105]
	v_mfma_f32_16x16x32_bf16 v[94:97], v[142:145], v[194:197], v[94:97]
	v_mfma_f32_16x16x32_bf16 v[86:89], v[154:157], v[194:197], v[86:89]
	v_mfma_f32_16x16x32_bf16 v[78:81], v[142:145], v[202:205], v[78:81]
	v_mfma_f32_16x16x32_bf16 v[70:73], v[154:157], v[202:205], v[70:73]
	v_mfma_f32_16x16x32_bf16 v[122:125], v[150:153], v[182:185], v[122:125]
	v_mfma_f32_16x16x32_bf16 v[118:121], v[158:161], v[182:185], v[118:121]
	v_mfma_f32_16x16x32_bf16 v[110:113], v[150:153], v[190:193], v[110:113]
	v_mfma_f32_16x16x32_bf16 v[102:105], v[158:161], v[190:193], v[102:105]
	v_mfma_f32_16x16x32_bf16 v[94:97], v[150:153], v[198:201], v[94:97]
	v_mfma_f32_16x16x32_bf16 v[86:89], v[158:161], v[198:201], v[86:89]
	v_mfma_f32_16x16x32_bf16 v[78:81], v[150:153], v[214:217], v[78:81]
	v_mfma_f32_16x16x32_bf16 v[70:73], v[158:161], v[214:217], v[70:73]
	s_setprio 0
	s_setprio 1
	v_mfma_f32_16x16x32_bf16 v[126:129], v[162:165], v[178:181], v[126:129]
	v_mfma_f32_16x16x32_bf16 v[114:117], v[170:173], v[178:181], v[114:117]
	v_mfma_f32_16x16x32_bf16 v[106:109], v[162:165], v[186:189], v[106:109]
	v_mfma_f32_16x16x32_bf16 v[98:101], v[170:173], v[186:189], v[98:101]
	v_mfma_f32_16x16x32_bf16 v[90:93], v[162:165], v[194:197], v[90:93]
	v_mfma_f32_16x16x32_bf16 v[82:85], v[170:173], v[194:197], v[82:85]
	v_mfma_f32_16x16x32_bf16 v[74:77], v[162:165], v[202:205], v[74:77]
	v_mfma_f32_16x16x32_bf16 v[66:69], v[170:173], v[202:205], v[66:69]
	v_mfma_f32_16x16x32_bf16 v[126:129], v[166:169], v[182:185], v[126:129]
	v_mfma_f32_16x16x32_bf16 v[114:117], v[174:177], v[182:185], v[114:117]
	v_mfma_f32_16x16x32_bf16 v[106:109], v[166:169], v[190:193], v[106:109]
	v_mfma_f32_16x16x32_bf16 v[98:101], v[174:177], v[190:193], v[98:101]
	v_mfma_f32_16x16x32_bf16 v[90:93], v[166:169], v[198:201], v[90:93]
	v_mfma_f32_16x16x32_bf16 v[82:85], v[174:177], v[198:201], v[82:85]
	v_mfma_f32_16x16x32_bf16 v[74:77], v[166:169], v[214:217], v[74:77]
	v_mfma_f32_16x16x32_bf16 v[66:69], v[174:177], v[214:217], v[66:69]
	s_setprio 0
	s_barrier
	s_add_i32 s31, s31, s74
	v_lshl_add_u64 v[218:219], v[218:219], 0, s[60:61]
	s_mov_b32 m0, s31
	s_nop 0
	global_load_lds_dwordx4 v[218:219], off
	v_lshl_add_u64 v[218:219], v[220:221], 0, s[60:61]
	s_add_i32 m0, s31, 0x2000
	s_add_i32 s31, s89, s74
	global_load_lds_dwordx4 v[218:219], off
	v_lshl_add_u64 v[218:219], v[222:223], 0, s[60:61]
	s_mov_b32 m0, s31
	s_nop 0
	global_load_lds_dwordx4 v[218:219], off
	v_lshl_add_u64 v[218:219], v[224:225], 0, s[60:61]
	s_add_i32 m0, s31, 0x2000
	s_nop 0
	global_load_lds_dwordx4 v[218:219], off
	v_lshl_add_u64 v[218:219], v[226:227], 0, s[60:61]
	s_mov_b32 m0, s91
	s_nop 0
	global_load_lds_dwordx4 v[218:219], off
	v_lshl_add_u64 v[218:219], v[236:237], 0, s[60:61]
	s_mov_b32 m0, s92
	s_nop 0
	global_load_lds_dwordx4 v[218:219], off
	ds_read_b128 v[178:181], v148 offset:49152
	ds_read_b128 v[182:185], v148 offset:50176
	ds_read_b128 v[186:189], v148 offset:51200
	ds_read_b128 v[190:193], v148 offset:52224
	ds_read_b128 v[194:197], v148 offset:53248
	ds_read_b128 v[198:201], v148 offset:54272
	ds_read_b128 v[202:205], v148 offset:55296
	ds_read_b128 v[214:217], v148 offset:56320
	s_waitcnt lgkmcnt(0)
	s_waitcnt vmcnt(8)
	s_barrier
	s_setprio 1
	s_waitcnt lgkmcnt(0)
	v_mfma_f32_16x16x32_bf16 v[62:65], v[142:145], v[178:181], v[62:65]
	v_mfma_f32_16x16x32_bf16 v[54:57], v[154:157], v[178:181], v[54:57]
	v_mfma_f32_16x16x32_bf16 v[46:49], v[142:145], v[186:189], v[46:49]
	v_mfma_f32_16x16x32_bf16 v[38:41], v[154:157], v[186:189], v[38:41]
	v_mfma_f32_16x16x32_bf16 v[30:33], v[142:145], v[194:197], v[30:33]
	v_mfma_f32_16x16x32_bf16 v[22:25], v[154:157], v[194:197], v[22:25]
	v_mfma_f32_16x16x32_bf16 v[14:17], v[142:145], v[202:205], v[14:17]
	v_mfma_f32_16x16x32_bf16 v[6:9], v[154:157], v[202:205], v[6:9]
	v_mfma_f32_16x16x32_bf16 v[62:65], v[150:153], v[182:185], v[62:65]
	v_mfma_f32_16x16x32_bf16 v[54:57], v[158:161], v[182:185], v[54:57]
	v_mfma_f32_16x16x32_bf16 v[46:49], v[150:153], v[190:193], v[46:49]
	v_mfma_f32_16x16x32_bf16 v[38:41], v[158:161], v[190:193], v[38:41]
	v_mfma_f32_16x16x32_bf16 v[30:33], v[150:153], v[198:201], v[30:33]
	v_mfma_f32_16x16x32_bf16 v[22:25], v[158:161], v[198:201], v[22:25]
	v_mfma_f32_16x16x32_bf16 v[14:17], v[150:153], v[214:217], v[14:17]
	v_mfma_f32_16x16x32_bf16 v[6:9], v[158:161], v[214:217], v[6:9]
	s_setprio 0
	s_setprio 1
	v_mfma_f32_16x16x32_bf16 v[58:61], v[162:165], v[178:181], v[58:61]
	v_mfma_f32_16x16x32_bf16 v[50:53], v[170:173], v[178:181], v[50:53]
	v_mfma_f32_16x16x32_bf16 v[42:45], v[162:165], v[186:189], v[42:45]
	v_mfma_f32_16x16x32_bf16 v[34:37], v[170:173], v[186:189], v[34:37]
	v_mfma_f32_16x16x32_bf16 v[26:29], v[162:165], v[194:197], v[26:29]
	v_mfma_f32_16x16x32_bf16 v[18:21], v[170:173], v[194:197], v[18:21]
	v_mfma_f32_16x16x32_bf16 v[10:13], v[162:165], v[202:205], v[10:13]
	v_mfma_f32_16x16x32_bf16 v[2:5], v[170:173], v[202:205], v[2:5]
	v_mfma_f32_16x16x32_bf16 v[58:61], v[166:169], v[182:185], v[58:61]
	v_mfma_f32_16x16x32_bf16 v[50:53], v[174:177], v[182:185], v[50:53]
	v_mfma_f32_16x16x32_bf16 v[42:45], v[166:169], v[190:193], v[42:45]
	v_mfma_f32_16x16x32_bf16 v[34:37], v[174:177], v[190:193], v[34:37]
	v_mfma_f32_16x16x32_bf16 v[26:29], v[166:169], v[198:201], v[26:29]
	v_mfma_f32_16x16x32_bf16 v[18:21], v[174:177], v[198:201], v[18:21]
	v_mfma_f32_16x16x32_bf16 v[10:13], v[166:169], v[214:217], v[10:13]
	v_mfma_f32_16x16x32_bf16 v[2:5], v[174:177], v[214:217], v[2:5]
	s_setprio 0
	s_barrier
	s_add_u32 s22, s22, 0x100
	s_addc_u32 s23, s23, 0
	s_add_u32 vcc_lo, vcc_lo, 0x100
	s_addc_u32 vcc_hi, vcc_hi, 0
	s_cmp_ge_i32 s88, s52
	s_mov_b32 s66, s88
	s_cbranch_scc0 .LBB0_287

.Lzgo_2:
	s_add_u32 s20, s20, 0x80
	s_addc_u32 s21, s21, 0
	s_add_u32 vcc_lo, s22, 0x100
	s_addc_u32 vcc_hi, s23, 0
	s_mov_b32 s22, 0
	s_add_i32 s88, s22, 2
	s_add_u32 s31, s20, 0x80
	s_addc_u32 s23, s21, 0
	s_add_i32 s89, 0, 0x10000
	s_cmp_eq_u32 s90, s22
	s_cselect_b32 s23, s3, s23
	s_cselect_b32 s22, s2, s31
	s_cselect_b32 s63, s19, vcc_hi
	s_cselect_b32 s62, s18, vcc_lo
	s_add_i32 s31, 0, 0x14000
	v_lshl_add_u64 v[146:147], s[20:21], 0, v[134:135]
	s_add_i32 m0, s67, 0xc000
	s_nop 0
	global_load_lds_dwordx4 v[146:147], off
	v_lshl_add_u64 v[146:147], s[20:21], 0, v[136:137]
	s_add_i32 m0, s67, 0xe000
	s_nop 0
	global_load_lds_dwordx4 v[146:147], off
	v_add_u32_e32 v146, s89, v148
	ds_read_b128 v[138:141], v146
	ds_read_b128 v[142:145], v146 offset:1024
	ds_read_b128 v[152:155], v146 offset:2048
	ds_read_b128 v[156:159], v146 offset:3072
	v_add_u32_e32 v146, s31, v148
	ds_read_b128 v[160:163], v146
	ds_read_b128 v[164:167], v146 offset:1024
	ds_read_b128 v[168:171], v146 offset:2048
	ds_read_b128 v[172:175], v146 offset:3072
	ds_read_b128 v[176:179], v150
	ds_read_b128 v[180:183], v150 offset:1024
	ds_read_b128 v[184:187], v150 offset:2048
	ds_read_b128 v[188:191], v150 offset:3072
	ds_read_b128 v[192:195], v150 offset:4096
	ds_read_b128 v[196:199], v150 offset:5120
	ds_read_b128 v[200:203], v150 offset:6144
	ds_read_b128 v[214:217], v150 offset:7168
	s_waitcnt lgkmcnt(0)
	s_waitcnt vmcnt(8)
	s_barrier
	s_setprio 1
	s_waitcnt lgkmcnt(0)
	v_mfma_f32_16x16x32_bf16 v[126:129], v[138:141], v[176:179], 0
	v_mfma_f32_16x16x32_bf16 v[94:97], v[152:155], v[176:179], 0
	v_mfma_f32_16x16x32_bf16 v[122:125], v[138:141], v[184:187], 0
	v_mfma_f32_16x16x32_bf16 v[90:93], v[152:155], v[184:187], 0
	v_mfma_f32_16x16x32_bf16 v[118:121], v[138:141], v[192:195], 0
	v_mfma_f32_16x16x32_bf16 v[86:89], v[152:155], v[192:195], 0
	v_mfma_f32_16x16x32_bf16 v[114:117], v[138:141], v[200:203], 0
	v_mfma_f32_16x16x32_bf16 v[82:85], v[152:155], v[200:203], 0
	v_mfma_f32_16x16x32_bf16 v[126:129], v[142:145], v[180:183], v[126:129]
	v_mfma_f32_16x16x32_bf16 v[94:97], v[156:159], v[180:183], v[94:97]
	v_mfma_f32_16x16x32_bf16 v[122:125], v[142:145], v[188:191], v[122:125]
	v_mfma_f32_16x16x32_bf16 v[90:93], v[156:159], v[188:191], v[90:93]
	v_mfma_f32_16x16x32_bf16 v[118:121], v[142:145], v[196:199], v[118:121]
	v_mfma_f32_16x16x32_bf16 v[86:89], v[156:159], v[196:199], v[86:89]
	v_mfma_f32_16x16x32_bf16 v[114:117], v[142:145], v[214:217], v[114:117]
	v_mfma_f32_16x16x32_bf16 v[82:85], v[156:159], v[214:217], v[82:85]
	s_setprio 0
	s_setprio 1
	v_mfma_f32_16x16x32_bf16 v[62:65], v[160:163], v[176:179], 0
	v_mfma_f32_16x16x32_bf16 v[30:33], v[168:171], v[176:179], 0
	v_mfma_f32_16x16x32_bf16 v[58:61], v[160:163], v[184:187], 0
	v_mfma_f32_16x16x32_bf16 v[26:29], v[168:171], v[184:187], 0
	v_mfma_f32_16x16x32_bf16 v[54:57], v[160:163], v[192:195], 0
	v_mfma_f32_16x16x32_bf16 v[22:25], v[168:171], v[192:195], 0
	v_mfma_f32_16x16x32_bf16 v[50:53], v[160:163], v[200:203], 0
	v_mfma_f32_16x16x32_bf16 v[18:21], v[168:171], v[200:203], 0
	v_mfma_f32_16x16x32_bf16 v[62:65], v[164:167], v[180:183], v[62:65]
	v_mfma_f32_16x16x32_bf16 v[30:33], v[172:175], v[180:183], v[30:33]
	v_mfma_f32_16x16x32_bf16 v[58:61], v[164:167], v[188:191], v[58:61]
	v_mfma_f32_16x16x32_bf16 v[26:29], v[172:175], v[188:191], v[26:29]
	v_mfma_f32_16x16x32_bf16 v[54:57], v[164:167], v[196:199], v[54:57]
	v_mfma_f32_16x16x32_bf16 v[22:25], v[172:175], v[196:199], v[22:25]
	v_mfma_f32_16x16x32_bf16 v[50:53], v[164:167], v[214:217], v[50:53]
	v_mfma_f32_16x16x32_bf16 v[18:21], v[172:175], v[214:217], v[18:21]
	s_setprio 0
	s_barrier
	s_add_i32 s89, s89, s56
	v_lshl_add_u64 v[146:147], s[62:63], 0, v[132:133]
	s_mov_b32 m0, s89
	s_nop 0
	global_load_lds_dwordx4 v[146:147], off
	s_add_i32 m0, s89, 0x2000
	v_lshl_add_u64 v[204:205], s[62:63], 0, v[130:131]
	s_add_u32 s62, s62, s8
	s_addc_u32 s63, s63, s9
	s_add_i32 s31, s31, s56
	global_load_lds_dwordx4 v[204:205], off
	v_lshl_add_u64 v[218:219], s[62:63], 0, v[132:133]
	s_mov_b32 m0, s31
	v_lshl_add_u64 v[220:221], s[62:63], 0, v[130:131]
	global_load_lds_dwordx4 v[218:219], off
	s_add_i32 m0, s31, 0x2000
	v_lshl_add_u64 v[222:223], s[22:23], 0, v[132:133]
	global_load_lds_dwordx4 v[220:221], off
	s_mov_b32 m0, s67
	v_lshl_add_u64 v[224:225], s[22:23], 0, v[130:131]
	global_load_lds_dwordx4 v[222:223], off
	s_mov_b32 m0, s72
	s_nop 0
	global_load_lds_dwordx4 v[224:225], off
	ds_read_b128 v[176:179], v150 offset:16384
	ds_read_b128 v[180:183], v150 offset:17408
	ds_read_b128 v[184:187], v150 offset:18432
	ds_read_b128 v[188:191], v150 offset:19456
	ds_read_b128 v[192:195], v150 offset:20480
	ds_read_b128 v[196:199], v150 offset:21504
	ds_read_b128 v[200:203], v150 offset:22528
	ds_read_b128 v[214:217], v150 offset:23552
	s_waitcnt lgkmcnt(0)
	s_waitcnt vmcnt(8)
	s_barrier
	s_setprio 1
	s_waitcnt lgkmcnt(0)
	v_mfma_f32_16x16x32_bf16 v[110:113], v[138:141], v[176:179], 0
	v_mfma_f32_16x16x32_bf16 v[78:81], v[152:155], v[176:179], 0
	v_mfma_f32_16x16x32_bf16 v[106:109], v[138:141], v[184:187], 0
	v_mfma_f32_16x16x32_bf16 v[74:77], v[152:155], v[184:187], 0
	v_mfma_f32_16x16x32_bf16 v[102:105], v[138:141], v[192:195], 0
	v_mfma_f32_16x16x32_bf16 v[70:73], v[152:155], v[192:195], 0
	v_mfma_f32_16x16x32_bf16 v[98:101], v[138:141], v[200:203], 0
	v_mfma_f32_16x16x32_bf16 v[66:69], v[152:155], v[200:203], 0
	v_mfma_f32_16x16x32_bf16 v[110:113], v[142:145], v[180:183], v[110:113]
	v_mfma_f32_16x16x32_bf16 v[78:81], v[156:159], v[180:183], v[78:81]
	v_mfma_f32_16x16x32_bf16 v[106:109], v[142:145], v[188:191], v[106:109]
	v_mfma_f32_16x16x32_bf16 v[74:77], v[156:159], v[188:191], v[74:77]
	v_mfma_f32_16x16x32_bf16 v[102:105], v[142:145], v[196:199], v[102:105]
	v_mfma_f32_16x16x32_bf16 v[70:73], v[156:159], v[196:199], v[70:73]
	v_mfma_f32_16x16x32_bf16 v[98:101], v[142:145], v[214:217], v[98:101]
	v_mfma_f32_16x16x32_bf16 v[66:69], v[156:159], v[214:217], v[66:69]
	s_setprio 0
	s_setprio 1
	v_mfma_f32_16x16x32_bf16 v[46:49], v[160:163], v[176:179], 0
	v_mfma_f32_16x16x32_bf16 v[14:17], v[168:171], v[176:179], 0
	v_mfma_f32_16x16x32_bf16 v[42:45], v[160:163], v[184:187], 0
	v_mfma_f32_16x16x32_bf16 v[10:13], v[168:171], v[184:187], 0
	v_mfma_f32_16x16x32_bf16 v[38:41], v[160:163], v[192:195], 0
	v_mfma_f32_16x16x32_bf16 v[6:9], v[168:171], v[192:195], 0
	v_mfma_f32_16x16x32_bf16 v[34:37], v[160:163], v[200:203], 0
	v_mfma_f32_16x16x32_bf16 v[2:5], v[168:171], v[200:203], 0
	v_mfma_f32_16x16x32_bf16 v[46:49], v[164:167], v[180:183], v[46:49]
	v_mfma_f32_16x16x32_bf16 v[14:17], v[172:175], v[180:183], v[14:17]
	v_mfma_f32_16x16x32_bf16 v[42:45], v[164:167], v[188:191], v[42:45]
	v_mfma_f32_16x16x32_bf16 v[10:13], v[172:175], v[188:191], v[10:13]
	v_mfma_f32_16x16x32_bf16 v[38:41], v[164:167], v[196:199], v[38:41]
	v_mfma_f32_16x16x32_bf16 v[6:9], v[172:175], v[196:199], v[6:9]
	v_mfma_f32_16x16x32_bf16 v[34:37], v[164:167], v[214:217], v[34:37]
	v_mfma_f32_16x16x32_bf16 v[2:5], v[172:175], v[214:217], v[2:5]
	s_setprio 0
	s_barrier
	s_add_i32 s31, 0, 0x18000
	s_add_i32 s62, 0, 0x1c000
	s_add_u32 s22, s22, s8
	s_addc_u32 s23, s23, s9
	s_mov_b32 m0, s73
	v_lshl_add_u64 v[226:227], s[22:23], 0, v[132:133]
	global_load_lds_dwordx4 v[226:227], off
	v_lshl_add_u64 v[226:227], s[22:23], 0, v[130:131]
	s_mov_b32 m0, s74
	s_nop 0
	global_load_lds_dwordx4 v[226:227], off
	v_add_u32_e32 v151, s31, v148
	ds_read_b128 v[138:141], v151
	ds_read_b128 v[142:145], v151 offset:1024
	ds_read_b128 v[152:155], v151 offset:2048
	ds_read_b128 v[156:159], v151 offset:3072
	v_add_u32_e32 v151, s62, v148
	ds_read_b128 v[160:163], v151
	ds_read_b128 v[164:167], v151 offset:1024
	ds_read_b128 v[168:171], v151 offset:2048
	ds_read_b128 v[172:175], v151 offset:3072
	ds_read_b128 v[176:179], v150 offset:32768
	ds_read_b128 v[180:183], v150 offset:33792
	ds_read_b128 v[184:187], v150 offset:34816
	ds_read_b128 v[188:191], v150 offset:35840
	ds_read_b128 v[192:195], v150 offset:36864
	ds_read_b128 v[196:199], v150 offset:37888
	ds_read_b128 v[200:203], v150 offset:38912
	ds_read_b128 v[214:217], v150 offset:39936
	s_waitcnt lgkmcnt(0)
	s_waitcnt vmcnt(8)
	s_barrier
	s_setprio 1
	s_waitcnt lgkmcnt(0)
	v_mfma_f32_16x16x32_bf16 v[126:129], v[138:141], v[176:179], v[126:129]
	v_mfma_f32_16x16x32_bf16 v[94:97], v[152:155], v[176:179], v[94:97]
	v_mfma_f32_16x16x32_bf16 v[122:125], v[138:141], v[184:187], v[122:125]
	v_mfma_f32_16x16x32_bf16 v[90:93], v[152:155], v[184:187], v[90:93]
	v_mfma_f32_16x16x32_bf16 v[118:121], v[138:141], v[192:195], v[118:121]
	v_mfma_f32_16x16x32_bf16 v[86:89], v[152:155], v[192:195], v[86:89]
	v_mfma_f32_16x16x32_bf16 v[114:117], v[138:141], v[200:203], v[114:117]
	v_mfma_f32_16x16x32_bf16 v[82:85], v[152:155], v[200:203], v[82:85]
	v_mfma_f32_16x16x32_bf16 v[126:129], v[142:145], v[180:183], v[126:129]
	v_mfma_f32_16x16x32_bf16 v[94:97], v[156:159], v[180:183], v[94:97]
	v_mfma_f32_16x16x32_bf16 v[122:125], v[142:145], v[188:191], v[122:125]
	v_mfma_f32_16x16x32_bf16 v[90:93], v[156:159], v[188:191], v[90:93]
	v_mfma_f32_16x16x32_bf16 v[118:121], v[142:145], v[196:199], v[118:121]
	v_mfma_f32_16x16x32_bf16 v[86:89], v[156:159], v[196:199], v[86:89]
	v_mfma_f32_16x16x32_bf16 v[114:117], v[142:145], v[214:217], v[114:117]
	v_mfma_f32_16x16x32_bf16 v[82:85], v[156:159], v[214:217], v[82:85]
	s_setprio 0
	s_setprio 1
	v_mfma_f32_16x16x32_bf16 v[62:65], v[160:163], v[176:179], v[62:65]
	v_mfma_f32_16x16x32_bf16 v[30:33], v[168:171], v[176:179], v[30:33]
	v_mfma_f32_16x16x32_bf16 v[58:61], v[160:163], v[184:187], v[58:61]
	v_mfma_f32_16x16x32_bf16 v[26:29], v[168:171], v[184:187], v[26:29]
	v_mfma_f32_16x16x32_bf16 v[54:57], v[160:163], v[192:195], v[54:57]
	v_mfma_f32_16x16x32_bf16 v[22:25], v[168:171], v[192:195], v[22:25]
	v_mfma_f32_16x16x32_bf16 v[50:53], v[160:163], v[200:203], v[50:53]
	v_mfma_f32_16x16x32_bf16 v[18:21], v[168:171], v[200:203], v[18:21]
	v_mfma_f32_16x16x32_bf16 v[62:65], v[164:167], v[180:183], v[62:65]
	v_mfma_f32_16x16x32_bf16 v[30:33], v[172:175], v[180:183], v[30:33]
	v_mfma_f32_16x16x32_bf16 v[58:61], v[164:167], v[188:191], v[58:61]
	v_mfma_f32_16x16x32_bf16 v[26:29], v[172:175], v[188:191], v[26:29]
	v_mfma_f32_16x16x32_bf16 v[54:57], v[164:167], v[196:199], v[54:57]
	v_mfma_f32_16x16x32_bf16 v[22:25], v[172:175], v[196:199], v[22:25]
	v_mfma_f32_16x16x32_bf16 v[50:53], v[164:167], v[214:217], v[50:53]
	v_mfma_f32_16x16x32_bf16 v[18:21], v[172:175], v[214:217], v[18:21]
	s_setprio 0
	s_barrier
	s_add_i32 s22, s31, s56
	v_lshl_add_u64 v[146:147], v[146:147], 0, s[60:61]
	s_mov_b32 m0, s22
	s_nop 0
	global_load_lds_dwordx4 v[146:147], off
	v_lshl_add_u64 v[146:147], v[204:205], 0, s[60:61]
	s_add_i32 m0, s22, 0x2000
	s_add_i32 s22, s62, s56
	global_load_lds_dwordx4 v[146:147], off
	v_lshl_add_u64 v[146:147], v[218:219], 0, s[60:61]
	s_mov_b32 m0, s22
	s_nop 0
	global_load_lds_dwordx4 v[146:147], off
	v_lshl_add_u64 v[146:147], v[220:221], 0, s[60:61]
	s_add_i32 m0, s22, 0x2000
	s_nop 0
	global_load_lds_dwordx4 v[146:147], off
	v_lshl_add_u64 v[146:147], v[222:223], 0, s[60:61]
	s_mov_b32 m0, s77
	s_nop 0
	global_load_lds_dwordx4 v[146:147], off
	v_lshl_add_u64 v[146:147], v[224:225], 0, s[60:61]
	s_mov_b32 m0, s78
	s_nop 0
	global_load_lds_dwordx4 v[146:147], off
	ds_read_b128 v[176:179], v150 offset:49152
	ds_read_b128 v[180:183], v150 offset:50176
	ds_read_b128 v[184:187], v150 offset:51200
	ds_read_b128 v[188:191], v150 offset:52224
	ds_read_b128 v[192:195], v150 offset:53248
	ds_read_b128 v[196:199], v150 offset:54272
	ds_read_b128 v[200:203], v150 offset:55296
	ds_read_b128 v[214:217], v150 offset:56320
	s_waitcnt lgkmcnt(0)
	s_waitcnt vmcnt(8)
	s_barrier
	s_setprio 1
	s_waitcnt lgkmcnt(0)
	v_mfma_f32_16x16x32_bf16 v[110:113], v[138:141], v[176:179], v[110:113]
	v_mfma_f32_16x16x32_bf16 v[78:81], v[152:155], v[176:179], v[78:81]
	v_mfma_f32_16x16x32_bf16 v[106:109], v[138:141], v[184:187], v[106:109]
	v_mfma_f32_16x16x32_bf16 v[74:77], v[152:155], v[184:187], v[74:77]
	v_mfma_f32_16x16x32_bf16 v[102:105], v[138:141], v[192:195], v[102:105]
	v_mfma_f32_16x16x32_bf16 v[70:73], v[152:155], v[192:195], v[70:73]
	v_mfma_f32_16x16x32_bf16 v[98:101], v[138:141], v[200:203], v[98:101]
	v_mfma_f32_16x16x32_bf16 v[66:69], v[152:155], v[200:203], v[66:69]
	v_mfma_f32_16x16x32_bf16 v[110:113], v[142:145], v[180:183], v[110:113]
	v_mfma_f32_16x16x32_bf16 v[78:81], v[156:159], v[180:183], v[78:81]
	v_mfma_f32_16x16x32_bf16 v[106:109], v[142:145], v[188:191], v[106:109]
	v_mfma_f32_16x16x32_bf16 v[74:77], v[156:159], v[188:191], v[74:77]
	v_mfma_f32_16x16x32_bf16 v[102:105], v[142:145], v[196:199], v[102:105]
	v_mfma_f32_16x16x32_bf16 v[70:73], v[156:159], v[196:199], v[70:73]
	v_mfma_f32_16x16x32_bf16 v[98:101], v[142:145], v[214:217], v[98:101]
	v_mfma_f32_16x16x32_bf16 v[66:69], v[156:159], v[214:217], v[66:69]
	s_setprio 0
	s_setprio 1
	v_mfma_f32_16x16x32_bf16 v[46:49], v[160:163], v[176:179], v[46:49]
	v_mfma_f32_16x16x32_bf16 v[14:17], v[168:171], v[176:179], v[14:17]
	v_mfma_f32_16x16x32_bf16 v[42:45], v[160:163], v[184:187], v[42:45]
	v_mfma_f32_16x16x32_bf16 v[10:13], v[168:171], v[184:187], v[10:13]
	v_mfma_f32_16x16x32_bf16 v[38:41], v[160:163], v[192:195], v[38:41]
	v_mfma_f32_16x16x32_bf16 v[6:9], v[168:171], v[192:195], v[6:9]
	v_mfma_f32_16x16x32_bf16 v[34:37], v[160:163], v[200:203], v[34:37]
	v_mfma_f32_16x16x32_bf16 v[2:5], v[168:171], v[200:203], v[2:5]
	v_mfma_f32_16x16x32_bf16 v[46:49], v[164:167], v[180:183], v[46:49]
	v_mfma_f32_16x16x32_bf16 v[14:17], v[172:175], v[180:183], v[14:17]
	v_mfma_f32_16x16x32_bf16 v[42:45], v[164:167], v[188:191], v[42:45]
	v_mfma_f32_16x16x32_bf16 v[10:13], v[172:175], v[188:191], v[10:13]
	v_mfma_f32_16x16x32_bf16 v[38:41], v[164:167], v[196:199], v[38:41]
	v_mfma_f32_16x16x32_bf16 v[6:9], v[172:175], v[196:199], v[6:9]
	v_mfma_f32_16x16x32_bf16 v[34:37], v[164:167], v[214:217], v[34:37]
	v_mfma_f32_16x16x32_bf16 v[2:5], v[172:175], v[214:217], v[2:5]
	s_setprio 0
	s_barrier
	s_add_u32 s20, s20, 0x100
	s_addc_u32 s21, s21, 0
	s_add_u32 vcc_lo, vcc_lo, 0x100
	s_addc_u32 vcc_hi, vcc_hi, 0
	s_cmp_ge_i32 s88, s79
	s_mov_b32 s22, s88
	s_cbranch_scc1 .LBB0_361
.LBB0_360:
	s_add_i32 s88, s22, 2
	s_add_u32 s31, s20, 0x80
	s_addc_u32 s23, s21, 0
	s_add_i32 s89, 0, 0x10000
	s_cmp_eq_u32 s90, s22
	s_cselect_b32 s23, s3, s23
	s_cselect_b32 s22, s2, s31
	s_cselect_b32 s63, s19, vcc_hi
	s_cselect_b32 s62, s18, vcc_lo
	s_add_i32 s31, 0, 0x14000
	v_lshl_add_u64 v[146:147], s[20:21], 0, v[134:135]
	s_add_i32 m0, s67, 0xc000
	s_nop 0
	global_load_lds_dwordx4 v[146:147], off
	v_lshl_add_u64 v[146:147], s[20:21], 0, v[136:137]
	s_add_i32 m0, s67, 0xe000
	s_nop 0
	global_load_lds_dwordx4 v[146:147], off
	v_add_u32_e32 v146, s89, v148
	ds_read_b128 v[138:141], v146
	ds_read_b128 v[142:145], v146 offset:1024
	ds_read_b128 v[152:155], v146 offset:2048
	ds_read_b128 v[156:159], v146 offset:3072
	v_add_u32_e32 v146, s31, v148
	ds_read_b128 v[160:163], v146
	ds_read_b128 v[164:167], v146 offset:1024
	ds_read_b128 v[168:171], v146 offset:2048
	ds_read_b128 v[172:175], v146 offset:3072
	ds_read_b128 v[176:179], v150
	ds_read_b128 v[180:183], v150 offset:1024
	ds_read_b128 v[184:187], v150 offset:2048
	ds_read_b128 v[188:191], v150 offset:3072
	ds_read_b128 v[192:195], v150 offset:4096
	ds_read_b128 v[196:199], v150 offset:5120
	ds_read_b128 v[200:203], v150 offset:6144
	ds_read_b128 v[214:217], v150 offset:7168
	s_waitcnt lgkmcnt(0)
	s_waitcnt vmcnt(8)
	s_barrier
	s_setprio 1
	s_waitcnt lgkmcnt(0)
	v_mfma_f32_16x16x32_bf16 v[126:129], v[138:141], v[176:179], v[126:129]
	v_mfma_f32_16x16x32_bf16 v[94:97], v[152:155], v[176:179], v[94:97]
	v_mfma_f32_16x16x32_bf16 v[122:125], v[138:141], v[184:187], v[122:125]
	v_mfma_f32_16x16x32_bf16 v[90:93], v[152:155], v[184:187], v[90:93]
	v_mfma_f32_16x16x32_bf16 v[118:121], v[138:141], v[192:195], v[118:121]
	v_mfma_f32_16x16x32_bf16 v[86:89], v[152:155], v[192:195], v[86:89]
	v_mfma_f32_16x16x32_bf16 v[114:117], v[138:141], v[200:203], v[114:117]
	v_mfma_f32_16x16x32_bf16 v[82:85], v[152:155], v[200:203], v[82:85]
	v_mfma_f32_16x16x32_bf16 v[126:129], v[142:145], v[180:183], v[126:129]
	v_mfma_f32_16x16x32_bf16 v[94:97], v[156:159], v[180:183], v[94:97]
	v_mfma_f32_16x16x32_bf16 v[122:125], v[142:145], v[188:191], v[122:125]
	v_mfma_f32_16x16x32_bf16 v[90:93], v[156:159], v[188:191], v[90:93]
	v_mfma_f32_16x16x32_bf16 v[118:121], v[142:145], v[196:199], v[118:121]
	v_mfma_f32_16x16x32_bf16 v[86:89], v[156:159], v[196:199], v[86:89]
	v_mfma_f32_16x16x32_bf16 v[114:117], v[142:145], v[214:217], v[114:117]
	v_mfma_f32_16x16x32_bf16 v[82:85], v[156:159], v[214:217], v[82:85]
	s_setprio 0
	s_setprio 1
	v_mfma_f32_16x16x32_bf16 v[62:65], v[160:163], v[176:179], v[62:65]
	v_mfma_f32_16x16x32_bf16 v[30:33], v[168:171], v[176:179], v[30:33]
	v_mfma_f32_16x16x32_bf16 v[58:61], v[160:163], v[184:187], v[58:61]
	v_mfma_f32_16x16x32_bf16 v[26:29], v[168:171], v[184:187], v[26:29]
	v_mfma_f32_16x16x32_bf16 v[54:57], v[160:163], v[192:195], v[54:57]
	v_mfma_f32_16x16x32_bf16 v[22:25], v[168:171], v[192:195], v[22:25]
	v_mfma_f32_16x16x32_bf16 v[50:53], v[160:163], v[200:203], v[50:53]
	v_mfma_f32_16x16x32_bf16 v[18:21], v[168:171], v[200:203], v[18:21]
	v_mfma_f32_16x16x32_bf16 v[62:65], v[164:167], v[180:183], v[62:65]
	v_mfma_f32_16x16x32_bf16 v[30:33], v[172:175], v[180:183], v[30:33]
	v_mfma_f32_16x16x32_bf16 v[58:61], v[164:167], v[188:191], v[58:61]
	v_mfma_f32_16x16x32_bf16 v[26:29], v[172:175], v[188:191], v[26:29]
	v_mfma_f32_16x16x32_bf16 v[54:57], v[164:167], v[196:199], v[54:57]
	v_mfma_f32_16x16x32_bf16 v[22:25], v[172:175], v[196:199], v[22:25]
	v_mfma_f32_16x16x32_bf16 v[50:53], v[164:167], v[214:217], v[50:53]
	v_mfma_f32_16x16x32_bf16 v[18:21], v[172:175], v[214:217], v[18:21]
	s_setprio 0
	s_barrier
	s_add_i32 s89, s89, s56
	v_lshl_add_u64 v[146:147], s[62:63], 0, v[132:133]
	s_mov_b32 m0, s89
	s_nop 0
	global_load_lds_dwordx4 v[146:147], off
	s_add_i32 m0, s89, 0x2000
	v_lshl_add_u64 v[204:205], s[62:63], 0, v[130:131]
	s_add_u32 s62, s62, s8
	s_addc_u32 s63, s63, s9
	s_add_i32 s31, s31, s56
	global_load_lds_dwordx4 v[204:205], off
	v_lshl_add_u64 v[218:219], s[62:63], 0, v[132:133]
	s_mov_b32 m0, s31
	v_lshl_add_u64 v[220:221], s[62:63], 0, v[130:131]
	global_load_lds_dwordx4 v[218:219], off
	s_add_i32 m0, s31, 0x2000
	v_lshl_add_u64 v[222:223], s[22:23], 0, v[132:133]
	global_load_lds_dwordx4 v[220:221], off
	s_mov_b32 m0, s67
	v_lshl_add_u64 v[224:225], s[22:23], 0, v[130:131]
	global_load_lds_dwordx4 v[222:223], off
	s_mov_b32 m0, s72
	s_nop 0
	global_load_lds_dwordx4 v[224:225], off
	ds_read_b128 v[176:179], v150 offset:16384
	ds_read_b128 v[180:183], v150 offset:17408
	ds_read_b128 v[184:187], v150 offset:18432
	ds_read_b128 v[188:191], v150 offset:19456
	ds_read_b128 v[192:195], v150 offset:20480
	ds_read_b128 v[196:199], v150 offset:21504
	ds_read_b128 v[200:203], v150 offset:22528
	ds_read_b128 v[214:217], v150 offset:23552
	s_waitcnt lgkmcnt(0)
	s_waitcnt vmcnt(8)
	s_barrier
	s_setprio 1
	s_waitcnt lgkmcnt(0)
	v_mfma_f32_16x16x32_bf16 v[110:113], v[138:141], v[176:179], v[110:113]
	v_mfma_f32_16x16x32_bf16 v[78:81], v[152:155], v[176:179], v[78:81]
	v_mfma_f32_16x16x32_bf16 v[106:109], v[138:141], v[184:187], v[106:109]
	v_mfma_f32_16x16x32_bf16 v[74:77], v[152:155], v[184:187], v[74:77]
	v_mfma_f32_16x16x32_bf16 v[102:105], v[138:141], v[192:195], v[102:105]
	v_mfma_f32_16x16x32_bf16 v[70:73], v[152:155], v[192:195], v[70:73]
	v_mfma_f32_16x16x32_bf16 v[98:101], v[138:141], v[200:203], v[98:101]
	v_mfma_f32_16x16x32_bf16 v[66:69], v[152:155], v[200:203], v[66:69]
	v_mfma_f32_16x16x32_bf16 v[110:113], v[142:145], v[180:183], v[110:113]
	v_mfma_f32_16x16x32_bf16 v[78:81], v[156:159], v[180:183], v[78:81]
	v_mfma_f32_16x16x32_bf16 v[106:109], v[142:145], v[188:191], v[106:109]
	v_mfma_f32_16x16x32_bf16 v[74:77], v[156:159], v[188:191], v[74:77]
	v_mfma_f32_16x16x32_bf16 v[102:105], v[142:145], v[196:199], v[102:105]
	v_mfma_f32_16x16x32_bf16 v[70:73], v[156:159], v[196:199], v[70:73]
	v_mfma_f32_16x16x32_bf16 v[98:101], v[142:145], v[214:217], v[98:101]
	v_mfma_f32_16x16x32_bf16 v[66:69], v[156:159], v[214:217], v[66:69]
	s_setprio 0
	s_setprio 1
	v_mfma_f32_16x16x32_bf16 v[46:49], v[160:163], v[176:179], v[46:49]
	v_mfma_f32_16x16x32_bf16 v[14:17], v[168:171], v[176:179], v[14:17]
	v_mfma_f32_16x16x32_bf16 v[42:45], v[160:163], v[184:187], v[42:45]
	v_mfma_f32_16x16x32_bf16 v[10:13], v[168:171], v[184:187], v[10:13]
	v_mfma_f32_16x16x32_bf16 v[38:41], v[160:163], v[192:195], v[38:41]
	v_mfma_f32_16x16x32_bf16 v[6:9], v[168:171], v[192:195], v[6:9]
	v_mfma_f32_16x16x32_bf16 v[34:37], v[160:163], v[200:203], v[34:37]
	v_mfma_f32_16x16x32_bf16 v[2:5], v[168:171], v[200:203], v[2:5]
	v_mfma_f32_16x16x32_bf16 v[46:49], v[164:167], v[180:183], v[46:49]
	v_mfma_f32_16x16x32_bf16 v[14:17], v[172:175], v[180:183], v[14:17]
	v_mfma_f32_16x16x32_bf16 v[42:45], v[164:167], v[188:191], v[42:45]
	v_mfma_f32_16x16x32_bf16 v[10:13], v[172:175], v[188:191], v[10:13]
	v_mfma_f32_16x16x32_bf16 v[38:41], v[164:167], v[196:199], v[38:41]
	v_mfma_f32_16x16x32_bf16 v[6:9], v[172:175], v[196:199], v[6:9]
	v_mfma_f32_16x16x32_bf16 v[34:37], v[164:167], v[214:217], v[34:37]
	v_mfma_f32_16x16x32_bf16 v[2:5], v[172:175], v[214:217], v[2:5]
	s_setprio 0
	s_barrier
	s_add_i32 s31, 0, 0x18000
	s_add_i32 s62, 0, 0x1c000
	s_add_u32 s22, s22, s8
	s_addc_u32 s23, s23, s9
	s_mov_b32 m0, s73
	v_lshl_add_u64 v[226:227], s[22:23], 0, v[132:133]
	global_load_lds_dwordx4 v[226:227], off
	v_lshl_add_u64 v[226:227], s[22:23], 0, v[130:131]
	s_mov_b32 m0, s74
	s_nop 0
	global_load_lds_dwordx4 v[226:227], off
	v_add_u32_e32 v151, s31, v148
	ds_read_b128 v[138:141], v151
	ds_read_b128 v[142:145], v151 offset:1024
	ds_read_b128 v[152:155], v151 offset:2048
	ds_read_b128 v[156:159], v151 offset:3072
	v_add_u32_e32 v151, s62, v148
	ds_read_b128 v[160:163], v151
	ds_read_b128 v[164:167], v151 offset:1024
	ds_read_b128 v[168:171], v151 offset:2048
	ds_read_b128 v[172:175], v151 offset:3072
	ds_read_b128 v[176:179], v150 offset:32768
	ds_read_b128 v[180:183], v150 offset:33792
	ds_read_b128 v[184:187], v150 offset:34816
	ds_read_b128 v[188:191], v150 offset:35840
	ds_read_b128 v[192:195], v150 offset:36864
	ds_read_b128 v[196:199], v150 offset:37888
	ds_read_b128 v[200:203], v150 offset:38912
	ds_read_b128 v[214:217], v150 offset:39936
	s_waitcnt lgkmcnt(0)
	s_waitcnt vmcnt(8)
	s_barrier
	s_setprio 1
	s_waitcnt lgkmcnt(0)
	v_mfma_f32_16x16x32_bf16 v[126:129], v[138:141], v[176:179], v[126:129]
	v_mfma_f32_16x16x32_bf16 v[94:97], v[152:155], v[176:179], v[94:97]
	v_mfma_f32_16x16x32_bf16 v[122:125], v[138:141], v[184:187], v[122:125]
	v_mfma_f32_16x16x32_bf16 v[90:93], v[152:155], v[184:187], v[90:93]
	v_mfma_f32_16x16x32_bf16 v[118:121], v[138:141], v[192:195], v[118:121]
	v_mfma_f32_16x16x32_bf16 v[86:89], v[152:155], v[192:195], v[86:89]
	v_mfma_f32_16x16x32_bf16 v[114:117], v[138:141], v[200:203], v[114:117]
	v_mfma_f32_16x16x32_bf16 v[82:85], v[152:155], v[200:203], v[82:85]
	v_mfma_f32_16x16x32_bf16 v[126:129], v[142:145], v[180:183], v[126:129]
	v_mfma_f32_16x16x32_bf16 v[94:97], v[156:159], v[180:183], v[94:97]
	v_mfma_f32_16x16x32_bf16 v[122:125], v[142:145], v[188:191], v[122:125]
	v_mfma_f32_16x16x32_bf16 v[90:93], v[156:159], v[188:191], v[90:93]
	v_mfma_f32_16x16x32_bf16 v[118:121], v[142:145], v[196:199], v[118:121]
	v_mfma_f32_16x16x32_bf16 v[86:89], v[156:159], v[196:199], v[86:89]
	v_mfma_f32_16x16x32_bf16 v[114:117], v[142:145], v[214:217], v[114:117]
	v_mfma_f32_16x16x32_bf16 v[82:85], v[156:159], v[214:217], v[82:85]
	s_setprio 0
	s_setprio 1
	v_mfma_f32_16x16x32_bf16 v[62:65], v[160:163], v[176:179], v[62:65]
	v_mfma_f32_16x16x32_bf16 v[30:33], v[168:171], v[176:179], v[30:33]
	v_mfma_f32_16x16x32_bf16 v[58:61], v[160:163], v[184:187], v[58:61]
	v_mfma_f32_16x16x32_bf16 v[26:29], v[168:171], v[184:187], v[26:29]
	v_mfma_f32_16x16x32_bf16 v[54:57], v[160:163], v[192:195], v[54:57]
	v_mfma_f32_16x16x32_bf16 v[22:25], v[168:171], v[192:195], v[22:25]
	v_mfma_f32_16x16x32_bf16 v[50:53], v[160:163], v[200:203], v[50:53]
	v_mfma_f32_16x16x32_bf16 v[18:21], v[168:171], v[200:203], v[18:21]
	v_mfma_f32_16x16x32_bf16 v[62:65], v[164:167], v[180:183], v[62:65]
	v_mfma_f32_16x16x32_bf16 v[30:33], v[172:175], v[180:183], v[30:33]
	v_mfma_f32_16x16x32_bf16 v[58:61], v[164:167], v[188:191], v[58:61]
	v_mfma_f32_16x16x32_bf16 v[26:29], v[172:175], v[188:191], v[26:29]
	v_mfma_f32_16x16x32_bf16 v[54:57], v[164:167], v[196:199], v[54:57]
	v_mfma_f32_16x16x32_bf16 v[22:25], v[172:175], v[196:199], v[22:25]
	v_mfma_f32_16x16x32_bf16 v[50:53], v[164:167], v[214:217], v[50:53]
	v_mfma_f32_16x16x32_bf16 v[18:21], v[172:175], v[214:217], v[18:21]
	s_setprio 0
	s_barrier
	s_add_i32 s22, s31, s56
	v_lshl_add_u64 v[146:147], v[146:147], 0, s[60:61]
	s_mov_b32 m0, s22
	s_nop 0
	global_load_lds_dwordx4 v[146:147], off
	v_lshl_add_u64 v[146:147], v[204:205], 0, s[60:61]
	s_add_i32 m0, s22, 0x2000
	s_add_i32 s22, s62, s56
	global_load_lds_dwordx4 v[146:147], off
	v_lshl_add_u64 v[146:147], v[218:219], 0, s[60:61]
	s_mov_b32 m0, s22
	s_nop 0
	global_load_lds_dwordx4 v[146:147], off
	v_lshl_add_u64 v[146:147], v[220:221], 0, s[60:61]
	s_add_i32 m0, s22, 0x2000
	s_nop 0
	global_load_lds_dwordx4 v[146:147], off
	v_lshl_add_u64 v[146:147], v[222:223], 0, s[60:61]
	s_mov_b32 m0, s77
	s_nop 0
	global_load_lds_dwordx4 v[146:147], off
	v_lshl_add_u64 v[146:147], v[224:225], 0, s[60:61]
	s_mov_b32 m0, s78
	s_nop 0
	global_load_lds_dwordx4 v[146:147], off
	ds_read_b128 v[176:179], v150 offset:49152
	ds_read_b128 v[180:183], v150 offset:50176
	ds_read_b128 v[184:187], v150 offset:51200
	ds_read_b128 v[188:191], v150 offset:52224
	ds_read_b128 v[192:195], v150 offset:53248
	ds_read_b128 v[196:199], v150 offset:54272
	ds_read_b128 v[200:203], v150 offset:55296
	ds_read_b128 v[214:217], v150 offset:56320
	s_waitcnt lgkmcnt(0)
	s_waitcnt vmcnt(8)
	s_barrier
	s_setprio 1
	s_waitcnt lgkmcnt(0)
	v_mfma_f32_16x16x32_bf16 v[110:113], v[138:141], v[176:179], v[110:113]
	v_mfma_f32_16x16x32_bf16 v[78:81], v[152:155], v[176:179], v[78:81]
	v_mfma_f32_16x16x32_bf16 v[106:109], v[138:141], v[184:187], v[106:109]
	v_mfma_f32_16x16x32_bf16 v[74:77], v[152:155], v[184:187], v[74:77]
	v_mfma_f32_16x16x32_bf16 v[102:105], v[138:141], v[192:195], v[102:105]
	v_mfma_f32_16x16x32_bf16 v[70:73], v[152:155], v[192:195], v[70:73]
	v_mfma_f32_16x16x32_bf16 v[98:101], v[138:141], v[200:203], v[98:101]
	v_mfma_f32_16x16x32_bf16 v[66:69], v[152:155], v[200:203], v[66:69]
	v_mfma_f32_16x16x32_bf16 v[110:113], v[142:145], v[180:183], v[110:113]
	v_mfma_f32_16x16x32_bf16 v[78:81], v[156:159], v[180:183], v[78:81]
	v_mfma_f32_16x16x32_bf16 v[106:109], v[142:145], v[188:191], v[106:109]
	v_mfma_f32_16x16x32_bf16 v[74:77], v[156:159], v[188:191], v[74:77]
	v_mfma_f32_16x16x32_bf16 v[102:105], v[142:145], v[196:199], v[102:105]
	v_mfma_f32_16x16x32_bf16 v[70:73], v[156:159], v[196:199], v[70:73]
	v_mfma_f32_16x16x32_bf16 v[98:101], v[142:145], v[214:217], v[98:101]
	v_mfma_f32_16x16x32_bf16 v[66:69], v[156:159], v[214:217], v[66:69]
	s_setprio 0
	s_setprio 1
	v_mfma_f32_16x16x32_bf16 v[46:49], v[160:163], v[176:179], v[46:49]
	v_mfma_f32_16x16x32_bf16 v[14:17], v[168:171], v[176:179], v[14:17]
	v_mfma_f32_16x16x32_bf16 v[42:45], v[160:163], v[184:187], v[42:45]
	v_mfma_f32_16x16x32_bf16 v[10:13], v[168:171], v[184:187], v[10:13]
	v_mfma_f32_16x16x32_bf16 v[38:41], v[160:163], v[192:195], v[38:41]
	v_mfma_f32_16x16x32_bf16 v[6:9], v[168:171], v[192:195], v[6:9]
	v_mfma_f32_16x16x32_bf16 v[34:37], v[160:163], v[200:203], v[34:37]
	v_mfma_f32_16x16x32_bf16 v[2:5], v[168:171], v[200:203], v[2:5]
	v_mfma_f32_16x16x32_bf16 v[46:49], v[164:167], v[180:183], v[46:49]
	v_mfma_f32_16x16x32_bf16 v[14:17], v[172:175], v[180:183], v[14:17]
	v_mfma_f32_16x16x32_bf16 v[42:45], v[164:167], v[188:191], v[42:45]
	v_mfma_f32_16x16x32_bf16 v[10:13], v[172:175], v[188:191], v[10:13]
	v_mfma_f32_16x16x32_bf16 v[38:41], v[164:167], v[196:199], v[38:41]
	v_mfma_f32_16x16x32_bf16 v[6:9], v[172:175], v[196:199], v[6:9]
	v_mfma_f32_16x16x32_bf16 v[34:37], v[164:167], v[214:217], v[34:37]
	v_mfma_f32_16x16x32_bf16 v[2:5], v[172:175], v[214:217], v[2:5]
	s_setprio 0
	s_barrier
	s_add_u32 s20, s20, 0x100
	s_addc_u32 s21, s21, 0
	s_add_u32 vcc_lo, vcc_lo, 0x100
	s_addc_u32 vcc_hi, vcc_hi, 0
	s_cmp_ge_i32 s88, s79
	s_mov_b32 s22, s88
	s_cbranch_scc0 .LBB0_360

.Lzgo_3:
	s_add_u32 s18, s18, 0x80
	s_addc_u32 s19, s19, 0
	s_add_u32 s71, s20, 0x100
	s_addc_u32 s72, s21, 0
	s_mov_b32 s20, 0
	s_add_i32 s73, s20, 2
	s_add_u32 s31, s18, 0x80
	s_addc_u32 s21, s19, 0
	s_add_i32 s74, 0, 0x10000
	s_cmp_eq_u32 s11, s20
	s_cselect_b32 s21, s3, s21
	s_cselect_b32 s20, s2, s31
	s_cselect_b32 s63, s17, s72
	s_cselect_b32 s62, s16, s71
	s_add_i32 s31, 0, 0x14000
	v_lshl_add_u64 v[218:219], s[18:19], 0, v[138:139]
	s_add_i32 m0, s23, 0xc000
	s_nop 0
	global_load_lds_dwordx4 v[218:219], off
	v_lshl_add_u64 v[218:219], s[18:19], 0, v[140:141]
	s_add_i32 m0, s23, 0xe000
	s_nop 0
	global_load_lds_dwordx4 v[218:219], off
	v_add_u32_e32 v145, s74, v142
	ds_read_b128 v[146:149], v145
	ds_read_b128 v[150:153], v145 offset:1024
	ds_read_b128 v[154:157], v145 offset:2048
	ds_read_b128 v[158:161], v145 offset:3072
	v_add_u32_e32 v145, s31, v142
	ds_read_b128 v[162:165], v145
	ds_read_b128 v[166:169], v145 offset:1024
	ds_read_b128 v[170:173], v145 offset:2048
	ds_read_b128 v[174:177], v145 offset:3072
	ds_read_b128 v[178:181], v144
	ds_read_b128 v[182:185], v144 offset:1024
	ds_read_b128 v[186:189], v144 offset:2048
	ds_read_b128 v[190:193], v144 offset:3072
	ds_read_b128 v[194:197], v144 offset:4096
	ds_read_b128 v[198:201], v144 offset:5120
	ds_read_b128 v[202:205], v144 offset:6144
	ds_read_b128 v[214:217], v144 offset:7168
	s_waitcnt lgkmcnt(0)
	s_waitcnt vmcnt(8)
	s_barrier
	s_setprio 1
	s_waitcnt lgkmcnt(0)
	v_mfma_f32_16x16x32_bf16 v[122:125], v[146:149], v[178:181], 0
	v_mfma_f32_16x16x32_bf16 v[126:129], v[154:157], v[178:181], 0
	v_mfma_f32_16x16x32_bf16 v[118:121], v[146:149], v[186:189], 0
	v_mfma_f32_16x16x32_bf16 v[114:117], v[154:157], v[186:189], 0
	v_mfma_f32_16x16x32_bf16 v[110:113], v[146:149], v[194:197], 0
	v_mfma_f32_16x16x32_bf16 v[106:109], v[154:157], v[194:197], 0
	v_mfma_f32_16x16x32_bf16 v[102:105], v[146:149], v[202:205], 0
	v_mfma_f32_16x16x32_bf16 v[98:101], v[154:157], v[202:205], 0
	v_mfma_f32_16x16x32_bf16 v[122:125], v[150:153], v[182:185], v[122:125]
	v_mfma_f32_16x16x32_bf16 v[126:129], v[158:161], v[182:185], v[126:129]
	v_mfma_f32_16x16x32_bf16 v[118:121], v[150:153], v[190:193], v[118:121]
	v_mfma_f32_16x16x32_bf16 v[114:117], v[158:161], v[190:193], v[114:117]
	v_mfma_f32_16x16x32_bf16 v[110:113], v[150:153], v[198:201], v[110:113]
	v_mfma_f32_16x16x32_bf16 v[106:109], v[158:161], v[198:201], v[106:109]
	v_mfma_f32_16x16x32_bf16 v[102:105], v[150:153], v[214:217], v[102:105]
	v_mfma_f32_16x16x32_bf16 v[98:101], v[158:161], v[214:217], v[98:101]
	s_setprio 0
	s_setprio 1
	v_mfma_f32_16x16x32_bf16 v[62:65], v[162:165], v[178:181], 0
	v_mfma_f32_16x16x32_bf16 v[58:61], v[170:173], v[178:181], 0
	v_mfma_f32_16x16x32_bf16 v[54:57], v[162:165], v[186:189], 0
	v_mfma_f32_16x16x32_bf16 v[50:53], v[170:173], v[186:189], 0
	v_mfma_f32_16x16x32_bf16 v[46:49], v[162:165], v[194:197], 0
	v_mfma_f32_16x16x32_bf16 v[42:45], v[170:173], v[194:197], 0
	v_mfma_f32_16x16x32_bf16 v[38:41], v[162:165], v[202:205], 0
	v_mfma_f32_16x16x32_bf16 v[34:37], v[170:173], v[202:205], 0
	v_mfma_f32_16x16x32_bf16 v[62:65], v[166:169], v[182:185], v[62:65]
	v_mfma_f32_16x16x32_bf16 v[58:61], v[174:177], v[182:185], v[58:61]
	v_mfma_f32_16x16x32_bf16 v[54:57], v[166:169], v[190:193], v[54:57]
	v_mfma_f32_16x16x32_bf16 v[50:53], v[174:177], v[190:193], v[50:53]
	v_mfma_f32_16x16x32_bf16 v[46:49], v[166:169], v[198:201], v[46:49]
	v_mfma_f32_16x16x32_bf16 v[42:45], v[174:177], v[198:201], v[42:45]
	v_mfma_f32_16x16x32_bf16 v[38:41], v[166:169], v[214:217], v[38:41]
	v_mfma_f32_16x16x32_bf16 v[34:37], v[174:177], v[214:217], v[34:37]
	s_setprio 0
	s_barrier
	s_add_i32 s74, s74, s22
	v_lshl_add_u64 v[218:219], s[62:63], 0, v[134:135]
	s_mov_b32 m0, s74
	s_nop 0
	global_load_lds_dwordx4 v[218:219], off
	s_add_i32 m0, s74, 0x2000
	v_lshl_add_u64 v[220:221], s[62:63], 0, v[130:131]
	s_add_u32 s62, s62, s4
	s_addc_u32 s63, s63, s5
	s_add_i32 s31, s31, s22
	global_load_lds_dwordx4 v[220:221], off
	v_lshl_add_u64 v[222:223], s[62:63], 0, v[134:135]
	s_mov_b32 m0, s31
	v_lshl_add_u64 v[224:225], s[62:63], 0, v[130:131]
	global_load_lds_dwordx4 v[222:223], off
	s_add_i32 m0, s31, 0x2000
	v_lshl_add_u64 v[226:227], s[20:21], 0, v[136:137]
	global_load_lds_dwordx4 v[224:225], off
	s_mov_b32 m0, s23
	v_lshl_add_u64 v[236:237], s[20:21], 0, v[132:133]
	global_load_lds_dwordx4 v[226:227], off
	s_mov_b32 m0, s52
	s_nop 0
	global_load_lds_dwordx4 v[236:237], off
	ds_read_b128 v[178:181], v144 offset:16384
	ds_read_b128 v[182:185], v144 offset:17408
	ds_read_b128 v[186:189], v144 offset:18432
	ds_read_b128 v[190:193], v144 offset:19456
	ds_read_b128 v[194:197], v144 offset:20480
	ds_read_b128 v[198:201], v144 offset:21504
	ds_read_b128 v[202:205], v144 offset:22528
	ds_read_b128 v[214:217], v144 offset:23552
	s_waitcnt lgkmcnt(0)
	s_waitcnt vmcnt(8)
	s_barrier
	s_setprio 1
	s_waitcnt lgkmcnt(0)
	v_mfma_f32_16x16x32_bf16 v[94:97], v[146:149], v[178:181], 0
	v_mfma_f32_16x16x32_bf16 v[90:93], v[154:157], v[178:181], 0
	v_mfma_f32_16x16x32_bf16 v[86:89], v[146:149], v[186:189], 0
	v_mfma_f32_16x16x32_bf16 v[82:85], v[154:157], v[186:189], 0
	v_mfma_f32_16x16x32_bf16 v[78:81], v[146:149], v[194:197], 0
	v_mfma_f32_16x16x32_bf16 v[74:77], v[154:157], v[194:197], 0
	v_mfma_f32_16x16x32_bf16 v[70:73], v[146:149], v[202:205], 0
	v_mfma_f32_16x16x32_bf16 v[66:69], v[154:157], v[202:205], 0
	v_mfma_f32_16x16x32_bf16 v[94:97], v[150:153], v[182:185], v[94:97]
	v_mfma_f32_16x16x32_bf16 v[90:93], v[158:161], v[182:185], v[90:93]
	v_mfma_f32_16x16x32_bf16 v[86:89], v[150:153], v[190:193], v[86:89]
	v_mfma_f32_16x16x32_bf16 v[82:85], v[158:161], v[190:193], v[82:85]
	v_mfma_f32_16x16x32_bf16 v[78:81], v[150:153], v[198:201], v[78:81]
	v_mfma_f32_16x16x32_bf16 v[74:77], v[158:161], v[198:201], v[74:77]
	v_mfma_f32_16x16x32_bf16 v[70:73], v[150:153], v[214:217], v[70:73]
	v_mfma_f32_16x16x32_bf16 v[66:69], v[158:161], v[214:217], v[66:69]
	s_setprio 0
	s_setprio 1
	v_mfma_f32_16x16x32_bf16 v[30:33], v[162:165], v[178:181], 0
	v_mfma_f32_16x16x32_bf16 v[26:29], v[170:173], v[178:181], 0
	v_mfma_f32_16x16x32_bf16 v[22:25], v[162:165], v[186:189], 0
	v_mfma_f32_16x16x32_bf16 v[18:21], v[170:173], v[186:189], 0
	v_mfma_f32_16x16x32_bf16 v[14:17], v[162:165], v[194:197], 0
	v_mfma_f32_16x16x32_bf16 v[10:13], v[170:173], v[194:197], 0
	v_mfma_f32_16x16x32_bf16 v[6:9], v[162:165], v[202:205], 0
	v_mfma_f32_16x16x32_bf16 v[2:5], v[170:173], v[202:205], 0
	v_mfma_f32_16x16x32_bf16 v[30:33], v[166:169], v[182:185], v[30:33]
	v_mfma_f32_16x16x32_bf16 v[26:29], v[174:177], v[182:185], v[26:29]
	v_mfma_f32_16x16x32_bf16 v[22:25], v[166:169], v[190:193], v[22:25]
	v_mfma_f32_16x16x32_bf16 v[18:21], v[174:177], v[190:193], v[18:21]
	v_mfma_f32_16x16x32_bf16 v[14:17], v[166:169], v[198:201], v[14:17]
	v_mfma_f32_16x16x32_bf16 v[10:13], v[174:177], v[198:201], v[10:13]
	v_mfma_f32_16x16x32_bf16 v[6:9], v[166:169], v[214:217], v[6:9]
	v_mfma_f32_16x16x32_bf16 v[2:5], v[174:177], v[214:217], v[2:5]
	s_setprio 0
	s_barrier
	s_add_i32 s31, 0, 0x18000
	s_add_i32 s62, 0, 0x1c000
	s_add_u32 s20, s20, s4
	s_addc_u32 s21, s21, s5
	s_mov_b32 m0, s53
	v_lshl_add_u64 v[238:239], s[20:21], 0, v[136:137]
	global_load_lds_dwordx4 v[238:239], off
	v_lshl_add_u64 v[238:239], s[20:21], 0, v[132:133]
	s_mov_b32 m0, s56
	s_nop 0
	global_load_lds_dwordx4 v[238:239], off
	v_add_u32_e32 v145, s31, v142
	ds_read_b128 v[146:149], v145
	ds_read_b128 v[150:153], v145 offset:1024
	ds_read_b128 v[154:157], v145 offset:2048
	ds_read_b128 v[158:161], v145 offset:3072
	v_add_u32_e32 v145, s62, v142
	ds_read_b128 v[162:165], v145
	ds_read_b128 v[166:169], v145 offset:1024
	ds_read_b128 v[170:173], v145 offset:2048
	ds_read_b128 v[174:177], v145 offset:3072
	ds_read_b128 v[178:181], v144 offset:32768
	ds_read_b128 v[182:185], v144 offset:33792
	ds_read_b128 v[186:189], v144 offset:34816
	ds_read_b128 v[190:193], v144 offset:35840
	ds_read_b128 v[194:197], v144 offset:36864
	ds_read_b128 v[198:201], v144 offset:37888
	ds_read_b128 v[202:205], v144 offset:38912
	ds_read_b128 v[214:217], v144 offset:39936
	s_waitcnt lgkmcnt(0)
	s_waitcnt vmcnt(8)
	s_barrier
	s_setprio 1
	s_waitcnt lgkmcnt(0)
	v_mfma_f32_16x16x32_bf16 v[122:125], v[146:149], v[178:181], v[122:125]
	v_mfma_f32_16x16x32_bf16 v[126:129], v[154:157], v[178:181], v[126:129]
	v_mfma_f32_16x16x32_bf16 v[118:121], v[146:149], v[186:189], v[118:121]
	v_mfma_f32_16x16x32_bf16 v[114:117], v[154:157], v[186:189], v[114:117]
	v_mfma_f32_16x16x32_bf16 v[110:113], v[146:149], v[194:197], v[110:113]
	v_mfma_f32_16x16x32_bf16 v[106:109], v[154:157], v[194:197], v[106:109]
	v_mfma_f32_16x16x32_bf16 v[102:105], v[146:149], v[202:205], v[102:105]
	v_mfma_f32_16x16x32_bf16 v[98:101], v[154:157], v[202:205], v[98:101]
	v_mfma_f32_16x16x32_bf16 v[122:125], v[150:153], v[182:185], v[122:125]
	v_mfma_f32_16x16x32_bf16 v[126:129], v[158:161], v[182:185], v[126:129]
	v_mfma_f32_16x16x32_bf16 v[118:121], v[150:153], v[190:193], v[118:121]
	v_mfma_f32_16x16x32_bf16 v[114:117], v[158:161], v[190:193], v[114:117]
	v_mfma_f32_16x16x32_bf16 v[110:113], v[150:153], v[198:201], v[110:113]
	v_mfma_f32_16x16x32_bf16 v[106:109], v[158:161], v[198:201], v[106:109]
	v_mfma_f32_16x16x32_bf16 v[102:105], v[150:153], v[214:217], v[102:105]
	v_mfma_f32_16x16x32_bf16 v[98:101], v[158:161], v[214:217], v[98:101]
	s_setprio 0
	s_setprio 1
	v_mfma_f32_16x16x32_bf16 v[62:65], v[162:165], v[178:181], v[62:65]
	v_mfma_f32_16x16x32_bf16 v[58:61], v[170:173], v[178:181], v[58:61]
	v_mfma_f32_16x16x32_bf16 v[54:57], v[162:165], v[186:189], v[54:57]
	v_mfma_f32_16x16x32_bf16 v[50:53], v[170:173], v[186:189], v[50:53]
	v_mfma_f32_16x16x32_bf16 v[46:49], v[162:165], v[194:197], v[46:49]
	v_mfma_f32_16x16x32_bf16 v[42:45], v[170:173], v[194:197], v[42:45]
	v_mfma_f32_16x16x32_bf16 v[38:41], v[162:165], v[202:205], v[38:41]
	v_mfma_f32_16x16x32_bf16 v[34:37], v[170:173], v[202:205], v[34:37]
	v_mfma_f32_16x16x32_bf16 v[62:65], v[166:169], v[182:185], v[62:65]
	v_mfma_f32_16x16x32_bf16 v[58:61], v[174:177], v[182:185], v[58:61]
	v_mfma_f32_16x16x32_bf16 v[54:57], v[166:169], v[190:193], v[54:57]
	v_mfma_f32_16x16x32_bf16 v[50:53], v[174:177], v[190:193], v[50:53]
	v_mfma_f32_16x16x32_bf16 v[46:49], v[166:169], v[198:201], v[46:49]
	v_mfma_f32_16x16x32_bf16 v[42:45], v[174:177], v[198:201], v[42:45]
	v_mfma_f32_16x16x32_bf16 v[38:41], v[166:169], v[214:217], v[38:41]
	v_mfma_f32_16x16x32_bf16 v[34:37], v[174:177], v[214:217], v[34:37]
	s_setprio 0
	s_barrier
	s_add_i32 s20, s31, s22
	v_lshl_add_u64 v[218:219], v[218:219], 0, s[60:61]
	s_mov_b32 m0, s20
	s_nop 0
	global_load_lds_dwordx4 v[218:219], off
	v_lshl_add_u64 v[218:219], v[220:221], 0, s[60:61]
	s_add_i32 m0, s20, 0x2000
	s_add_i32 s20, s62, s22
	global_load_lds_dwordx4 v[218:219], off
	v_lshl_add_u64 v[218:219], v[222:223], 0, s[60:61]
	s_mov_b32 m0, s20
	s_nop 0
	global_load_lds_dwordx4 v[218:219], off
	v_lshl_add_u64 v[218:219], v[224:225], 0, s[60:61]
	s_add_i32 m0, s20, 0x2000
	s_nop 0
	global_load_lds_dwordx4 v[218:219], off
	v_lshl_add_u64 v[218:219], v[226:227], 0, s[60:61]
	s_mov_b32 m0, s57
	s_nop 0
	global_load_lds_dwordx4 v[218:219], off
	v_lshl_add_u64 v[218:219], v[236:237], 0, s[60:61]
	s_mov_b32 m0, s65
	s_nop 0
	global_load_lds_dwordx4 v[218:219], off
	ds_read_b128 v[178:181], v144 offset:49152
	ds_read_b128 v[182:185], v144 offset:50176
	ds_read_b128 v[186:189], v144 offset:51200
	ds_read_b128 v[190:193], v144 offset:52224
	ds_read_b128 v[194:197], v144 offset:53248
	ds_read_b128 v[198:201], v144 offset:54272
	ds_read_b128 v[202:205], v144 offset:55296
	ds_read_b128 v[214:217], v144 offset:56320
	s_waitcnt lgkmcnt(0)
	s_waitcnt vmcnt(8)
	s_barrier
	s_setprio 1
	s_waitcnt lgkmcnt(0)
	v_mfma_f32_16x16x32_bf16 v[94:97], v[146:149], v[178:181], v[94:97]
	v_mfma_f32_16x16x32_bf16 v[90:93], v[154:157], v[178:181], v[90:93]
	v_mfma_f32_16x16x32_bf16 v[86:89], v[146:149], v[186:189], v[86:89]
	v_mfma_f32_16x16x32_bf16 v[82:85], v[154:157], v[186:189], v[82:85]
	v_mfma_f32_16x16x32_bf16 v[78:81], v[146:149], v[194:197], v[78:81]
	v_mfma_f32_16x16x32_bf16 v[74:77], v[154:157], v[194:197], v[74:77]
	v_mfma_f32_16x16x32_bf16 v[70:73], v[146:149], v[202:205], v[70:73]
	v_mfma_f32_16x16x32_bf16 v[66:69], v[154:157], v[202:205], v[66:69]
	v_mfma_f32_16x16x32_bf16 v[94:97], v[150:153], v[182:185], v[94:97]
	v_mfma_f32_16x16x32_bf16 v[90:93], v[158:161], v[182:185], v[90:93]
	v_mfma_f32_16x16x32_bf16 v[86:89], v[150:153], v[190:193], v[86:89]
	v_mfma_f32_16x16x32_bf16 v[82:85], v[158:161], v[190:193], v[82:85]
	v_mfma_f32_16x16x32_bf16 v[78:81], v[150:153], v[198:201], v[78:81]
	v_mfma_f32_16x16x32_bf16 v[74:77], v[158:161], v[198:201], v[74:77]
	v_mfma_f32_16x16x32_bf16 v[70:73], v[150:153], v[214:217], v[70:73]
	v_mfma_f32_16x16x32_bf16 v[66:69], v[158:161], v[214:217], v[66:69]
	s_setprio 0
	s_setprio 1
	v_mfma_f32_16x16x32_bf16 v[30:33], v[162:165], v[178:181], v[30:33]
	v_mfma_f32_16x16x32_bf16 v[26:29], v[170:173], v[178:181], v[26:29]
	v_mfma_f32_16x16x32_bf16 v[22:25], v[162:165], v[186:189], v[22:25]
	v_mfma_f32_16x16x32_bf16 v[18:21], v[170:173], v[186:189], v[18:21]
	v_mfma_f32_16x16x32_bf16 v[14:17], v[162:165], v[194:197], v[14:17]
	v_mfma_f32_16x16x32_bf16 v[10:13], v[170:173], v[194:197], v[10:13]
	v_mfma_f32_16x16x32_bf16 v[6:9], v[162:165], v[202:205], v[6:9]
	v_mfma_f32_16x16x32_bf16 v[2:5], v[170:173], v[202:205], v[2:5]
	v_mfma_f32_16x16x32_bf16 v[30:33], v[166:169], v[182:185], v[30:33]
	v_mfma_f32_16x16x32_bf16 v[26:29], v[174:177], v[182:185], v[26:29]
	v_mfma_f32_16x16x32_bf16 v[22:25], v[166:169], v[190:193], v[22:25]
	v_mfma_f32_16x16x32_bf16 v[18:21], v[174:177], v[190:193], v[18:21]
	v_mfma_f32_16x16x32_bf16 v[14:17], v[166:169], v[198:201], v[14:17]
	v_mfma_f32_16x16x32_bf16 v[10:13], v[174:177], v[198:201], v[10:13]
	v_mfma_f32_16x16x32_bf16 v[6:9], v[166:169], v[214:217], v[6:9]
	v_mfma_f32_16x16x32_bf16 v[2:5], v[174:177], v[214:217], v[2:5]
	s_setprio 0
	s_barrier
	s_add_u32 s18, s18, 0x100
	s_addc_u32 s19, s19, 0
	s_add_u32 s71, s71, 0x100
	s_addc_u32 s72, s72, 0
	s_cmp_ge_i32 s73, s10
	s_mov_b32 s20, s73
	s_cbranch_scc1 .LBB0_493
.LBB0_492:
	s_add_i32 s73, s20, 2
	s_add_u32 s31, s18, 0x80
	s_addc_u32 s21, s19, 0
	s_add_i32 s74, 0, 0x10000
	s_cmp_eq_u32 s11, s20
	s_cselect_b32 s21, s3, s21
	s_cselect_b32 s20, s2, s31
	s_cselect_b32 s63, s17, s72
	s_cselect_b32 s62, s16, s71
	s_add_i32 s31, 0, 0x14000
	v_lshl_add_u64 v[218:219], s[18:19], 0, v[138:139]
	s_add_i32 m0, s23, 0xc000
	s_nop 0
	global_load_lds_dwordx4 v[218:219], off
	v_lshl_add_u64 v[218:219], s[18:19], 0, v[140:141]
	s_add_i32 m0, s23, 0xe000
	s_nop 0
	global_load_lds_dwordx4 v[218:219], off
	v_add_u32_e32 v145, s74, v142
	ds_read_b128 v[146:149], v145
	ds_read_b128 v[150:153], v145 offset:1024
	ds_read_b128 v[154:157], v145 offset:2048
	ds_read_b128 v[158:161], v145 offset:3072
	v_add_u32_e32 v145, s31, v142
	ds_read_b128 v[162:165], v145
	ds_read_b128 v[166:169], v145 offset:1024
	ds_read_b128 v[170:173], v145 offset:2048
	ds_read_b128 v[174:177], v145 offset:3072
	ds_read_b128 v[178:181], v144
	ds_read_b128 v[182:185], v144 offset:1024
	ds_read_b128 v[186:189], v144 offset:2048
	ds_read_b128 v[190:193], v144 offset:3072
	ds_read_b128 v[194:197], v144 offset:4096
	ds_read_b128 v[198:201], v144 offset:5120
	ds_read_b128 v[202:205], v144 offset:6144
	ds_read_b128 v[214:217], v144 offset:7168
	s_waitcnt lgkmcnt(0)
	s_waitcnt vmcnt(8)
	s_barrier
	s_setprio 1
	s_waitcnt lgkmcnt(0)
	v_mfma_f32_16x16x32_bf16 v[122:125], v[146:149], v[178:181], v[122:125]
	v_mfma_f32_16x16x32_bf16 v[126:129], v[154:157], v[178:181], v[126:129]
	v_mfma_f32_16x16x32_bf16 v[118:121], v[146:149], v[186:189], v[118:121]
	v_mfma_f32_16x16x32_bf16 v[114:117], v[154:157], v[186:189], v[114:117]
	v_mfma_f32_16x16x32_bf16 v[110:113], v[146:149], v[194:197], v[110:113]
	v_mfma_f32_16x16x32_bf16 v[106:109], v[154:157], v[194:197], v[106:109]
	v_mfma_f32_16x16x32_bf16 v[102:105], v[146:149], v[202:205], v[102:105]
	v_mfma_f32_16x16x32_bf16 v[98:101], v[154:157], v[202:205], v[98:101]
	v_mfma_f32_16x16x32_bf16 v[122:125], v[150:153], v[182:185], v[122:125]
	v_mfma_f32_16x16x32_bf16 v[126:129], v[158:161], v[182:185], v[126:129]
	v_mfma_f32_16x16x32_bf16 v[118:121], v[150:153], v[190:193], v[118:121]
	v_mfma_f32_16x16x32_bf16 v[114:117], v[158:161], v[190:193], v[114:117]
	v_mfma_f32_16x16x32_bf16 v[110:113], v[150:153], v[198:201], v[110:113]
	v_mfma_f32_16x16x32_bf16 v[106:109], v[158:161], v[198:201], v[106:109]
	v_mfma_f32_16x16x32_bf16 v[102:105], v[150:153], v[214:217], v[102:105]
	v_mfma_f32_16x16x32_bf16 v[98:101], v[158:161], v[214:217], v[98:101]
	s_setprio 0
	s_setprio 1
	v_mfma_f32_16x16x32_bf16 v[62:65], v[162:165], v[178:181], v[62:65]
	v_mfma_f32_16x16x32_bf16 v[58:61], v[170:173], v[178:181], v[58:61]
	v_mfma_f32_16x16x32_bf16 v[54:57], v[162:165], v[186:189], v[54:57]
	v_mfma_f32_16x16x32_bf16 v[50:53], v[170:173], v[186:189], v[50:53]
	v_mfma_f32_16x16x32_bf16 v[46:49], v[162:165], v[194:197], v[46:49]
	v_mfma_f32_16x16x32_bf16 v[42:45], v[170:173], v[194:197], v[42:45]
	v_mfma_f32_16x16x32_bf16 v[38:41], v[162:165], v[202:205], v[38:41]
	v_mfma_f32_16x16x32_bf16 v[34:37], v[170:173], v[202:205], v[34:37]
	v_mfma_f32_16x16x32_bf16 v[62:65], v[166:169], v[182:185], v[62:65]
	v_mfma_f32_16x16x32_bf16 v[58:61], v[174:177], v[182:185], v[58:61]
	v_mfma_f32_16x16x32_bf16 v[54:57], v[166:169], v[190:193], v[54:57]
	v_mfma_f32_16x16x32_bf16 v[50:53], v[174:177], v[190:193], v[50:53]
	v_mfma_f32_16x16x32_bf16 v[46:49], v[166:169], v[198:201], v[46:49]
	v_mfma_f32_16x16x32_bf16 v[42:45], v[174:177], v[198:201], v[42:45]
	v_mfma_f32_16x16x32_bf16 v[38:41], v[166:169], v[214:217], v[38:41]
	v_mfma_f32_16x16x32_bf16 v[34:37], v[174:177], v[214:217], v[34:37]
	s_setprio 0
	s_barrier
	s_add_i32 s74, s74, s22
	v_lshl_add_u64 v[218:219], s[62:63], 0, v[134:135]
	s_mov_b32 m0, s74
	s_nop 0
	global_load_lds_dwordx4 v[218:219], off
	s_add_i32 m0, s74, 0x2000
	v_lshl_add_u64 v[220:221], s[62:63], 0, v[130:131]
	s_add_u32 s62, s62, s4
	s_addc_u32 s63, s63, s5
	s_add_i32 s31, s31, s22
	global_load_lds_dwordx4 v[220:221], off
	v_lshl_add_u64 v[222:223], s[62:63], 0, v[134:135]
	s_mov_b32 m0, s31
	v_lshl_add_u64 v[224:225], s[62:63], 0, v[130:131]
	global_load_lds_dwordx4 v[222:223], off
	s_add_i32 m0, s31, 0x2000
	v_lshl_add_u64 v[226:227], s[20:21], 0, v[136:137]
	global_load_lds_dwordx4 v[224:225], off
	s_mov_b32 m0, s23
	v_lshl_add_u64 v[236:237], s[20:21], 0, v[132:133]
	global_load_lds_dwordx4 v[226:227], off
	s_mov_b32 m0, s52
	s_nop 0
	global_load_lds_dwordx4 v[236:237], off
	ds_read_b128 v[178:181], v144 offset:16384
	ds_read_b128 v[182:185], v144 offset:17408
	ds_read_b128 v[186:189], v144 offset:18432
	ds_read_b128 v[190:193], v144 offset:19456
	ds_read_b128 v[194:197], v144 offset:20480
	ds_read_b128 v[198:201], v144 offset:21504
	ds_read_b128 v[202:205], v144 offset:22528
	ds_read_b128 v[214:217], v144 offset:23552
	s_waitcnt lgkmcnt(0)
	s_waitcnt vmcnt(8)
	s_barrier
	s_setprio 1
	s_waitcnt lgkmcnt(0)
	v_mfma_f32_16x16x32_bf16 v[94:97], v[146:149], v[178:181], v[94:97]
	v_mfma_f32_16x16x32_bf16 v[90:93], v[154:157], v[178:181], v[90:93]
	v_mfma_f32_16x16x32_bf16 v[86:89], v[146:149], v[186:189], v[86:89]
	v_mfma_f32_16x16x32_bf16 v[82:85], v[154:157], v[186:189], v[82:85]
	v_mfma_f32_16x16x32_bf16 v[78:81], v[146:149], v[194:197], v[78:81]
	v_mfma_f32_16x16x32_bf16 v[74:77], v[154:157], v[194:197], v[74:77]
	v_mfma_f32_16x16x32_bf16 v[70:73], v[146:149], v[202:205], v[70:73]
	v_mfma_f32_16x16x32_bf16 v[66:69], v[154:157], v[202:205], v[66:69]
	v_mfma_f32_16x16x32_bf16 v[94:97], v[150:153], v[182:185], v[94:97]
	v_mfma_f32_16x16x32_bf16 v[90:93], v[158:161], v[182:185], v[90:93]
	v_mfma_f32_16x16x32_bf16 v[86:89], v[150:153], v[190:193], v[86:89]
	v_mfma_f32_16x16x32_bf16 v[82:85], v[158:161], v[190:193], v[82:85]
	v_mfma_f32_16x16x32_bf16 v[78:81], v[150:153], v[198:201], v[78:81]
	v_mfma_f32_16x16x32_bf16 v[74:77], v[158:161], v[198:201], v[74:77]
	v_mfma_f32_16x16x32_bf16 v[70:73], v[150:153], v[214:217], v[70:73]
	v_mfma_f32_16x16x32_bf16 v[66:69], v[158:161], v[214:217], v[66:69]
	s_setprio 0
	s_setprio 1
	v_mfma_f32_16x16x32_bf16 v[30:33], v[162:165], v[178:181], v[30:33]
	v_mfma_f32_16x16x32_bf16 v[26:29], v[170:173], v[178:181], v[26:29]
	v_mfma_f32_16x16x32_bf16 v[22:25], v[162:165], v[186:189], v[22:25]
	v_mfma_f32_16x16x32_bf16 v[18:21], v[170:173], v[186:189], v[18:21]
	v_mfma_f32_16x16x32_bf16 v[14:17], v[162:165], v[194:197], v[14:17]
	v_mfma_f32_16x16x32_bf16 v[10:13], v[170:173], v[194:197], v[10:13]
	v_mfma_f32_16x16x32_bf16 v[6:9], v[162:165], v[202:205], v[6:9]
	v_mfma_f32_16x16x32_bf16 v[2:5], v[170:173], v[202:205], v[2:5]
	v_mfma_f32_16x16x32_bf16 v[30:33], v[166:169], v[182:185], v[30:33]
	v_mfma_f32_16x16x32_bf16 v[26:29], v[174:177], v[182:185], v[26:29]
	v_mfma_f32_16x16x32_bf16 v[22:25], v[166:169], v[190:193], v[22:25]
	v_mfma_f32_16x16x32_bf16 v[18:21], v[174:177], v[190:193], v[18:21]
	v_mfma_f32_16x16x32_bf16 v[14:17], v[166:169], v[198:201], v[14:17]
	v_mfma_f32_16x16x32_bf16 v[10:13], v[174:177], v[198:201], v[10:13]
	v_mfma_f32_16x16x32_bf16 v[6:9], v[166:169], v[214:217], v[6:9]
	v_mfma_f32_16x16x32_bf16 v[2:5], v[174:177], v[214:217], v[2:5]
	s_setprio 0
	s_barrier
	s_add_i32 s31, 0, 0x18000
	s_add_i32 s62, 0, 0x1c000
	s_add_u32 s20, s20, s4
	s_addc_u32 s21, s21, s5
	s_mov_b32 m0, s53
	v_lshl_add_u64 v[238:239], s[20:21], 0, v[136:137]
	global_load_lds_dwordx4 v[238:239], off
	v_lshl_add_u64 v[238:239], s[20:21], 0, v[132:133]
	s_mov_b32 m0, s56
	s_nop 0
	global_load_lds_dwordx4 v[238:239], off
	v_add_u32_e32 v145, s31, v142
	ds_read_b128 v[146:149], v145
	ds_read_b128 v[150:153], v145 offset:1024
	ds_read_b128 v[154:157], v145 offset:2048
	ds_read_b128 v[158:161], v145 offset:3072
	v_add_u32_e32 v145, s62, v142
	ds_read_b128 v[162:165], v145
	ds_read_b128 v[166:169], v145 offset:1024
	ds_read_b128 v[170:173], v145 offset:2048
	ds_read_b128 v[174:177], v145 offset:3072
	ds_read_b128 v[178:181], v144 offset:32768
	ds_read_b128 v[182:185], v144 offset:33792
	ds_read_b128 v[186:189], v144 offset:34816
	ds_read_b128 v[190:193], v144 offset:35840
	ds_read_b128 v[194:197], v144 offset:36864
	ds_read_b128 v[198:201], v144 offset:37888
	ds_read_b128 v[202:205], v144 offset:38912
	ds_read_b128 v[214:217], v144 offset:39936
	s_waitcnt lgkmcnt(0)
	s_waitcnt vmcnt(8)
	s_barrier
	s_setprio 1
	s_waitcnt lgkmcnt(0)
	v_mfma_f32_16x16x32_bf16 v[122:125], v[146:149], v[178:181], v[122:125]
	v_mfma_f32_16x16x32_bf16 v[126:129], v[154:157], v[178:181], v[126:129]
	v_mfma_f32_16x16x32_bf16 v[118:121], v[146:149], v[186:189], v[118:121]
	v_mfma_f32_16x16x32_bf16 v[114:117], v[154:157], v[186:189], v[114:117]
	v_mfma_f32_16x16x32_bf16 v[110:113], v[146:149], v[194:197], v[110:113]
	v_mfma_f32_16x16x32_bf16 v[106:109], v[154:157], v[194:197], v[106:109]
	v_mfma_f32_16x16x32_bf16 v[102:105], v[146:149], v[202:205], v[102:105]
	v_mfma_f32_16x16x32_bf16 v[98:101], v[154:157], v[202:205], v[98:101]
	v_mfma_f32_16x16x32_bf16 v[122:125], v[150:153], v[182:185], v[122:125]
	v_mfma_f32_16x16x32_bf16 v[126:129], v[158:161], v[182:185], v[126:129]
	v_mfma_f32_16x16x32_bf16 v[118:121], v[150:153], v[190:193], v[118:121]
	v_mfma_f32_16x16x32_bf16 v[114:117], v[158:161], v[190:193], v[114:117]
	v_mfma_f32_16x16x32_bf16 v[110:113], v[150:153], v[198:201], v[110:113]
	v_mfma_f32_16x16x32_bf16 v[106:109], v[158:161], v[198:201], v[106:109]
	v_mfma_f32_16x16x32_bf16 v[102:105], v[150:153], v[214:217], v[102:105]
	v_mfma_f32_16x16x32_bf16 v[98:101], v[158:161], v[214:217], v[98:101]
	s_setprio 0
	s_setprio 1
	v_mfma_f32_16x16x32_bf16 v[62:65], v[162:165], v[178:181], v[62:65]
	v_mfma_f32_16x16x32_bf16 v[58:61], v[170:173], v[178:181], v[58:61]
	v_mfma_f32_16x16x32_bf16 v[54:57], v[162:165], v[186:189], v[54:57]
	v_mfma_f32_16x16x32_bf16 v[50:53], v[170:173], v[186:189], v[50:53]
	v_mfma_f32_16x16x32_bf16 v[46:49], v[162:165], v[194:197], v[46:49]
	v_mfma_f32_16x16x32_bf16 v[42:45], v[170:173], v[194:197], v[42:45]
	v_mfma_f32_16x16x32_bf16 v[38:41], v[162:165], v[202:205], v[38:41]
	v_mfma_f32_16x16x32_bf16 v[34:37], v[170:173], v[202:205], v[34:37]
	v_mfma_f32_16x16x32_bf16 v[62:65], v[166:169], v[182:185], v[62:65]
	v_mfma_f32_16x16x32_bf16 v[58:61], v[174:177], v[182:185], v[58:61]
	v_mfma_f32_16x16x32_bf16 v[54:57], v[166:169], v[190:193], v[54:57]
	v_mfma_f32_16x16x32_bf16 v[50:53], v[174:177], v[190:193], v[50:53]
	v_mfma_f32_16x16x32_bf16 v[46:49], v[166:169], v[198:201], v[46:49]
	v_mfma_f32_16x16x32_bf16 v[42:45], v[174:177], v[198:201], v[42:45]
	v_mfma_f32_16x16x32_bf16 v[38:41], v[166:169], v[214:217], v[38:41]
	v_mfma_f32_16x16x32_bf16 v[34:37], v[174:177], v[214:217], v[34:37]
	s_setprio 0
	s_barrier
	s_add_i32 s20, s31, s22
	v_lshl_add_u64 v[218:219], v[218:219], 0, s[60:61]
	s_mov_b32 m0, s20
	s_nop 0
	global_load_lds_dwordx4 v[218:219], off
	v_lshl_add_u64 v[218:219], v[220:221], 0, s[60:61]
	s_add_i32 m0, s20, 0x2000
	s_add_i32 s20, s62, s22
	global_load_lds_dwordx4 v[218:219], off
	v_lshl_add_u64 v[218:219], v[222:223], 0, s[60:61]
	s_mov_b32 m0, s20
	s_nop 0
	global_load_lds_dwordx4 v[218:219], off
	v_lshl_add_u64 v[218:219], v[224:225], 0, s[60:61]
	s_add_i32 m0, s20, 0x2000
	s_nop 0
	global_load_lds_dwordx4 v[218:219], off
	v_lshl_add_u64 v[218:219], v[226:227], 0, s[60:61]
	s_mov_b32 m0, s57
	s_nop 0
	global_load_lds_dwordx4 v[218:219], off
	v_lshl_add_u64 v[218:219], v[236:237], 0, s[60:61]
	s_mov_b32 m0, s65
	s_nop 0
	global_load_lds_dwordx4 v[218:219], off
	ds_read_b128 v[178:181], v144 offset:49152
	ds_read_b128 v[182:185], v144 offset:50176
	ds_read_b128 v[186:189], v144 offset:51200
	ds_read_b128 v[190:193], v144 offset:52224
	ds_read_b128 v[194:197], v144 offset:53248
	ds_read_b128 v[198:201], v144 offset:54272
	ds_read_b128 v[202:205], v144 offset:55296
	ds_read_b128 v[214:217], v144 offset:56320
	s_waitcnt lgkmcnt(0)
	s_waitcnt vmcnt(8)
	s_barrier
	s_setprio 1
	s_waitcnt lgkmcnt(0)
	v_mfma_f32_16x16x32_bf16 v[94:97], v[146:149], v[178:181], v[94:97]
	v_mfma_f32_16x16x32_bf16 v[90:93], v[154:157], v[178:181], v[90:93]
	v_mfma_f32_16x16x32_bf16 v[86:89], v[146:149], v[186:189], v[86:89]
	v_mfma_f32_16x16x32_bf16 v[82:85], v[154:157], v[186:189], v[82:85]
	v_mfma_f32_16x16x32_bf16 v[78:81], v[146:149], v[194:197], v[78:81]
	v_mfma_f32_16x16x32_bf16 v[74:77], v[154:157], v[194:197], v[74:77]
	v_mfma_f32_16x16x32_bf16 v[70:73], v[146:149], v[202:205], v[70:73]
	v_mfma_f32_16x16x32_bf16 v[66:69], v[154:157], v[202:205], v[66:69]
	v_mfma_f32_16x16x32_bf16 v[94:97], v[150:153], v[182:185], v[94:97]
	v_mfma_f32_16x16x32_bf16 v[90:93], v[158:161], v[182:185], v[90:93]
	v_mfma_f32_16x16x32_bf16 v[86:89], v[150:153], v[190:193], v[86:89]
	v_mfma_f32_16x16x32_bf16 v[82:85], v[158:161], v[190:193], v[82:85]
	v_mfma_f32_16x16x32_bf16 v[78:81], v[150:153], v[198:201], v[78:81]
	v_mfma_f32_16x16x32_bf16 v[74:77], v[158:161], v[198:201], v[74:77]
	v_mfma_f32_16x16x32_bf16 v[70:73], v[150:153], v[214:217], v[70:73]
	v_mfma_f32_16x16x32_bf16 v[66:69], v[158:161], v[214:217], v[66:69]
	s_setprio 0
	s_setprio 1
	v_mfma_f32_16x16x32_bf16 v[30:33], v[162:165], v[178:181], v[30:33]
	v_mfma_f32_16x16x32_bf16 v[26:29], v[170:173], v[178:181], v[26:29]
	v_mfma_f32_16x16x32_bf16 v[22:25], v[162:165], v[186:189], v[22:25]
	v_mfma_f32_16x16x32_bf16 v[18:21], v[170:173], v[186:189], v[18:21]
	v_mfma_f32_16x16x32_bf16 v[14:17], v[162:165], v[194:197], v[14:17]
	v_mfma_f32_16x16x32_bf16 v[10:13], v[170:173], v[194:197], v[10:13]
	v_mfma_f32_16x16x32_bf16 v[6:9], v[162:165], v[202:205], v[6:9]
	v_mfma_f32_16x16x32_bf16 v[2:5], v[170:173], v[202:205], v[2:5]
	v_mfma_f32_16x16x32_bf16 v[30:33], v[166:169], v[182:185], v[30:33]
	v_mfma_f32_16x16x32_bf16 v[26:29], v[174:177], v[182:185], v[26:29]
	v_mfma_f32_16x16x32_bf16 v[22:25], v[166:169], v[190:193], v[22:25]
	v_mfma_f32_16x16x32_bf16 v[18:21], v[174:177], v[190:193], v[18:21]
	v_mfma_f32_16x16x32_bf16 v[14:17], v[166:169], v[198:201], v[14:17]
	v_mfma_f32_16x16x32_bf16 v[10:13], v[174:177], v[198:201], v[10:13]
	v_mfma_f32_16x16x32_bf16 v[6:9], v[166:169], v[214:217], v[6:9]
	v_mfma_f32_16x16x32_bf16 v[2:5], v[174:177], v[214:217], v[2:5]
	s_setprio 0
	s_barrier
	s_add_u32 s18, s18, 0x100
	s_addc_u32 s19, s19, 0
	s_add_u32 s71, s71, 0x100
	s_addc_u32 s72, s72, 0
	s_cmp_ge_i32 s73, s10
	s_mov_b32 s20, s73
	s_cbranch_scc0 .LBB0_492

.Lzgo_5:
	s_add_u32 s18, s18, 0x80
	s_addc_u32 s19, s19, 0
	s_add_u32 s71, s20, 0x100
	s_addc_u32 s72, s21, 0
	s_mov_b32 s20, 0
	s_add_i32 s73, s20, 2
	s_add_u32 s31, s18, 0x80
	s_addc_u32 s21, s19, 0
	s_add_i32 s74, 0, 0x10000
	s_cmp_eq_u32 s67, s20
	s_cselect_b32 s21, s3, s21
	s_cselect_b32 s20, s2, s31
	s_cselect_b32 s63, s17, s72
	s_cselect_b32 s62, s16, s71
	s_add_i32 s31, 0, 0x14000
	v_lshl_add_u64 v[214:215], s[18:19], 0, v[138:139]
	s_add_i32 m0, s23, 0xc000
	s_nop 0
	global_load_lds_dwordx4 v[214:215], off
	v_lshl_add_u64 v[214:215], s[18:19], 0, v[140:141]
	s_add_i32 m0, s23, 0xe000
	s_nop 0
	global_load_lds_dwordx4 v[214:215], off
	v_add_u32_e32 v149, s74, v146
	ds_read_b128 v[130:133], v149
	ds_read_b128 v[142:145], v149 offset:1024
	ds_read_b128 v[150:153], v149 offset:2048
	ds_read_b128 v[154:157], v149 offset:3072
	v_add_u32_e32 v149, s31, v146
	ds_read_b128 v[158:161], v149
	ds_read_b128 v[162:165], v149 offset:1024
	ds_read_b128 v[166:169], v149 offset:2048
	ds_read_b128 v[170:173], v149 offset:3072
	ds_read_b128 v[174:177], v148
	ds_read_b128 v[178:181], v148 offset:1024
	ds_read_b128 v[182:185], v148 offset:2048
	ds_read_b128 v[186:189], v148 offset:3072
	ds_read_b128 v[190:193], v148 offset:4096
	ds_read_b128 v[194:197], v148 offset:5120
	ds_read_b128 v[198:201], v148 offset:6144
	ds_read_b128 v[202:205], v148 offset:7168
	s_waitcnt lgkmcnt(0)
	s_waitcnt vmcnt(8)
	s_barrier
	s_setprio 1
	s_waitcnt lgkmcnt(0)
	v_mfma_f32_16x16x32_bf16 v[126:129], v[130:133], v[174:177], 0
	v_mfma_f32_16x16x32_bf16 v[94:97], v[150:153], v[174:177], 0
	v_mfma_f32_16x16x32_bf16 v[122:125], v[130:133], v[182:185], 0
	v_mfma_f32_16x16x32_bf16 v[90:93], v[150:153], v[182:185], 0
	v_mfma_f32_16x16x32_bf16 v[118:121], v[130:133], v[190:193], 0
	v_mfma_f32_16x16x32_bf16 v[86:89], v[150:153], v[190:193], 0
	v_mfma_f32_16x16x32_bf16 v[114:117], v[130:133], v[198:201], 0
	v_mfma_f32_16x16x32_bf16 v[82:85], v[150:153], v[198:201], 0
	v_mfma_f32_16x16x32_bf16 v[126:129], v[142:145], v[178:181], v[126:129]
	v_mfma_f32_16x16x32_bf16 v[94:97], v[154:157], v[178:181], v[94:97]
	v_mfma_f32_16x16x32_bf16 v[122:125], v[142:145], v[186:189], v[122:125]
	v_mfma_f32_16x16x32_bf16 v[90:93], v[154:157], v[186:189], v[90:93]
	v_mfma_f32_16x16x32_bf16 v[118:121], v[142:145], v[194:197], v[118:121]
	v_mfma_f32_16x16x32_bf16 v[86:89], v[154:157], v[194:197], v[86:89]
	v_mfma_f32_16x16x32_bf16 v[114:117], v[142:145], v[202:205], v[114:117]
	v_mfma_f32_16x16x32_bf16 v[82:85], v[154:157], v[202:205], v[82:85]
	s_setprio 0
	s_setprio 1
	v_mfma_f32_16x16x32_bf16 v[62:65], v[158:161], v[174:177], 0
	v_mfma_f32_16x16x32_bf16 v[30:33], v[166:169], v[174:177], 0
	v_mfma_f32_16x16x32_bf16 v[58:61], v[158:161], v[182:185], 0
	v_mfma_f32_16x16x32_bf16 v[26:29], v[166:169], v[182:185], 0
	v_mfma_f32_16x16x32_bf16 v[54:57], v[158:161], v[190:193], 0
	v_mfma_f32_16x16x32_bf16 v[22:25], v[166:169], v[190:193], 0
	v_mfma_f32_16x16x32_bf16 v[50:53], v[158:161], v[198:201], 0
	v_mfma_f32_16x16x32_bf16 v[18:21], v[166:169], v[198:201], 0
	v_mfma_f32_16x16x32_bf16 v[62:65], v[162:165], v[178:181], v[62:65]
	v_mfma_f32_16x16x32_bf16 v[30:33], v[170:173], v[178:181], v[30:33]
	v_mfma_f32_16x16x32_bf16 v[58:61], v[162:165], v[186:189], v[58:61]
	v_mfma_f32_16x16x32_bf16 v[26:29], v[170:173], v[186:189], v[26:29]
	v_mfma_f32_16x16x32_bf16 v[54:57], v[162:165], v[194:197], v[54:57]
	v_mfma_f32_16x16x32_bf16 v[22:25], v[170:173], v[194:197], v[22:25]
	v_mfma_f32_16x16x32_bf16 v[50:53], v[162:165], v[202:205], v[50:53]
	v_mfma_f32_16x16x32_bf16 v[18:21], v[170:173], v[202:205], v[18:21]
	s_setprio 0
	s_barrier
	s_add_i32 s74, s74, s22
	v_lshl_add_u64 v[214:215], s[62:63], 0, v[136:137]
	s_mov_b32 m0, s74
	s_nop 0
	global_load_lds_dwordx4 v[214:215], off
	s_add_i32 m0, s74, 0x2000
	v_lshl_add_u64 v[216:217], s[62:63], 0, v[134:135]
	s_add_u32 s62, s62, s4
	s_addc_u32 s63, s63, s5
	s_add_i32 s31, s31, s22
	global_load_lds_dwordx4 v[216:217], off
	v_lshl_add_u64 v[218:219], s[62:63], 0, v[136:137]
	s_mov_b32 m0, s31
	v_lshl_add_u64 v[220:221], s[62:63], 0, v[134:135]
	global_load_lds_dwordx4 v[218:219], off
	s_add_i32 m0, s31, 0x2000
	v_lshl_add_u64 v[222:223], s[20:21], 0, v[136:137]
	global_load_lds_dwordx4 v[220:221], off
	s_mov_b32 m0, s23
	v_lshl_add_u64 v[224:225], s[20:21], 0, v[134:135]
	global_load_lds_dwordx4 v[222:223], off
	s_mov_b32 m0, s52
	s_nop 0
	global_load_lds_dwordx4 v[224:225], off
	ds_read_b128 v[174:177], v148 offset:16384
	ds_read_b128 v[178:181], v148 offset:17408
	ds_read_b128 v[182:185], v148 offset:18432
	ds_read_b128 v[186:189], v148 offset:19456
	ds_read_b128 v[190:193], v148 offset:20480
	ds_read_b128 v[194:197], v148 offset:21504
	ds_read_b128 v[198:201], v148 offset:22528
	ds_read_b128 v[202:205], v148 offset:23552
	s_waitcnt lgkmcnt(0)
	s_waitcnt vmcnt(8)
	s_barrier
	s_setprio 1
	s_waitcnt lgkmcnt(0)
	v_mfma_f32_16x16x32_bf16 v[110:113], v[130:133], v[174:177], 0
	v_mfma_f32_16x16x32_bf16 v[78:81], v[150:153], v[174:177], 0
	v_mfma_f32_16x16x32_bf16 v[106:109], v[130:133], v[182:185], 0
	v_mfma_f32_16x16x32_bf16 v[74:77], v[150:153], v[182:185], 0
	v_mfma_f32_16x16x32_bf16 v[102:105], v[130:133], v[190:193], 0
	v_mfma_f32_16x16x32_bf16 v[70:73], v[150:153], v[190:193], 0
	v_mfma_f32_16x16x32_bf16 v[98:101], v[130:133], v[198:201], 0
	v_mfma_f32_16x16x32_bf16 v[66:69], v[150:153], v[198:201], 0
	v_mfma_f32_16x16x32_bf16 v[110:113], v[142:145], v[178:181], v[110:113]
	v_mfma_f32_16x16x32_bf16 v[78:81], v[154:157], v[178:181], v[78:81]
	v_mfma_f32_16x16x32_bf16 v[106:109], v[142:145], v[186:189], v[106:109]
	v_mfma_f32_16x16x32_bf16 v[74:77], v[154:157], v[186:189], v[74:77]
	v_mfma_f32_16x16x32_bf16 v[102:105], v[142:145], v[194:197], v[102:105]
	v_mfma_f32_16x16x32_bf16 v[70:73], v[154:157], v[194:197], v[70:73]
	v_mfma_f32_16x16x32_bf16 v[98:101], v[142:145], v[202:205], v[98:101]
	v_mfma_f32_16x16x32_bf16 v[66:69], v[154:157], v[202:205], v[66:69]
	s_setprio 0
	s_setprio 1
	v_mfma_f32_16x16x32_bf16 v[46:49], v[158:161], v[174:177], 0
	v_mfma_f32_16x16x32_bf16 v[14:17], v[166:169], v[174:177], 0
	v_mfma_f32_16x16x32_bf16 v[42:45], v[158:161], v[182:185], 0
	v_mfma_f32_16x16x32_bf16 v[10:13], v[166:169], v[182:185], 0
	v_mfma_f32_16x16x32_bf16 v[38:41], v[158:161], v[190:193], 0
	v_mfma_f32_16x16x32_bf16 v[6:9], v[166:169], v[190:193], 0
	v_mfma_f32_16x16x32_bf16 v[34:37], v[158:161], v[198:201], 0
	v_mfma_f32_16x16x32_bf16 v[2:5], v[166:169], v[198:201], 0
	v_mfma_f32_16x16x32_bf16 v[46:49], v[162:165], v[178:181], v[46:49]
	v_mfma_f32_16x16x32_bf16 v[14:17], v[170:173], v[178:181], v[14:17]
	v_mfma_f32_16x16x32_bf16 v[42:45], v[162:165], v[186:189], v[42:45]
	v_mfma_f32_16x16x32_bf16 v[10:13], v[170:173], v[186:189], v[10:13]
	v_mfma_f32_16x16x32_bf16 v[38:41], v[162:165], v[194:197], v[38:41]
	v_mfma_f32_16x16x32_bf16 v[6:9], v[170:173], v[194:197], v[6:9]
	v_mfma_f32_16x16x32_bf16 v[34:37], v[162:165], v[202:205], v[34:37]
	v_mfma_f32_16x16x32_bf16 v[2:5], v[170:173], v[202:205], v[2:5]
	s_setprio 0
	s_barrier
	s_add_i32 s31, 0, 0x18000
	s_add_i32 s62, 0, 0x1c000
	s_add_u32 s20, s20, s4
	s_addc_u32 s21, s21, s5
	s_mov_b32 m0, s53
	v_lshl_add_u64 v[226:227], s[20:21], 0, v[136:137]
	global_load_lds_dwordx4 v[226:227], off
	v_lshl_add_u64 v[226:227], s[20:21], 0, v[134:135]
	s_mov_b32 m0, s56
	s_nop 0
	global_load_lds_dwordx4 v[226:227], off
	v_add_u32_e32 v149, s31, v146
	ds_read_b128 v[130:133], v149
	ds_read_b128 v[142:145], v149 offset:1024
	ds_read_b128 v[150:153], v149 offset:2048
	ds_read_b128 v[154:157], v149 offset:3072
	v_add_u32_e32 v149, s62, v146
	ds_read_b128 v[158:161], v149
	ds_read_b128 v[162:165], v149 offset:1024
	ds_read_b128 v[166:169], v149 offset:2048
	ds_read_b128 v[170:173], v149 offset:3072
	ds_read_b128 v[174:177], v148 offset:32768
	ds_read_b128 v[178:181], v148 offset:33792
	ds_read_b128 v[182:185], v148 offset:34816
	ds_read_b128 v[186:189], v148 offset:35840
	ds_read_b128 v[190:193], v148 offset:36864
	ds_read_b128 v[194:197], v148 offset:37888
	ds_read_b128 v[198:201], v148 offset:38912
	ds_read_b128 v[202:205], v148 offset:39936
	s_waitcnt lgkmcnt(0)
	s_waitcnt vmcnt(8)
	s_barrier
	s_setprio 1
	s_waitcnt lgkmcnt(0)
	v_mfma_f32_16x16x32_bf16 v[126:129], v[130:133], v[174:177], v[126:129]
	v_mfma_f32_16x16x32_bf16 v[94:97], v[150:153], v[174:177], v[94:97]
	v_mfma_f32_16x16x32_bf16 v[122:125], v[130:133], v[182:185], v[122:125]
	v_mfma_f32_16x16x32_bf16 v[90:93], v[150:153], v[182:185], v[90:93]
	v_mfma_f32_16x16x32_bf16 v[118:121], v[130:133], v[190:193], v[118:121]
	v_mfma_f32_16x16x32_bf16 v[86:89], v[150:153], v[190:193], v[86:89]
	v_mfma_f32_16x16x32_bf16 v[114:117], v[130:133], v[198:201], v[114:117]
	v_mfma_f32_16x16x32_bf16 v[82:85], v[150:153], v[198:201], v[82:85]
	v_mfma_f32_16x16x32_bf16 v[126:129], v[142:145], v[178:181], v[126:129]
	v_mfma_f32_16x16x32_bf16 v[94:97], v[154:157], v[178:181], v[94:97]
	v_mfma_f32_16x16x32_bf16 v[122:125], v[142:145], v[186:189], v[122:125]
	v_mfma_f32_16x16x32_bf16 v[90:93], v[154:157], v[186:189], v[90:93]
	v_mfma_f32_16x16x32_bf16 v[118:121], v[142:145], v[194:197], v[118:121]
	v_mfma_f32_16x16x32_bf16 v[86:89], v[154:157], v[194:197], v[86:89]
	v_mfma_f32_16x16x32_bf16 v[114:117], v[142:145], v[202:205], v[114:117]
	v_mfma_f32_16x16x32_bf16 v[82:85], v[154:157], v[202:205], v[82:85]
	s_setprio 0
	s_setprio 1
	v_mfma_f32_16x16x32_bf16 v[62:65], v[158:161], v[174:177], v[62:65]
	v_mfma_f32_16x16x32_bf16 v[30:33], v[166:169], v[174:177], v[30:33]
	v_mfma_f32_16x16x32_bf16 v[58:61], v[158:161], v[182:185], v[58:61]
	v_mfma_f32_16x16x32_bf16 v[26:29], v[166:169], v[182:185], v[26:29]
	v_mfma_f32_16x16x32_bf16 v[54:57], v[158:161], v[190:193], v[54:57]
	v_mfma_f32_16x16x32_bf16 v[22:25], v[166:169], v[190:193], v[22:25]
	v_mfma_f32_16x16x32_bf16 v[50:53], v[158:161], v[198:201], v[50:53]
	v_mfma_f32_16x16x32_bf16 v[18:21], v[166:169], v[198:201], v[18:21]
	v_mfma_f32_16x16x32_bf16 v[62:65], v[162:165], v[178:181], v[62:65]
	v_mfma_f32_16x16x32_bf16 v[30:33], v[170:173], v[178:181], v[30:33]
	v_mfma_f32_16x16x32_bf16 v[58:61], v[162:165], v[186:189], v[58:61]
	v_mfma_f32_16x16x32_bf16 v[26:29], v[170:173], v[186:189], v[26:29]
	v_mfma_f32_16x16x32_bf16 v[54:57], v[162:165], v[194:197], v[54:57]
	v_mfma_f32_16x16x32_bf16 v[22:25], v[170:173], v[194:197], v[22:25]
	v_mfma_f32_16x16x32_bf16 v[50:53], v[162:165], v[202:205], v[50:53]
	v_mfma_f32_16x16x32_bf16 v[18:21], v[170:173], v[202:205], v[18:21]
	s_setprio 0
	s_barrier
	s_add_i32 s20, s31, s22
	v_lshl_add_u64 v[214:215], v[214:215], 0, s[60:61]
	s_mov_b32 m0, s20
	s_nop 0
	global_load_lds_dwordx4 v[214:215], off
	v_lshl_add_u64 v[214:215], v[216:217], 0, s[60:61]
	s_add_i32 m0, s20, 0x2000
	s_add_i32 s20, s62, s22
	global_load_lds_dwordx4 v[214:215], off
	v_lshl_add_u64 v[214:215], v[218:219], 0, s[60:61]
	s_mov_b32 m0, s20
	s_nop 0
	global_load_lds_dwordx4 v[214:215], off
	v_lshl_add_u64 v[214:215], v[220:221], 0, s[60:61]
	s_add_i32 m0, s20, 0x2000
	s_nop 0
	global_load_lds_dwordx4 v[214:215], off
	v_lshl_add_u64 v[214:215], v[222:223], 0, s[60:61]
	s_mov_b32 m0, s57
	s_nop 0
	global_load_lds_dwordx4 v[214:215], off
	v_lshl_add_u64 v[214:215], v[224:225], 0, s[60:61]
	s_mov_b32 m0, s65
	s_nop 0
	global_load_lds_dwordx4 v[214:215], off
	ds_read_b128 v[174:177], v148 offset:49152
	ds_read_b128 v[178:181], v148 offset:50176
	ds_read_b128 v[182:185], v148 offset:51200
	ds_read_b128 v[186:189], v148 offset:52224
	ds_read_b128 v[190:193], v148 offset:53248
	ds_read_b128 v[194:197], v148 offset:54272
	ds_read_b128 v[198:201], v148 offset:55296
	ds_read_b128 v[202:205], v148 offset:56320
	s_waitcnt lgkmcnt(0)
	s_waitcnt vmcnt(8)
	s_barrier
	s_setprio 1
	s_waitcnt lgkmcnt(0)
	v_mfma_f32_16x16x32_bf16 v[110:113], v[130:133], v[174:177], v[110:113]
	v_mfma_f32_16x16x32_bf16 v[78:81], v[150:153], v[174:177], v[78:81]
	v_mfma_f32_16x16x32_bf16 v[106:109], v[130:133], v[182:185], v[106:109]
	v_mfma_f32_16x16x32_bf16 v[74:77], v[150:153], v[182:185], v[74:77]
	v_mfma_f32_16x16x32_bf16 v[102:105], v[130:133], v[190:193], v[102:105]
	v_mfma_f32_16x16x32_bf16 v[70:73], v[150:153], v[190:193], v[70:73]
	v_mfma_f32_16x16x32_bf16 v[98:101], v[130:133], v[198:201], v[98:101]
	v_mfma_f32_16x16x32_bf16 v[66:69], v[150:153], v[198:201], v[66:69]
	v_mfma_f32_16x16x32_bf16 v[110:113], v[142:145], v[178:181], v[110:113]
	v_mfma_f32_16x16x32_bf16 v[78:81], v[154:157], v[178:181], v[78:81]
	v_mfma_f32_16x16x32_bf16 v[106:109], v[142:145], v[186:189], v[106:109]
	v_mfma_f32_16x16x32_bf16 v[74:77], v[154:157], v[186:189], v[74:77]
	v_mfma_f32_16x16x32_bf16 v[102:105], v[142:145], v[194:197], v[102:105]
	v_mfma_f32_16x16x32_bf16 v[70:73], v[154:157], v[194:197], v[70:73]
	v_mfma_f32_16x16x32_bf16 v[98:101], v[142:145], v[202:205], v[98:101]
	v_mfma_f32_16x16x32_bf16 v[66:69], v[154:157], v[202:205], v[66:69]
	s_setprio 0
	s_setprio 1
	v_mfma_f32_16x16x32_bf16 v[46:49], v[158:161], v[174:177], v[46:49]
	v_mfma_f32_16x16x32_bf16 v[14:17], v[166:169], v[174:177], v[14:17]
	v_mfma_f32_16x16x32_bf16 v[42:45], v[158:161], v[182:185], v[42:45]
	v_mfma_f32_16x16x32_bf16 v[10:13], v[166:169], v[182:185], v[10:13]
	v_mfma_f32_16x16x32_bf16 v[38:41], v[158:161], v[190:193], v[38:41]
	v_mfma_f32_16x16x32_bf16 v[6:9], v[166:169], v[190:193], v[6:9]
	v_mfma_f32_16x16x32_bf16 v[34:37], v[158:161], v[198:201], v[34:37]
	v_mfma_f32_16x16x32_bf16 v[2:5], v[166:169], v[198:201], v[2:5]
	v_mfma_f32_16x16x32_bf16 v[46:49], v[162:165], v[178:181], v[46:49]
	v_mfma_f32_16x16x32_bf16 v[14:17], v[170:173], v[178:181], v[14:17]
	v_mfma_f32_16x16x32_bf16 v[42:45], v[162:165], v[186:189], v[42:45]
	v_mfma_f32_16x16x32_bf16 v[10:13], v[170:173], v[186:189], v[10:13]
	v_mfma_f32_16x16x32_bf16 v[38:41], v[162:165], v[194:197], v[38:41]
	v_mfma_f32_16x16x32_bf16 v[6:9], v[170:173], v[194:197], v[6:9]
	v_mfma_f32_16x16x32_bf16 v[34:37], v[162:165], v[202:205], v[34:37]
	v_mfma_f32_16x16x32_bf16 v[2:5], v[170:173], v[202:205], v[2:5]
	s_setprio 0
	s_barrier
	s_add_u32 s18, s18, 0x100
	s_addc_u32 s19, s19, 0
	s_add_u32 s71, s71, 0x100
	s_addc_u32 s72, s72, 0
	s_cmp_ge_i32 s73, s66
	s_mov_b32 s20, s73
	s_cbranch_scc1 .LBB0_1013
.LBB0_1012:
	s_add_i32 s73, s20, 2
	s_add_u32 s31, s18, 0x80
	s_addc_u32 s21, s19, 0
	s_add_i32 s74, 0, 0x10000
	s_cmp_eq_u32 s67, s20
	s_cselect_b32 s21, s3, s21
	s_cselect_b32 s20, s2, s31
	s_cselect_b32 s63, s17, s72
	s_cselect_b32 s62, s16, s71
	s_add_i32 s31, 0, 0x14000
	v_lshl_add_u64 v[214:215], s[18:19], 0, v[138:139]
	s_add_i32 m0, s23, 0xc000
	s_nop 0
	global_load_lds_dwordx4 v[214:215], off
	v_lshl_add_u64 v[214:215], s[18:19], 0, v[140:141]
	s_add_i32 m0, s23, 0xe000
	s_nop 0
	global_load_lds_dwordx4 v[214:215], off
	v_add_u32_e32 v149, s74, v146
	ds_read_b128 v[130:133], v149
	ds_read_b128 v[142:145], v149 offset:1024
	ds_read_b128 v[150:153], v149 offset:2048
	ds_read_b128 v[154:157], v149 offset:3072
	v_add_u32_e32 v149, s31, v146
	ds_read_b128 v[158:161], v149
	ds_read_b128 v[162:165], v149 offset:1024
	ds_read_b128 v[166:169], v149 offset:2048
	ds_read_b128 v[170:173], v149 offset:3072
	ds_read_b128 v[174:177], v148
	ds_read_b128 v[178:181], v148 offset:1024
	ds_read_b128 v[182:185], v148 offset:2048
	ds_read_b128 v[186:189], v148 offset:3072
	ds_read_b128 v[190:193], v148 offset:4096
	ds_read_b128 v[194:197], v148 offset:5120
	ds_read_b128 v[198:201], v148 offset:6144
	ds_read_b128 v[202:205], v148 offset:7168
	s_waitcnt lgkmcnt(0)
	s_waitcnt vmcnt(8)
	s_barrier
	s_setprio 1
	s_waitcnt lgkmcnt(0)
	v_mfma_f32_16x16x32_bf16 v[126:129], v[130:133], v[174:177], v[126:129]
	v_mfma_f32_16x16x32_bf16 v[94:97], v[150:153], v[174:177], v[94:97]
	v_mfma_f32_16x16x32_bf16 v[122:125], v[130:133], v[182:185], v[122:125]
	v_mfma_f32_16x16x32_bf16 v[90:93], v[150:153], v[182:185], v[90:93]
	v_mfma_f32_16x16x32_bf16 v[118:121], v[130:133], v[190:193], v[118:121]
	v_mfma_f32_16x16x32_bf16 v[86:89], v[150:153], v[190:193], v[86:89]
	v_mfma_f32_16x16x32_bf16 v[114:117], v[130:133], v[198:201], v[114:117]
	v_mfma_f32_16x16x32_bf16 v[82:85], v[150:153], v[198:201], v[82:85]
	v_mfma_f32_16x16x32_bf16 v[126:129], v[142:145], v[178:181], v[126:129]
	v_mfma_f32_16x16x32_bf16 v[94:97], v[154:157], v[178:181], v[94:97]
	v_mfma_f32_16x16x32_bf16 v[122:125], v[142:145], v[186:189], v[122:125]
	v_mfma_f32_16x16x32_bf16 v[90:93], v[154:157], v[186:189], v[90:93]
	v_mfma_f32_16x16x32_bf16 v[118:121], v[142:145], v[194:197], v[118:121]
	v_mfma_f32_16x16x32_bf16 v[86:89], v[154:157], v[194:197], v[86:89]
	v_mfma_f32_16x16x32_bf16 v[114:117], v[142:145], v[202:205], v[114:117]
	v_mfma_f32_16x16x32_bf16 v[82:85], v[154:157], v[202:205], v[82:85]
	s_setprio 0
	s_setprio 1
	v_mfma_f32_16x16x32_bf16 v[62:65], v[158:161], v[174:177], v[62:65]
	v_mfma_f32_16x16x32_bf16 v[30:33], v[166:169], v[174:177], v[30:33]
	v_mfma_f32_16x16x32_bf16 v[58:61], v[158:161], v[182:185], v[58:61]
	v_mfma_f32_16x16x32_bf16 v[26:29], v[166:169], v[182:185], v[26:29]
	v_mfma_f32_16x16x32_bf16 v[54:57], v[158:161], v[190:193], v[54:57]
	v_mfma_f32_16x16x32_bf16 v[22:25], v[166:169], v[190:193], v[22:25]
	v_mfma_f32_16x16x32_bf16 v[50:53], v[158:161], v[198:201], v[50:53]
	v_mfma_f32_16x16x32_bf16 v[18:21], v[166:169], v[198:201], v[18:21]
	v_mfma_f32_16x16x32_bf16 v[62:65], v[162:165], v[178:181], v[62:65]
	v_mfma_f32_16x16x32_bf16 v[30:33], v[170:173], v[178:181], v[30:33]
	v_mfma_f32_16x16x32_bf16 v[58:61], v[162:165], v[186:189], v[58:61]
	v_mfma_f32_16x16x32_bf16 v[26:29], v[170:173], v[186:189], v[26:29]
	v_mfma_f32_16x16x32_bf16 v[54:57], v[162:165], v[194:197], v[54:57]
	v_mfma_f32_16x16x32_bf16 v[22:25], v[170:173], v[194:197], v[22:25]
	v_mfma_f32_16x16x32_bf16 v[50:53], v[162:165], v[202:205], v[50:53]
	v_mfma_f32_16x16x32_bf16 v[18:21], v[170:173], v[202:205], v[18:21]
	s_setprio 0
	s_barrier
	s_add_i32 s74, s74, s22
	v_lshl_add_u64 v[214:215], s[62:63], 0, v[136:137]
	s_mov_b32 m0, s74
	s_nop 0
	global_load_lds_dwordx4 v[214:215], off
	s_add_i32 m0, s74, 0x2000
	v_lshl_add_u64 v[216:217], s[62:63], 0, v[134:135]
	s_add_u32 s62, s62, s4
	s_addc_u32 s63, s63, s5
	s_add_i32 s31, s31, s22
	global_load_lds_dwordx4 v[216:217], off
	v_lshl_add_u64 v[218:219], s[62:63], 0, v[136:137]
	s_mov_b32 m0, s31
	v_lshl_add_u64 v[220:221], s[62:63], 0, v[134:135]
	global_load_lds_dwordx4 v[218:219], off
	s_add_i32 m0, s31, 0x2000
	v_lshl_add_u64 v[222:223], s[20:21], 0, v[136:137]
	global_load_lds_dwordx4 v[220:221], off
	s_mov_b32 m0, s23
	v_lshl_add_u64 v[224:225], s[20:21], 0, v[134:135]
	global_load_lds_dwordx4 v[222:223], off
	s_mov_b32 m0, s52
	s_nop 0
	global_load_lds_dwordx4 v[224:225], off
	ds_read_b128 v[174:177], v148 offset:16384
	ds_read_b128 v[178:181], v148 offset:17408
	ds_read_b128 v[182:185], v148 offset:18432
	ds_read_b128 v[186:189], v148 offset:19456
	ds_read_b128 v[190:193], v148 offset:20480
	ds_read_b128 v[194:197], v148 offset:21504
	ds_read_b128 v[198:201], v148 offset:22528
	ds_read_b128 v[202:205], v148 offset:23552
	s_waitcnt lgkmcnt(0)
	s_waitcnt vmcnt(8)
	s_barrier
	s_setprio 1
	s_waitcnt lgkmcnt(0)
	v_mfma_f32_16x16x32_bf16 v[110:113], v[130:133], v[174:177], v[110:113]
	v_mfma_f32_16x16x32_bf16 v[78:81], v[150:153], v[174:177], v[78:81]
	v_mfma_f32_16x16x32_bf16 v[106:109], v[130:133], v[182:185], v[106:109]
	v_mfma_f32_16x16x32_bf16 v[74:77], v[150:153], v[182:185], v[74:77]
	v_mfma_f32_16x16x32_bf16 v[102:105], v[130:133], v[190:193], v[102:105]
	v_mfma_f32_16x16x32_bf16 v[70:73], v[150:153], v[190:193], v[70:73]
	v_mfma_f32_16x16x32_bf16 v[98:101], v[130:133], v[198:201], v[98:101]
	v_mfma_f32_16x16x32_bf16 v[66:69], v[150:153], v[198:201], v[66:69]
	v_mfma_f32_16x16x32_bf16 v[110:113], v[142:145], v[178:181], v[110:113]
	v_mfma_f32_16x16x32_bf16 v[78:81], v[154:157], v[178:181], v[78:81]
	v_mfma_f32_16x16x32_bf16 v[106:109], v[142:145], v[186:189], v[106:109]
	v_mfma_f32_16x16x32_bf16 v[74:77], v[154:157], v[186:189], v[74:77]
	v_mfma_f32_16x16x32_bf16 v[102:105], v[142:145], v[194:197], v[102:105]
	v_mfma_f32_16x16x32_bf16 v[70:73], v[154:157], v[194:197], v[70:73]
	v_mfma_f32_16x16x32_bf16 v[98:101], v[142:145], v[202:205], v[98:101]
	v_mfma_f32_16x16x32_bf16 v[66:69], v[154:157], v[202:205], v[66:69]
	s_setprio 0
	s_setprio 1
	v_mfma_f32_16x16x32_bf16 v[46:49], v[158:161], v[174:177], v[46:49]
	v_mfma_f32_16x16x32_bf16 v[14:17], v[166:169], v[174:177], v[14:17]
	v_mfma_f32_16x16x32_bf16 v[42:45], v[158:161], v[182:185], v[42:45]
	v_mfma_f32_16x16x32_bf16 v[10:13], v[166:169], v[182:185], v[10:13]
	v_mfma_f32_16x16x32_bf16 v[38:41], v[158:161], v[190:193], v[38:41]
	v_mfma_f32_16x16x32_bf16 v[6:9], v[166:169], v[190:193], v[6:9]
	v_mfma_f32_16x16x32_bf16 v[34:37], v[158:161], v[198:201], v[34:37]
	v_mfma_f32_16x16x32_bf16 v[2:5], v[166:169], v[198:201], v[2:5]
	v_mfma_f32_16x16x32_bf16 v[46:49], v[162:165], v[178:181], v[46:49]
	v_mfma_f32_16x16x32_bf16 v[14:17], v[170:173], v[178:181], v[14:17]
	v_mfma_f32_16x16x32_bf16 v[42:45], v[162:165], v[186:189], v[42:45]
	v_mfma_f32_16x16x32_bf16 v[10:13], v[170:173], v[186:189], v[10:13]
	v_mfma_f32_16x16x32_bf16 v[38:41], v[162:165], v[194:197], v[38:41]
	v_mfma_f32_16x16x32_bf16 v[6:9], v[170:173], v[194:197], v[6:9]
	v_mfma_f32_16x16x32_bf16 v[34:37], v[162:165], v[202:205], v[34:37]
	v_mfma_f32_16x16x32_bf16 v[2:5], v[170:173], v[202:205], v[2:5]
	s_setprio 0
	s_barrier
	s_add_i32 s31, 0, 0x18000
	s_add_i32 s62, 0, 0x1c000
	s_add_u32 s20, s20, s4
	s_addc_u32 s21, s21, s5
	s_mov_b32 m0, s53
	v_lshl_add_u64 v[226:227], s[20:21], 0, v[136:137]
	global_load_lds_dwordx4 v[226:227], off
	v_lshl_add_u64 v[226:227], s[20:21], 0, v[134:135]
	s_mov_b32 m0, s56
	s_nop 0
	global_load_lds_dwordx4 v[226:227], off
	v_add_u32_e32 v149, s31, v146
	ds_read_b128 v[130:133], v149
	ds_read_b128 v[142:145], v149 offset:1024
	ds_read_b128 v[150:153], v149 offset:2048
	ds_read_b128 v[154:157], v149 offset:3072
	v_add_u32_e32 v149, s62, v146
	ds_read_b128 v[158:161], v149
	ds_read_b128 v[162:165], v149 offset:1024
	ds_read_b128 v[166:169], v149 offset:2048
	ds_read_b128 v[170:173], v149 offset:3072
	ds_read_b128 v[174:177], v148 offset:32768
	ds_read_b128 v[178:181], v148 offset:33792
	ds_read_b128 v[182:185], v148 offset:34816
	ds_read_b128 v[186:189], v148 offset:35840
	ds_read_b128 v[190:193], v148 offset:36864
	ds_read_b128 v[194:197], v148 offset:37888
	ds_read_b128 v[198:201], v148 offset:38912
	ds_read_b128 v[202:205], v148 offset:39936
	s_waitcnt lgkmcnt(0)
	s_waitcnt vmcnt(8)
	s_barrier
	s_setprio 1
	s_waitcnt lgkmcnt(0)
	v_mfma_f32_16x16x32_bf16 v[126:129], v[130:133], v[174:177], v[126:129]
	v_mfma_f32_16x16x32_bf16 v[94:97], v[150:153], v[174:177], v[94:97]
	v_mfma_f32_16x16x32_bf16 v[122:125], v[130:133], v[182:185], v[122:125]
	v_mfma_f32_16x16x32_bf16 v[90:93], v[150:153], v[182:185], v[90:93]
	v_mfma_f32_16x16x32_bf16 v[118:121], v[130:133], v[190:193], v[118:121]
	v_mfma_f32_16x16x32_bf16 v[86:89], v[150:153], v[190:193], v[86:89]
	v_mfma_f32_16x16x32_bf16 v[114:117], v[130:133], v[198:201], v[114:117]
	v_mfma_f32_16x16x32_bf16 v[82:85], v[150:153], v[198:201], v[82:85]
	v_mfma_f32_16x16x32_bf16 v[126:129], v[142:145], v[178:181], v[126:129]
	v_mfma_f32_16x16x32_bf16 v[94:97], v[154:157], v[178:181], v[94:97]
	v_mfma_f32_16x16x32_bf16 v[122:125], v[142:145], v[186:189], v[122:125]
	v_mfma_f32_16x16x32_bf16 v[90:93], v[154:157], v[186:189], v[90:93]
	v_mfma_f32_16x16x32_bf16 v[118:121], v[142:145], v[194:197], v[118:121]
	v_mfma_f32_16x16x32_bf16 v[86:89], v[154:157], v[194:197], v[86:89]
	v_mfma_f32_16x16x32_bf16 v[114:117], v[142:145], v[202:205], v[114:117]
	v_mfma_f32_16x16x32_bf16 v[82:85], v[154:157], v[202:205], v[82:85]
	s_setprio 0
	s_setprio 1
	v_mfma_f32_16x16x32_bf16 v[62:65], v[158:161], v[174:177], v[62:65]
	v_mfma_f32_16x16x32_bf16 v[30:33], v[166:169], v[174:177], v[30:33]
	v_mfma_f32_16x16x32_bf16 v[58:61], v[158:161], v[182:185], v[58:61]
	v_mfma_f32_16x16x32_bf16 v[26:29], v[166:169], v[182:185], v[26:29]
	v_mfma_f32_16x16x32_bf16 v[54:57], v[158:161], v[190:193], v[54:57]
	v_mfma_f32_16x16x32_bf16 v[22:25], v[166:169], v[190:193], v[22:25]
	v_mfma_f32_16x16x32_bf16 v[50:53], v[158:161], v[198:201], v[50:53]
	v_mfma_f32_16x16x32_bf16 v[18:21], v[166:169], v[198:201], v[18:21]
	v_mfma_f32_16x16x32_bf16 v[62:65], v[162:165], v[178:181], v[62:65]
	v_mfma_f32_16x16x32_bf16 v[30:33], v[170:173], v[178:181], v[30:33]
	v_mfma_f32_16x16x32_bf16 v[58:61], v[162:165], v[186:189], v[58:61]
	v_mfma_f32_16x16x32_bf16 v[26:29], v[170:173], v[186:189], v[26:29]
	v_mfma_f32_16x16x32_bf16 v[54:57], v[162:165], v[194:197], v[54:57]
	v_mfma_f32_16x16x32_bf16 v[22:25], v[170:173], v[194:197], v[22:25]
	v_mfma_f32_16x16x32_bf16 v[50:53], v[162:165], v[202:205], v[50:53]
	v_mfma_f32_16x16x32_bf16 v[18:21], v[170:173], v[202:205], v[18:21]
	s_setprio 0
	s_barrier
	s_add_i32 s20, s31, s22
	v_lshl_add_u64 v[214:215], v[214:215], 0, s[60:61]
	s_mov_b32 m0, s20
	s_nop 0
	global_load_lds_dwordx4 v[214:215], off
	v_lshl_add_u64 v[214:215], v[216:217], 0, s[60:61]
	s_add_i32 m0, s20, 0x2000
	s_add_i32 s20, s62, s22
	global_load_lds_dwordx4 v[214:215], off
	v_lshl_add_u64 v[214:215], v[218:219], 0, s[60:61]
	s_mov_b32 m0, s20
	s_nop 0
	global_load_lds_dwordx4 v[214:215], off
	v_lshl_add_u64 v[214:215], v[220:221], 0, s[60:61]
	s_add_i32 m0, s20, 0x2000
	s_nop 0
	global_load_lds_dwordx4 v[214:215], off
	v_lshl_add_u64 v[214:215], v[222:223], 0, s[60:61]
	s_mov_b32 m0, s57
	s_nop 0
	global_load_lds_dwordx4 v[214:215], off
	v_lshl_add_u64 v[214:215], v[224:225], 0, s[60:61]
	s_mov_b32 m0, s65
	s_nop 0
	global_load_lds_dwordx4 v[214:215], off
	ds_read_b128 v[174:177], v148 offset:49152
	ds_read_b128 v[178:181], v148 offset:50176
	ds_read_b128 v[182:185], v148 offset:51200
	ds_read_b128 v[186:189], v148 offset:52224
	ds_read_b128 v[190:193], v148 offset:53248
	ds_read_b128 v[194:197], v148 offset:54272
	ds_read_b128 v[198:201], v148 offset:55296
	ds_read_b128 v[202:205], v148 offset:56320
	s_waitcnt lgkmcnt(0)
	s_waitcnt vmcnt(8)
	s_barrier
	s_setprio 1
	s_waitcnt lgkmcnt(0)
	v_mfma_f32_16x16x32_bf16 v[110:113], v[130:133], v[174:177], v[110:113]
	v_mfma_f32_16x16x32_bf16 v[78:81], v[150:153], v[174:177], v[78:81]
	v_mfma_f32_16x16x32_bf16 v[106:109], v[130:133], v[182:185], v[106:109]
	v_mfma_f32_16x16x32_bf16 v[74:77], v[150:153], v[182:185], v[74:77]
	v_mfma_f32_16x16x32_bf16 v[102:105], v[130:133], v[190:193], v[102:105]
	v_mfma_f32_16x16x32_bf16 v[70:73], v[150:153], v[190:193], v[70:73]
	v_mfma_f32_16x16x32_bf16 v[98:101], v[130:133], v[198:201], v[98:101]
	v_mfma_f32_16x16x32_bf16 v[66:69], v[150:153], v[198:201], v[66:69]
	v_mfma_f32_16x16x32_bf16 v[110:113], v[142:145], v[178:181], v[110:113]
	v_mfma_f32_16x16x32_bf16 v[78:81], v[154:157], v[178:181], v[78:81]
	v_mfma_f32_16x16x32_bf16 v[106:109], v[142:145], v[186:189], v[106:109]
	v_mfma_f32_16x16x32_bf16 v[74:77], v[154:157], v[186:189], v[74:77]
	v_mfma_f32_16x16x32_bf16 v[102:105], v[142:145], v[194:197], v[102:105]
	v_mfma_f32_16x16x32_bf16 v[70:73], v[154:157], v[194:197], v[70:73]
	v_mfma_f32_16x16x32_bf16 v[98:101], v[142:145], v[202:205], v[98:101]
	v_mfma_f32_16x16x32_bf16 v[66:69], v[154:157], v[202:205], v[66:69]
	s_setprio 0
	s_setprio 1
	v_mfma_f32_16x16x32_bf16 v[46:49], v[158:161], v[174:177], v[46:49]
	v_mfma_f32_16x16x32_bf16 v[14:17], v[166:169], v[174:177], v[14:17]
	v_mfma_f32_16x16x32_bf16 v[42:45], v[158:161], v[182:185], v[42:45]
	v_mfma_f32_16x16x32_bf16 v[10:13], v[166:169], v[182:185], v[10:13]
	v_mfma_f32_16x16x32_bf16 v[38:41], v[158:161], v[190:193], v[38:41]
	v_mfma_f32_16x16x32_bf16 v[6:9], v[166:169], v[190:193], v[6:9]
	v_mfma_f32_16x16x32_bf16 v[34:37], v[158:161], v[198:201], v[34:37]
	v_mfma_f32_16x16x32_bf16 v[2:5], v[166:169], v[198:201], v[2:5]
	v_mfma_f32_16x16x32_bf16 v[46:49], v[162:165], v[178:181], v[46:49]
	v_mfma_f32_16x16x32_bf16 v[14:17], v[170:173], v[178:181], v[14:17]
	v_mfma_f32_16x16x32_bf16 v[42:45], v[162:165], v[186:189], v[42:45]
	v_mfma_f32_16x16x32_bf16 v[10:13], v[170:173], v[186:189], v[10:13]
	v_mfma_f32_16x16x32_bf16 v[38:41], v[162:165], v[194:197], v[38:41]
	v_mfma_f32_16x16x32_bf16 v[6:9], v[170:173], v[194:197], v[6:9]
	v_mfma_f32_16x16x32_bf16 v[34:37], v[162:165], v[202:205], v[34:37]
	v_mfma_f32_16x16x32_bf16 v[2:5], v[170:173], v[202:205], v[2:5]
	s_setprio 0
	s_barrier
	s_add_u32 s18, s18, 0x100
	s_addc_u32 s19, s19, 0
	s_add_u32 s71, s71, 0x100
	s_addc_u32 s72, s72, 0
	s_cmp_ge_i32 s73, s66
	s_mov_b32 s20, s73
	s_cbranch_scc0 .LBB0_1012

.LBB0_1141:
	s_add_u32 s0, s6, 0x80
	s_addc_u32 s1, s7, 0
	s_add_u32 s6, s4, 0x100
	s_addc_u32 s7, s5, 0
	s_mov_b32 s4, 0
	s_add_i32 s9, s4, 2
	s_add_u32 s10, s0, 0x80
	s_addc_u32 s5, s1, 0
	s_add_i32 s31, 0, 0x10000
	s_cmp_eq_u32 s77, s4
	s_cselect_b32 s5, s23, s5
	s_cselect_b32 s4, s22, s10
	s_cselect_b32 s11, s67, s7
	s_cselect_b32 s10, s66, s6
	s_add_i32 s53, 0, 0x14000
	v_lshl_add_u64 v[162:163], s[0:1], 0, v[154:155]
	s_add_i32 m0, s70, 0xc000
	s_nop 0
	global_load_lds_dwordx4 v[162:163], off
	v_lshl_add_u64 v[162:163], s[0:1], 0, v[156:157]
	s_add_i32 m0, s70, 0xe000
	s_nop 0
	global_load_lds_dwordx4 v[162:163], off
	v_add_u32_e32 v1, s31, v165
	ds_read_b128 v[82:85], v1
	ds_read_b128 v[86:89], v1 offset:1024
	ds_read_b128 v[138:141], v1 offset:2048
	ds_read_b128 v[142:145], v1 offset:3072
	v_add_u32_e32 v1, s53, v165
	ds_read_b128 v[158:161], v1
	ds_read_b128 v[168:171], v1 offset:1024
	ds_read_b128 v[172:175], v1 offset:2048
	ds_read_b128 v[176:179], v1 offset:3072
	ds_read_b128 v[180:183], v167
	ds_read_b128 v[184:187], v167 offset:1024
	ds_read_b128 v[188:191], v167 offset:2048
	ds_read_b128 v[192:195], v167 offset:3072
	ds_read_b128 v[196:199], v167 offset:4096
	ds_read_b128 v[200:203], v167 offset:5120
	ds_read_b128 v[214:217], v167 offset:6144
	ds_read_b128 v[218:221], v167 offset:7168
	s_waitcnt lgkmcnt(0)
	s_waitcnt vmcnt(8)
	s_barrier
	s_setprio 1
	s_waitcnt lgkmcnt(0)
	v_mfma_f32_16x16x32_bf16 v[134:137], v[82:85], v[180:183], 0
	v_mfma_f32_16x16x32_bf16 v[130:133], v[138:141], v[180:183], 0
	v_mfma_f32_16x16x32_bf16 v[126:129], v[82:85], v[188:191], 0
	v_mfma_f32_16x16x32_bf16 v[122:125], v[138:141], v[188:191], 0
	v_mfma_f32_16x16x32_bf16 v[118:121], v[82:85], v[196:199], 0
	v_mfma_f32_16x16x32_bf16 v[114:117], v[138:141], v[196:199], 0
	v_mfma_f32_16x16x32_bf16 v[110:113], v[82:85], v[214:217], 0
	v_mfma_f32_16x16x32_bf16 v[106:109], v[138:141], v[214:217], 0
	v_mfma_f32_16x16x32_bf16 v[134:137], v[86:89], v[184:187], v[134:137]
	v_mfma_f32_16x16x32_bf16 v[130:133], v[142:145], v[184:187], v[130:133]
	v_mfma_f32_16x16x32_bf16 v[126:129], v[86:89], v[192:195], v[126:129]
	v_mfma_f32_16x16x32_bf16 v[122:125], v[142:145], v[192:195], v[122:125]
	v_mfma_f32_16x16x32_bf16 v[118:121], v[86:89], v[200:203], v[118:121]
	v_mfma_f32_16x16x32_bf16 v[114:117], v[142:145], v[200:203], v[114:117]
	v_mfma_f32_16x16x32_bf16 v[110:113], v[86:89], v[218:221], v[110:113]
	v_mfma_f32_16x16x32_bf16 v[106:109], v[142:145], v[218:221], v[106:109]
	s_setprio 0
	s_setprio 1
	v_mfma_f32_16x16x32_bf16 v[62:65], v[158:161], v[180:183], 0
	v_mfma_f32_16x16x32_bf16 v[58:61], v[172:175], v[180:183], 0
	v_mfma_f32_16x16x32_bf16 v[54:57], v[158:161], v[188:191], 0
	v_mfma_f32_16x16x32_bf16 v[50:53], v[172:175], v[188:191], 0
	v_mfma_f32_16x16x32_bf16 v[46:49], v[158:161], v[196:199], 0
	v_mfma_f32_16x16x32_bf16 v[42:45], v[172:175], v[196:199], 0
	v_mfma_f32_16x16x32_bf16 v[38:41], v[158:161], v[214:217], 0
	v_mfma_f32_16x16x32_bf16 v[34:37], v[172:175], v[214:217], 0
	v_mfma_f32_16x16x32_bf16 v[62:65], v[168:171], v[184:187], v[62:65]
	v_mfma_f32_16x16x32_bf16 v[58:61], v[176:179], v[184:187], v[58:61]
	v_mfma_f32_16x16x32_bf16 v[54:57], v[168:171], v[192:195], v[54:57]
	v_mfma_f32_16x16x32_bf16 v[50:53], v[176:179], v[192:195], v[50:53]
	v_mfma_f32_16x16x32_bf16 v[46:49], v[168:171], v[200:203], v[46:49]
	v_mfma_f32_16x16x32_bf16 v[42:45], v[176:179], v[200:203], v[42:45]
	v_mfma_f32_16x16x32_bf16 v[38:41], v[168:171], v[218:221], v[38:41]
	v_mfma_f32_16x16x32_bf16 v[34:37], v[176:179], v[218:221], v[34:37]
	s_setprio 0
	s_barrier
	s_add_i32 s31, s31, s65
	v_lshl_add_u64 v[162:163], s[10:11], 0, v[150:151]
	s_mov_b32 m0, s31
	s_nop 0
	global_load_lds_dwordx4 v[162:163], off
	s_add_i32 m0, s31, 0x2000
	v_lshl_add_u64 v[204:205], s[10:11], 0, v[146:147]
	s_add_u32 s10, s10, s12
	s_addc_u32 s11, s11, s13
	s_add_i32 s31, s53, s65
	global_load_lds_dwordx4 v[204:205], off
	v_lshl_add_u64 v[222:223], s[10:11], 0, v[150:151]
	s_mov_b32 m0, s31
	v_lshl_add_u64 v[224:225], s[10:11], 0, v[146:147]
	global_load_lds_dwordx4 v[222:223], off
	s_add_i32 m0, s31, 0x2000
	v_lshl_add_u64 v[226:227], s[4:5], 0, v[152:153]
	global_load_lds_dwordx4 v[224:225], off
	s_mov_b32 m0, s70
	v_lshl_add_u64 v[236:237], s[4:5], 0, v[148:149]
	global_load_lds_dwordx4 v[226:227], off
	s_mov_b32 m0, s71
	s_nop 0
	global_load_lds_dwordx4 v[236:237], off
	ds_read_b128 v[180:183], v167 offset:16384
	ds_read_b128 v[184:187], v167 offset:17408
	ds_read_b128 v[188:191], v167 offset:18432
	ds_read_b128 v[192:195], v167 offset:19456
	ds_read_b128 v[196:199], v167 offset:20480
	ds_read_b128 v[200:203], v167 offset:21504
	ds_read_b128 v[214:217], v167 offset:22528
	ds_read_b128 v[218:221], v167 offset:23552
	s_waitcnt lgkmcnt(0)
	s_waitcnt vmcnt(8)
	s_barrier
	s_setprio 1
	s_waitcnt lgkmcnt(0)
	v_mfma_f32_16x16x32_bf16 v[102:105], v[82:85], v[180:183], 0
	v_mfma_f32_16x16x32_bf16 v[98:101], v[138:141], v[180:183], 0
	v_mfma_f32_16x16x32_bf16 v[94:97], v[82:85], v[188:191], 0
	v_mfma_f32_16x16x32_bf16 v[90:93], v[138:141], v[188:191], 0
	v_mfma_f32_16x16x32_bf16 v[78:81], v[82:85], v[196:199], 0
	v_mfma_f32_16x16x32_bf16 v[74:77], v[138:141], v[196:199], 0
	v_mfma_f32_16x16x32_bf16 v[70:73], v[82:85], v[214:217], 0
	v_mfma_f32_16x16x32_bf16 v[66:69], v[138:141], v[214:217], 0
	v_mfma_f32_16x16x32_bf16 v[102:105], v[86:89], v[184:187], v[102:105]
	v_mfma_f32_16x16x32_bf16 v[98:101], v[142:145], v[184:187], v[98:101]
	v_mfma_f32_16x16x32_bf16 v[94:97], v[86:89], v[192:195], v[94:97]
	v_mfma_f32_16x16x32_bf16 v[90:93], v[142:145], v[192:195], v[90:93]
	v_mfma_f32_16x16x32_bf16 v[78:81], v[86:89], v[200:203], v[78:81]
	v_mfma_f32_16x16x32_bf16 v[74:77], v[142:145], v[200:203], v[74:77]
	v_mfma_f32_16x16x32_bf16 v[70:73], v[86:89], v[218:221], v[70:73]
	v_mfma_f32_16x16x32_bf16 v[66:69], v[142:145], v[218:221], v[66:69]
	s_setprio 0
	s_setprio 1
	v_mfma_f32_16x16x32_bf16 v[30:33], v[158:161], v[180:183], 0
	v_mfma_f32_16x16x32_bf16 v[26:29], v[172:175], v[180:183], 0
	v_mfma_f32_16x16x32_bf16 v[22:25], v[158:161], v[188:191], 0
	v_mfma_f32_16x16x32_bf16 v[18:21], v[172:175], v[188:191], 0
	v_mfma_f32_16x16x32_bf16 v[14:17], v[158:161], v[196:199], 0
	v_mfma_f32_16x16x32_bf16 v[10:13], v[172:175], v[196:199], 0
	v_mfma_f32_16x16x32_bf16 v[6:9], v[158:161], v[214:217], 0
	v_mfma_f32_16x16x32_bf16 v[2:5], v[172:175], v[214:217], 0
	v_mfma_f32_16x16x32_bf16 v[30:33], v[168:171], v[184:187], v[30:33]
	v_mfma_f32_16x16x32_bf16 v[26:29], v[176:179], v[184:187], v[26:29]
	v_mfma_f32_16x16x32_bf16 v[22:25], v[168:171], v[192:195], v[22:25]
	v_mfma_f32_16x16x32_bf16 v[18:21], v[176:179], v[192:195], v[18:21]
	v_mfma_f32_16x16x32_bf16 v[14:17], v[168:171], v[200:203], v[14:17]
	v_mfma_f32_16x16x32_bf16 v[10:13], v[176:179], v[200:203], v[10:13]
	v_mfma_f32_16x16x32_bf16 v[6:9], v[168:171], v[218:221], v[6:9]
	v_mfma_f32_16x16x32_bf16 v[2:5], v[176:179], v[218:221], v[2:5]
	s_setprio 0
	s_barrier
	s_add_i32 s10, 0, 0x18000
	s_add_i32 s11, 0, 0x1c000
	s_add_u32 s4, s4, s12
	s_addc_u32 s5, s5, s13
	s_mov_b32 m0, s72
	v_lshl_add_u64 v[238:239], s[4:5], 0, v[152:153]
	global_load_lds_dwordx4 v[238:239], off
	v_lshl_add_u64 v[238:239], s[4:5], 0, v[148:149]
	s_mov_b32 m0, s73
	s_nop 0
	global_load_lds_dwordx4 v[238:239], off
	v_add_u32_e32 v1, s10, v165
	ds_read_b128 v[82:85], v1
	ds_read_b128 v[86:89], v1 offset:1024
	ds_read_b128 v[138:141], v1 offset:2048
	ds_read_b128 v[142:145], v1 offset:3072
	v_add_u32_e32 v1, s11, v165
	ds_read_b128 v[158:161], v1
	ds_read_b128 v[168:171], v1 offset:1024
	ds_read_b128 v[172:175], v1 offset:2048
	ds_read_b128 v[176:179], v1 offset:3072
	ds_read_b128 v[180:183], v167 offset:32768
	ds_read_b128 v[184:187], v167 offset:33792
	ds_read_b128 v[188:191], v167 offset:34816
	ds_read_b128 v[192:195], v167 offset:35840
	ds_read_b128 v[196:199], v167 offset:36864
	ds_read_b128 v[200:203], v167 offset:37888
	ds_read_b128 v[214:217], v167 offset:38912
	ds_read_b128 v[218:221], v167 offset:39936
	s_waitcnt lgkmcnt(0)
	s_waitcnt vmcnt(8)
	s_barrier
	s_setprio 1
	s_waitcnt lgkmcnt(0)
	v_mfma_f32_16x16x32_bf16 v[134:137], v[82:85], v[180:183], v[134:137]
	v_mfma_f32_16x16x32_bf16 v[130:133], v[138:141], v[180:183], v[130:133]
	v_mfma_f32_16x16x32_bf16 v[126:129], v[82:85], v[188:191], v[126:129]
	v_mfma_f32_16x16x32_bf16 v[122:125], v[138:141], v[188:191], v[122:125]
	v_mfma_f32_16x16x32_bf16 v[118:121], v[82:85], v[196:199], v[118:121]
	v_mfma_f32_16x16x32_bf16 v[114:117], v[138:141], v[196:199], v[114:117]
	v_mfma_f32_16x16x32_bf16 v[110:113], v[82:85], v[214:217], v[110:113]
	v_mfma_f32_16x16x32_bf16 v[106:109], v[138:141], v[214:217], v[106:109]
	v_mfma_f32_16x16x32_bf16 v[134:137], v[86:89], v[184:187], v[134:137]
	v_mfma_f32_16x16x32_bf16 v[130:133], v[142:145], v[184:187], v[130:133]
	v_mfma_f32_16x16x32_bf16 v[126:129], v[86:89], v[192:195], v[126:129]
	v_mfma_f32_16x16x32_bf16 v[122:125], v[142:145], v[192:195], v[122:125]
	v_mfma_f32_16x16x32_bf16 v[118:121], v[86:89], v[200:203], v[118:121]
	v_mfma_f32_16x16x32_bf16 v[114:117], v[142:145], v[200:203], v[114:117]
	v_mfma_f32_16x16x32_bf16 v[110:113], v[86:89], v[218:221], v[110:113]
	v_mfma_f32_16x16x32_bf16 v[106:109], v[142:145], v[218:221], v[106:109]
	s_setprio 0
	s_setprio 1
	v_mfma_f32_16x16x32_bf16 v[62:65], v[158:161], v[180:183], v[62:65]
	v_mfma_f32_16x16x32_bf16 v[58:61], v[172:175], v[180:183], v[58:61]
	v_mfma_f32_16x16x32_bf16 v[54:57], v[158:161], v[188:191], v[54:57]
	v_mfma_f32_16x16x32_bf16 v[50:53], v[172:175], v[188:191], v[50:53]
	v_mfma_f32_16x16x32_bf16 v[46:49], v[158:161], v[196:199], v[46:49]
	v_mfma_f32_16x16x32_bf16 v[42:45], v[172:175], v[196:199], v[42:45]
	v_mfma_f32_16x16x32_bf16 v[38:41], v[158:161], v[214:217], v[38:41]
	v_mfma_f32_16x16x32_bf16 v[34:37], v[172:175], v[214:217], v[34:37]
	v_mfma_f32_16x16x32_bf16 v[62:65], v[168:171], v[184:187], v[62:65]
	v_mfma_f32_16x16x32_bf16 v[58:61], v[176:179], v[184:187], v[58:61]
	v_mfma_f32_16x16x32_bf16 v[54:57], v[168:171], v[192:195], v[54:57]
	v_mfma_f32_16x16x32_bf16 v[50:53], v[176:179], v[192:195], v[50:53]
	v_mfma_f32_16x16x32_bf16 v[46:49], v[168:171], v[200:203], v[46:49]
	v_mfma_f32_16x16x32_bf16 v[42:45], v[176:179], v[200:203], v[42:45]
	v_mfma_f32_16x16x32_bf16 v[38:41], v[168:171], v[218:221], v[38:41]
	v_mfma_f32_16x16x32_bf16 v[34:37], v[176:179], v[218:221], v[34:37]
	s_setprio 0
	s_barrier
	s_add_i32 s4, s10, s65
	v_lshl_add_u64 v[162:163], v[162:163], 0, s[60:61]
	s_mov_b32 m0, s4
	s_nop 0
	global_load_lds_dwordx4 v[162:163], off
	v_lshl_add_u64 v[162:163], v[204:205], 0, s[60:61]
	s_add_i32 m0, s4, 0x2000
	s_add_i32 s4, s11, s65
	global_load_lds_dwordx4 v[162:163], off
	v_lshl_add_u64 v[162:163], v[222:223], 0, s[60:61]
	s_mov_b32 m0, s4
	s_nop 0
	global_load_lds_dwordx4 v[162:163], off
	v_lshl_add_u64 v[162:163], v[224:225], 0, s[60:61]
	s_add_i32 m0, s4, 0x2000
	s_nop 0
	global_load_lds_dwordx4 v[162:163], off
	v_lshl_add_u64 v[162:163], v[226:227], 0, s[60:61]
	s_mov_b32 m0, s74
	s_nop 0
	global_load_lds_dwordx4 v[162:163], off
	v_lshl_add_u64 v[162:163], v[236:237], 0, s[60:61]
	s_mov_b32 m0, s75
	s_nop 0
	global_load_lds_dwordx4 v[162:163], off
	ds_read_b128 v[180:183], v167 offset:49152
	ds_read_b128 v[184:187], v167 offset:50176
	ds_read_b128 v[188:191], v167 offset:51200
	ds_read_b128 v[192:195], v167 offset:52224
	ds_read_b128 v[196:199], v167 offset:53248
	ds_read_b128 v[200:203], v167 offset:54272
	ds_read_b128 v[214:217], v167 offset:55296
	ds_read_b128 v[218:221], v167 offset:56320
	s_waitcnt lgkmcnt(0)
	s_waitcnt vmcnt(8)
	s_barrier
	s_setprio 1
	s_waitcnt lgkmcnt(0)
	v_mfma_f32_16x16x32_bf16 v[102:105], v[82:85], v[180:183], v[102:105]
	v_mfma_f32_16x16x32_bf16 v[98:101], v[138:141], v[180:183], v[98:101]
	v_mfma_f32_16x16x32_bf16 v[94:97], v[82:85], v[188:191], v[94:97]
	v_mfma_f32_16x16x32_bf16 v[90:93], v[138:141], v[188:191], v[90:93]
	v_mfma_f32_16x16x32_bf16 v[78:81], v[82:85], v[196:199], v[78:81]
	v_mfma_f32_16x16x32_bf16 v[74:77], v[138:141], v[196:199], v[74:77]
	v_mfma_f32_16x16x32_bf16 v[70:73], v[82:85], v[214:217], v[70:73]
	v_mfma_f32_16x16x32_bf16 v[66:69], v[138:141], v[214:217], v[66:69]
	v_mfma_f32_16x16x32_bf16 v[102:105], v[86:89], v[184:187], v[102:105]
	v_mfma_f32_16x16x32_bf16 v[98:101], v[142:145], v[184:187], v[98:101]
	v_mfma_f32_16x16x32_bf16 v[94:97], v[86:89], v[192:195], v[94:97]
	v_mfma_f32_16x16x32_bf16 v[90:93], v[142:145], v[192:195], v[90:93]
	v_mfma_f32_16x16x32_bf16 v[78:81], v[86:89], v[200:203], v[78:81]
	v_mfma_f32_16x16x32_bf16 v[74:77], v[142:145], v[200:203], v[74:77]
	v_mfma_f32_16x16x32_bf16 v[70:73], v[86:89], v[218:221], v[70:73]
	v_mfma_f32_16x16x32_bf16 v[66:69], v[142:145], v[218:221], v[66:69]
	s_setprio 0
	s_setprio 1
	v_mfma_f32_16x16x32_bf16 v[30:33], v[158:161], v[180:183], v[30:33]
	v_mfma_f32_16x16x32_bf16 v[26:29], v[172:175], v[180:183], v[26:29]
	v_mfma_f32_16x16x32_bf16 v[22:25], v[158:161], v[188:191], v[22:25]
	v_mfma_f32_16x16x32_bf16 v[18:21], v[172:175], v[188:191], v[18:21]
	v_mfma_f32_16x16x32_bf16 v[14:17], v[158:161], v[196:199], v[14:17]
	v_mfma_f32_16x16x32_bf16 v[10:13], v[172:175], v[196:199], v[10:13]
	v_mfma_f32_16x16x32_bf16 v[6:9], v[158:161], v[214:217], v[6:9]
	v_mfma_f32_16x16x32_bf16 v[2:5], v[172:175], v[214:217], v[2:5]
	v_mfma_f32_16x16x32_bf16 v[30:33], v[168:171], v[184:187], v[30:33]
	v_mfma_f32_16x16x32_bf16 v[26:29], v[176:179], v[184:187], v[26:29]
	v_mfma_f32_16x16x32_bf16 v[22:25], v[168:171], v[192:195], v[22:25]
	v_mfma_f32_16x16x32_bf16 v[18:21], v[176:179], v[192:195], v[18:21]
	v_mfma_f32_16x16x32_bf16 v[14:17], v[168:171], v[200:203], v[14:17]
	v_mfma_f32_16x16x32_bf16 v[10:13], v[176:179], v[200:203], v[10:13]
	v_mfma_f32_16x16x32_bf16 v[6:9], v[168:171], v[218:221], v[6:9]
	v_mfma_f32_16x16x32_bf16 v[2:5], v[176:179], v[218:221], v[2:5]
	s_setprio 0
	s_barrier
	s_add_u32 s0, s0, 0x100
	s_addc_u32 s1, s1, 0
	s_add_u32 s6, s6, 0x100
	s_addc_u32 s7, s7, 0
	s_cmp_ge_i32 s9, s76
	s_mov_b32 s4, s9
	s_cbranch_scc1 .Lin1_exit
.LBB0_1142:
	s_add_i32 s9, s4, 2
	s_add_u32 s10, s0, 0x80
	s_addc_u32 s5, s1, 0
	s_add_i32 s31, 0, 0x10000
	s_cmp_eq_u32 s77, s4
	s_cselect_b32 s5, s23, s5
	s_cselect_b32 s4, s22, s10
	s_cselect_b32 s11, s67, s7
	s_cselect_b32 s10, s66, s6
	s_add_i32 s53, 0, 0x14000
	v_lshl_add_u64 v[162:163], s[0:1], 0, v[154:155]
	s_add_i32 m0, s70, 0xc000
	s_nop 0
	global_load_lds_dwordx4 v[162:163], off
	v_lshl_add_u64 v[162:163], s[0:1], 0, v[156:157]
	s_add_i32 m0, s70, 0xe000
	s_nop 0
	global_load_lds_dwordx4 v[162:163], off
	v_add_u32_e32 v1, s31, v165
	ds_read_b128 v[82:85], v1
	ds_read_b128 v[86:89], v1 offset:1024
	ds_read_b128 v[138:141], v1 offset:2048
	ds_read_b128 v[142:145], v1 offset:3072
	v_add_u32_e32 v1, s53, v165
	ds_read_b128 v[158:161], v1
	ds_read_b128 v[168:171], v1 offset:1024
	ds_read_b128 v[172:175], v1 offset:2048
	ds_read_b128 v[176:179], v1 offset:3072
	ds_read_b128 v[180:183], v167
	ds_read_b128 v[184:187], v167 offset:1024
	ds_read_b128 v[188:191], v167 offset:2048
	ds_read_b128 v[192:195], v167 offset:3072
	ds_read_b128 v[196:199], v167 offset:4096
	ds_read_b128 v[200:203], v167 offset:5120
	ds_read_b128 v[214:217], v167 offset:6144
	ds_read_b128 v[218:221], v167 offset:7168
	s_waitcnt lgkmcnt(0)
	s_waitcnt vmcnt(8)
	s_barrier
	s_setprio 1
	s_waitcnt lgkmcnt(0)
	v_mfma_f32_16x16x32_bf16 v[134:137], v[82:85], v[180:183], v[134:137]
	v_mfma_f32_16x16x32_bf16 v[130:133], v[138:141], v[180:183], v[130:133]
	v_mfma_f32_16x16x32_bf16 v[126:129], v[82:85], v[188:191], v[126:129]
	v_mfma_f32_16x16x32_bf16 v[122:125], v[138:141], v[188:191], v[122:125]
	v_mfma_f32_16x16x32_bf16 v[118:121], v[82:85], v[196:199], v[118:121]
	v_mfma_f32_16x16x32_bf16 v[114:117], v[138:141], v[196:199], v[114:117]
	v_mfma_f32_16x16x32_bf16 v[110:113], v[82:85], v[214:217], v[110:113]
	v_mfma_f32_16x16x32_bf16 v[106:109], v[138:141], v[214:217], v[106:109]
	v_mfma_f32_16x16x32_bf16 v[134:137], v[86:89], v[184:187], v[134:137]
	v_mfma_f32_16x16x32_bf16 v[130:133], v[142:145], v[184:187], v[130:133]
	v_mfma_f32_16x16x32_bf16 v[126:129], v[86:89], v[192:195], v[126:129]
	v_mfma_f32_16x16x32_bf16 v[122:125], v[142:145], v[192:195], v[122:125]
	v_mfma_f32_16x16x32_bf16 v[118:121], v[86:89], v[200:203], v[118:121]
	v_mfma_f32_16x16x32_bf16 v[114:117], v[142:145], v[200:203], v[114:117]
	v_mfma_f32_16x16x32_bf16 v[110:113], v[86:89], v[218:221], v[110:113]
	v_mfma_f32_16x16x32_bf16 v[106:109], v[142:145], v[218:221], v[106:109]
	s_setprio 0
	s_setprio 1
	v_mfma_f32_16x16x32_bf16 v[62:65], v[158:161], v[180:183], v[62:65]
	v_mfma_f32_16x16x32_bf16 v[58:61], v[172:175], v[180:183], v[58:61]
	v_mfma_f32_16x16x32_bf16 v[54:57], v[158:161], v[188:191], v[54:57]
	v_mfma_f32_16x16x32_bf16 v[50:53], v[172:175], v[188:191], v[50:53]
	v_mfma_f32_16x16x32_bf16 v[46:49], v[158:161], v[196:199], v[46:49]
	v_mfma_f32_16x16x32_bf16 v[42:45], v[172:175], v[196:199], v[42:45]
	v_mfma_f32_16x16x32_bf16 v[38:41], v[158:161], v[214:217], v[38:41]
	v_mfma_f32_16x16x32_bf16 v[34:37], v[172:175], v[214:217], v[34:37]
	v_mfma_f32_16x16x32_bf16 v[62:65], v[168:171], v[184:187], v[62:65]
	v_mfma_f32_16x16x32_bf16 v[58:61], v[176:179], v[184:187], v[58:61]
	v_mfma_f32_16x16x32_bf16 v[54:57], v[168:171], v[192:195], v[54:57]
	v_mfma_f32_16x16x32_bf16 v[50:53], v[176:179], v[192:195], v[50:53]
	v_mfma_f32_16x16x32_bf16 v[46:49], v[168:171], v[200:203], v[46:49]
	v_mfma_f32_16x16x32_bf16 v[42:45], v[176:179], v[200:203], v[42:45]
	v_mfma_f32_16x16x32_bf16 v[38:41], v[168:171], v[218:221], v[38:41]
	v_mfma_f32_16x16x32_bf16 v[34:37], v[176:179], v[218:221], v[34:37]
	s_setprio 0
	s_barrier
	s_add_i32 s31, s31, s65
	v_lshl_add_u64 v[162:163], s[10:11], 0, v[150:151]
	s_mov_b32 m0, s31
	s_nop 0
	global_load_lds_dwordx4 v[162:163], off
	s_add_i32 m0, s31, 0x2000
	v_lshl_add_u64 v[204:205], s[10:11], 0, v[146:147]
	s_add_u32 s10, s10, s12
	s_addc_u32 s11, s11, s13
	s_add_i32 s31, s53, s65
	global_load_lds_dwordx4 v[204:205], off
	v_lshl_add_u64 v[222:223], s[10:11], 0, v[150:151]
	s_mov_b32 m0, s31
	v_lshl_add_u64 v[224:225], s[10:11], 0, v[146:147]
	global_load_lds_dwordx4 v[222:223], off
	s_add_i32 m0, s31, 0x2000
	v_lshl_add_u64 v[226:227], s[4:5], 0, v[152:153]
	global_load_lds_dwordx4 v[224:225], off
	s_mov_b32 m0, s70
	v_lshl_add_u64 v[236:237], s[4:5], 0, v[148:149]
	global_load_lds_dwordx4 v[226:227], off
	s_mov_b32 m0, s71
	s_nop 0
	global_load_lds_dwordx4 v[236:237], off
	ds_read_b128 v[180:183], v167 offset:16384
	ds_read_b128 v[184:187], v167 offset:17408
	ds_read_b128 v[188:191], v167 offset:18432
	ds_read_b128 v[192:195], v167 offset:19456
	ds_read_b128 v[196:199], v167 offset:20480
	ds_read_b128 v[200:203], v167 offset:21504
	ds_read_b128 v[214:217], v167 offset:22528
	ds_read_b128 v[218:221], v167 offset:23552
	s_waitcnt lgkmcnt(0)
	s_waitcnt vmcnt(8)
	s_barrier
	s_setprio 1
	s_waitcnt lgkmcnt(0)
	v_mfma_f32_16x16x32_bf16 v[102:105], v[82:85], v[180:183], v[102:105]
	v_mfma_f32_16x16x32_bf16 v[98:101], v[138:141], v[180:183], v[98:101]
	v_mfma_f32_16x16x32_bf16 v[94:97], v[82:85], v[188:191], v[94:97]
	v_mfma_f32_16x16x32_bf16 v[90:93], v[138:141], v[188:191], v[90:93]
	v_mfma_f32_16x16x32_bf16 v[78:81], v[82:85], v[196:199], v[78:81]
	v_mfma_f32_16x16x32_bf16 v[74:77], v[138:141], v[196:199], v[74:77]
	v_mfma_f32_16x16x32_bf16 v[70:73], v[82:85], v[214:217], v[70:73]
	v_mfma_f32_16x16x32_bf16 v[66:69], v[138:141], v[214:217], v[66:69]
	v_mfma_f32_16x16x32_bf16 v[102:105], v[86:89], v[184:187], v[102:105]
	v_mfma_f32_16x16x32_bf16 v[98:101], v[142:145], v[184:187], v[98:101]
	v_mfma_f32_16x16x32_bf16 v[94:97], v[86:89], v[192:195], v[94:97]
	v_mfma_f32_16x16x32_bf16 v[90:93], v[142:145], v[192:195], v[90:93]
	v_mfma_f32_16x16x32_bf16 v[78:81], v[86:89], v[200:203], v[78:81]
	v_mfma_f32_16x16x32_bf16 v[74:77], v[142:145], v[200:203], v[74:77]
	v_mfma_f32_16x16x32_bf16 v[70:73], v[86:89], v[218:221], v[70:73]
	v_mfma_f32_16x16x32_bf16 v[66:69], v[142:145], v[218:221], v[66:69]
	s_setprio 0
	s_setprio 1
	v_mfma_f32_16x16x32_bf16 v[30:33], v[158:161], v[180:183], v[30:33]
	v_mfma_f32_16x16x32_bf16 v[26:29], v[172:175], v[180:183], v[26:29]
	v_mfma_f32_16x16x32_bf16 v[22:25], v[158:161], v[188:191], v[22:25]
	v_mfma_f32_16x16x32_bf16 v[18:21], v[172:175], v[188:191], v[18:21]
	v_mfma_f32_16x16x32_bf16 v[14:17], v[158:161], v[196:199], v[14:17]
	v_mfma_f32_16x16x32_bf16 v[10:13], v[172:175], v[196:199], v[10:13]
	v_mfma_f32_16x16x32_bf16 v[6:9], v[158:161], v[214:217], v[6:9]
	v_mfma_f32_16x16x32_bf16 v[2:5], v[172:175], v[214:217], v[2:5]
	v_mfma_f32_16x16x32_bf16 v[30:33], v[168:171], v[184:187], v[30:33]
	v_mfma_f32_16x16x32_bf16 v[26:29], v[176:179], v[184:187], v[26:29]
	v_mfma_f32_16x16x32_bf16 v[22:25], v[168:171], v[192:195], v[22:25]
	v_mfma_f32_16x16x32_bf16 v[18:21], v[176:179], v[192:195], v[18:21]
	v_mfma_f32_16x16x32_bf16 v[14:17], v[168:171], v[200:203], v[14:17]
	v_mfma_f32_16x16x32_bf16 v[10:13], v[176:179], v[200:203], v[10:13]
	v_mfma_f32_16x16x32_bf16 v[6:9], v[168:171], v[218:221], v[6:9]
	v_mfma_f32_16x16x32_bf16 v[2:5], v[176:179], v[218:221], v[2:5]
	s_setprio 0
	s_barrier
	s_add_i32 s10, 0, 0x18000
	s_add_i32 s11, 0, 0x1c000
	s_add_u32 s4, s4, s12
	s_addc_u32 s5, s5, s13
	s_mov_b32 m0, s72
	v_lshl_add_u64 v[238:239], s[4:5], 0, v[152:153]
	global_load_lds_dwordx4 v[238:239], off
	v_lshl_add_u64 v[238:239], s[4:5], 0, v[148:149]
	s_mov_b32 m0, s73
	s_nop 0
	global_load_lds_dwordx4 v[238:239], off
	v_add_u32_e32 v1, s10, v165
	ds_read_b128 v[82:85], v1
	ds_read_b128 v[86:89], v1 offset:1024
	ds_read_b128 v[138:141], v1 offset:2048
	ds_read_b128 v[142:145], v1 offset:3072
	v_add_u32_e32 v1, s11, v165
	ds_read_b128 v[158:161], v1
	ds_read_b128 v[168:171], v1 offset:1024
	ds_read_b128 v[172:175], v1 offset:2048
	ds_read_b128 v[176:179], v1 offset:3072
	ds_read_b128 v[180:183], v167 offset:32768
	ds_read_b128 v[184:187], v167 offset:33792
	ds_read_b128 v[188:191], v167 offset:34816
	ds_read_b128 v[192:195], v167 offset:35840
	ds_read_b128 v[196:199], v167 offset:36864
	ds_read_b128 v[200:203], v167 offset:37888
	ds_read_b128 v[214:217], v167 offset:38912
	ds_read_b128 v[218:221], v167 offset:39936
	s_waitcnt lgkmcnt(0)
	s_waitcnt vmcnt(8)
	s_barrier
	s_setprio 1
	s_waitcnt lgkmcnt(0)
	v_mfma_f32_16x16x32_bf16 v[134:137], v[82:85], v[180:183], v[134:137]
	v_mfma_f32_16x16x32_bf16 v[130:133], v[138:141], v[180:183], v[130:133]
	v_mfma_f32_16x16x32_bf16 v[126:129], v[82:85], v[188:191], v[126:129]
	v_mfma_f32_16x16x32_bf16 v[122:125], v[138:141], v[188:191], v[122:125]
	v_mfma_f32_16x16x32_bf16 v[118:121], v[82:85], v[196:199], v[118:121]
	v_mfma_f32_16x16x32_bf16 v[114:117], v[138:141], v[196:199], v[114:117]
	v_mfma_f32_16x16x32_bf16 v[110:113], v[82:85], v[214:217], v[110:113]
	v_mfma_f32_16x16x32_bf16 v[106:109], v[138:141], v[214:217], v[106:109]
	v_mfma_f32_16x16x32_bf16 v[134:137], v[86:89], v[184:187], v[134:137]
	v_mfma_f32_16x16x32_bf16 v[130:133], v[142:145], v[184:187], v[130:133]
	v_mfma_f32_16x16x32_bf16 v[126:129], v[86:89], v[192:195], v[126:129]
	v_mfma_f32_16x16x32_bf16 v[122:125], v[142:145], v[192:195], v[122:125]
	v_mfma_f32_16x16x32_bf16 v[118:121], v[86:89], v[200:203], v[118:121]
	v_mfma_f32_16x16x32_bf16 v[114:117], v[142:145], v[200:203], v[114:117]
	v_mfma_f32_16x16x32_bf16 v[110:113], v[86:89], v[218:221], v[110:113]
	v_mfma_f32_16x16x32_bf16 v[106:109], v[142:145], v[218:221], v[106:109]
	s_setprio 0
	s_setprio 1
	v_mfma_f32_16x16x32_bf16 v[62:65], v[158:161], v[180:183], v[62:65]
	v_mfma_f32_16x16x32_bf16 v[58:61], v[172:175], v[180:183], v[58:61]
	v_mfma_f32_16x16x32_bf16 v[54:57], v[158:161], v[188:191], v[54:57]
	v_mfma_f32_16x16x32_bf16 v[50:53], v[172:175], v[188:191], v[50:53]
	v_mfma_f32_16x16x32_bf16 v[46:49], v[158:161], v[196:199], v[46:49]
	v_mfma_f32_16x16x32_bf16 v[42:45], v[172:175], v[196:199], v[42:45]
	v_mfma_f32_16x16x32_bf16 v[38:41], v[158:161], v[214:217], v[38:41]
	v_mfma_f32_16x16x32_bf16 v[34:37], v[172:175], v[214:217], v[34:37]
	v_mfma_f32_16x16x32_bf16 v[62:65], v[168:171], v[184:187], v[62:65]
	v_mfma_f32_16x16x32_bf16 v[58:61], v[176:179], v[184:187], v[58:61]
	v_mfma_f32_16x16x32_bf16 v[54:57], v[168:171], v[192:195], v[54:57]
	v_mfma_f32_16x16x32_bf16 v[50:53], v[176:179], v[192:195], v[50:53]
	v_mfma_f32_16x16x32_bf16 v[46:49], v[168:171], v[200:203], v[46:49]
	v_mfma_f32_16x16x32_bf16 v[42:45], v[176:179], v[200:203], v[42:45]
	v_mfma_f32_16x16x32_bf16 v[38:41], v[168:171], v[218:221], v[38:41]
	v_mfma_f32_16x16x32_bf16 v[34:37], v[176:179], v[218:221], v[34:37]
	s_setprio 0
	s_barrier
	s_add_i32 s4, s10, s65
	v_lshl_add_u64 v[162:163], v[162:163], 0, s[60:61]
	s_mov_b32 m0, s4
	s_nop 0
	global_load_lds_dwordx4 v[162:163], off
	v_lshl_add_u64 v[162:163], v[204:205], 0, s[60:61]
	s_add_i32 m0, s4, 0x2000
	s_add_i32 s4, s11, s65
	global_load_lds_dwordx4 v[162:163], off
	v_lshl_add_u64 v[162:163], v[222:223], 0, s[60:61]
	s_mov_b32 m0, s4
	s_nop 0
	global_load_lds_dwordx4 v[162:163], off
	v_lshl_add_u64 v[162:163], v[224:225], 0, s[60:61]
	s_add_i32 m0, s4, 0x2000
	s_nop 0
	global_load_lds_dwordx4 v[162:163], off
	v_lshl_add_u64 v[162:163], v[226:227], 0, s[60:61]
	s_mov_b32 m0, s74
	s_nop 0
	global_load_lds_dwordx4 v[162:163], off
	v_lshl_add_u64 v[162:163], v[236:237], 0, s[60:61]
	s_mov_b32 m0, s75
	s_nop 0
	global_load_lds_dwordx4 v[162:163], off
	ds_read_b128 v[180:183], v167 offset:49152
	ds_read_b128 v[184:187], v167 offset:50176
	ds_read_b128 v[188:191], v167 offset:51200
	ds_read_b128 v[192:195], v167 offset:52224
	ds_read_b128 v[196:199], v167 offset:53248
	ds_read_b128 v[200:203], v167 offset:54272
	ds_read_b128 v[214:217], v167 offset:55296
	ds_read_b128 v[218:221], v167 offset:56320
	s_waitcnt lgkmcnt(0)
	s_waitcnt vmcnt(8)
	s_barrier
	s_setprio 1
	s_waitcnt lgkmcnt(0)
	v_mfma_f32_16x16x32_bf16 v[102:105], v[82:85], v[180:183], v[102:105]
	v_mfma_f32_16x16x32_bf16 v[98:101], v[138:141], v[180:183], v[98:101]
	v_mfma_f32_16x16x32_bf16 v[94:97], v[82:85], v[188:191], v[94:97]
	v_mfma_f32_16x16x32_bf16 v[90:93], v[138:141], v[188:191], v[90:93]
	v_mfma_f32_16x16x32_bf16 v[78:81], v[82:85], v[196:199], v[78:81]
	v_mfma_f32_16x16x32_bf16 v[74:77], v[138:141], v[196:199], v[74:77]
	v_mfma_f32_16x16x32_bf16 v[70:73], v[82:85], v[214:217], v[70:73]
	v_mfma_f32_16x16x32_bf16 v[66:69], v[138:141], v[214:217], v[66:69]
	v_mfma_f32_16x16x32_bf16 v[102:105], v[86:89], v[184:187], v[102:105]
	v_mfma_f32_16x16x32_bf16 v[98:101], v[142:145], v[184:187], v[98:101]
	v_mfma_f32_16x16x32_bf16 v[94:97], v[86:89], v[192:195], v[94:97]
	v_mfma_f32_16x16x32_bf16 v[90:93], v[142:145], v[192:195], v[90:93]
	v_mfma_f32_16x16x32_bf16 v[78:81], v[86:89], v[200:203], v[78:81]
	v_mfma_f32_16x16x32_bf16 v[74:77], v[142:145], v[200:203], v[74:77]
	v_mfma_f32_16x16x32_bf16 v[70:73], v[86:89], v[218:221], v[70:73]
	v_mfma_f32_16x16x32_bf16 v[66:69], v[142:145], v[218:221], v[66:69]
	s_setprio 0
	s_setprio 1
	v_mfma_f32_16x16x32_bf16 v[30:33], v[158:161], v[180:183], v[30:33]
	v_mfma_f32_16x16x32_bf16 v[26:29], v[172:175], v[180:183], v[26:29]
	v_mfma_f32_16x16x32_bf16 v[22:25], v[158:161], v[188:191], v[22:25]
	v_mfma_f32_16x16x32_bf16 v[18:21], v[172:175], v[188:191], v[18:21]
	v_mfma_f32_16x16x32_bf16 v[14:17], v[158:161], v[196:199], v[14:17]
	v_mfma_f32_16x16x32_bf16 v[10:13], v[172:175], v[196:199], v[10:13]
	v_mfma_f32_16x16x32_bf16 v[6:9], v[158:161], v[214:217], v[6:9]
	v_mfma_f32_16x16x32_bf16 v[2:5], v[172:175], v[214:217], v[2:5]
	v_mfma_f32_16x16x32_bf16 v[30:33], v[168:171], v[184:187], v[30:33]
	v_mfma_f32_16x16x32_bf16 v[26:29], v[176:179], v[184:187], v[26:29]
	v_mfma_f32_16x16x32_bf16 v[22:25], v[168:171], v[192:195], v[22:25]
	v_mfma_f32_16x16x32_bf16 v[18:21], v[176:179], v[192:195], v[18:21]
	v_mfma_f32_16x16x32_bf16 v[14:17], v[168:171], v[200:203], v[14:17]
	v_mfma_f32_16x16x32_bf16 v[10:13], v[176:179], v[200:203], v[10:13]
	v_mfma_f32_16x16x32_bf16 v[6:9], v[168:171], v[218:221], v[6:9]
	v_mfma_f32_16x16x32_bf16 v[2:5], v[176:179], v[218:221], v[2:5]
	s_setprio 0
	s_barrier
	s_add_u32 s0, s0, 0x100
	s_addc_u32 s1, s1, 0
	s_add_u32 s6, s6, 0x100
	s_addc_u32 s7, s7, 0
	s_cmp_ge_i32 s9, s76
	s_mov_b32 s4, s9
	s_cbranch_scc0 .LBB0_1142
